# v37 plus: packed +0.0 adds on accumulators in bias-less GEMM epilogues replaced by s_nop 0 (wait states kept)
# baseline (speedup 1.0000x reference)
;     __device__ __forceinline__ void operator()(const f32x4 (&acc)[2][2][4][2], const Unit& u, int wr, int wc, int fr_, int fq_) const {
;         const int lane_ = lane_id_v(), fr = lane_ & 15, fq = lane_ >> 4;
;         const int row0 = u.pm * 256 + wr * 64 + fr, col0 = u.pn * 256 + wc * 32 + 8 * fq;
;     ...
;             for (int m = 0; m < 4; ++m) {
;                 const size_t ro = (size_t)(row0 + ai * 128 + m * 16) * ldc + col0;
; #pragma unroll
;                 for (int bj = 0; bj < 2; ++bj) {
;                     f32x4 v0 = acc[ai][bj][m][0] + bv[bj][0], v1 = acc[ai][bj][m][1] + bv[bj][1];
;                     if (MODE == 1) {
; #pragma unroll
;                         for (int j = 0; j < 4; ++j) { float a = fmaxf(v0[j], 0.f), b = fmaxf(v1[j], 0.f); v0[j] = a * a; v1[j] = b * b; }
;                     } else if (MODE == 2) {
; #pragma unroll
;                         for (int j = 0; j < 4; ++j) { v0[j] = sigmoidf_(v0[j]); v1[j] = sigmoidf_(v1[j]); }
;                     } else if (MODE == 5) {
;                         const u32x4v pp = pq[ai][m][bj];
;                         v0[0] += DN_ALPHA * bflo(pp[0]); v0[1] += DN_ALPHA * bfhi(pp[0]); v0[2] += DN_ALPHA * bflo(pp[1]); v0[3] += DN_ALPHA * bfhi(pp[1]);
;                         v1[0] += DN_ALPHA * bflo(pp[2]); v1[1] += DN_ALPHA * bfhi(pp[2]); v1[2] += DN_ALPHA * bflo(pp[3]); v1[3] += DN_ALPHA * bfhi(pp[3]);
;                     } else if (MODE == 3 || MODE == 4) {
;                         const u32x4v gg = gq[ai][m][bj];
;                         v0[0] *= bflo(gg[0]); v0[1] *= bfhi(gg[0]); v0[2] *= bflo(gg[1]); v0[3] *= bfhi(gg[1]);
;                         v1[0] *= bflo(gg[2]); v1[1] *= bfhi(gg[2]); v1[2] *= bflo(gg[3]); v1[3] *= bfhi(gg[3]);
;                         if (MODE == 4) {
;                             const u32x4v pp = pq[ai][m][bj];
;                             v0[0] += bflo(pp[0]); v0[1] += bfhi(pp[0]); v0[2] += bflo(pp[1]); v0[3] += bfhi(pp[1]);
;                             v1[0] += bflo(pp[2]); v1[1] += bfhi(pp[2]); v1[2] += bflo(pp[3]); v1[3] += bfhi(pp[3]);
;                         }
;                     }
;                     u32x4v o; o[0] = cvt_pk_bf16(v0[0], v0[1]); o[1] = cvt_pk_bf16(v0[2], v0[3]); o[2] = cvt_pk_bf16(v1[0], v1[1]); o[3] = cvt_pk_bf16(v1[2], v1[3]);
;                     if (MODE == 1) __builtin_nontemporal_store(o, (u32x4v*)(O + ro + bj * 128));
.LBB0_143:
	v_mbcnt_lo_u32_b32 v131, -1, 0
	v_mbcnt_hi_u32_b32 v131, -1, v131
	s_lshl_b32 s0, s61, 8
	v_ashrrev_i32_e32 v130, 1, v131
	v_and_or_b32 v131, v131, 15, s53
	v_and_b32_e32 v130, -8, v130
	s_or_b32 s0, s0, s6
	v_add_u32_e32 v132, s13, v131
	v_add_u32_e32 v130, s0, v130
	v_ashrrev_i32_e32 v133, 31, v132
	s_nop 0
	s_nop 0
	v_readlane_b32 s36, v252, 0
	v_ashrrev_i32_e32 v131, 31, v130
	s_nop 0
	v_pk_add_f32 v[134:135], v[124:125], 0 op_sel_hi:[1,0]
	v_cvt_pk_bf16_f32 v124, v126, v127
	v_cvt_pk_bf16_f32 v126, v122, v123
	v_lshlrev_b64 v[122:123], 12, v[132:133]
	v_readlane_b32 s37, v252, 1
	v_cvt_pk_bf16_f32 v125, v128, v129
	v_lshlrev_b64 v[128:129], 1, v[130:131]
	v_lshl_add_u64 v[122:123], s[36:37], 0, v[122:123]
	v_cvt_pk_bf16_f32 v127, v134, v135
	v_lshl_add_u64 v[122:123], v[122:123], 0, v[128:129]
	global_store_dwordx4 v[122:123], v[124:127], off
	s_nop 0
	s_nop 0
	v_pk_add_f32 v[124:125], v[108:109], 0 op_sel_hi:[1,0]
	v_pk_add_f32 v[108:109], v[106:107], 0 op_sel_hi:[1,0]
	v_cvt_pk_bf16_f32 v106, v114, v115
	v_cvt_pk_bf16_f32 v107, v116, v117
	v_cvt_pk_bf16_f32 v108, v108, v109
	v_cvt_pk_bf16_f32 v109, v124, v125
	v_or_b32_e32 v114, 16, v132
	global_store_dwordx4 v[122:123], v[106:109], off offset:256
	v_ashrrev_i32_e32 v115, 31, v114
	s_nop 0
	v_pk_add_f32 v[108:109], v[120:121], 0 op_sel_hi:[1,0]
	v_pk_add_f32 v[106:107], v[118:119], 0 op_sel_hi:[1,0]
	s_nop 0
	v_cvt_pk_bf16_f32 v106, v106, v107
	v_cvt_pk_bf16_f32 v107, v108, v109
	v_cvt_pk_bf16_f32 v108, v110, v111
	v_lshlrev_b64 v[110:111], 12, v[114:115]
	v_lshl_add_u64 v[110:111], s[36:37], 0, v[110:111]
	v_cvt_pk_bf16_f32 v109, v112, v113
	v_lshl_add_u64 v[110:111], v[110:111], 0, v[128:129]
	global_store_dwordx4 v[110:111], v[106:109], off
	s_nop 0
	s_nop 0
	v_pk_add_f32 v[106:107], v[92:93], 0 op_sel_hi:[1,0]
	v_pk_add_f32 v[92:93], v[90:91], 0 op_sel_hi:[1,0]
	v_cvt_pk_bf16_f32 v90, v98, v99
	v_cvt_pk_bf16_f32 v91, v100, v101
	v_cvt_pk_bf16_f32 v92, v92, v93
	v_cvt_pk_bf16_f32 v93, v106, v107
	v_or_b32_e32 v98, 32, v132
	global_store_dwordx4 v[110:111], v[90:93], off offset:256
	v_ashrrev_i32_e32 v99, 31, v98
	s_nop 0
	v_pk_add_f32 v[92:93], v[104:105], 0 op_sel_hi:[1,0]
	v_pk_add_f32 v[90:91], v[102:103], 0 op_sel_hi:[1,0]
	s_nop 0
	v_cvt_pk_bf16_f32 v90, v90, v91
	v_cvt_pk_bf16_f32 v91, v92, v93
	v_cvt_pk_bf16_f32 v92, v94, v95
	v_lshlrev_b64 v[94:95], 12, v[98:99]
	v_lshl_add_u64 v[94:95], s[36:37], 0, v[94:95]
	v_cvt_pk_bf16_f32 v93, v96, v97
	v_lshl_add_u64 v[94:95], v[94:95], 0, v[128:129]
	global_store_dwordx4 v[94:95], v[90:93], off
	s_nop 0
	s_nop 0
	v_pk_add_f32 v[90:91], v[76:77], 0 op_sel_hi:[1,0]
	v_pk_add_f32 v[76:77], v[74:75], 0 op_sel_hi:[1,0]
	v_cvt_pk_bf16_f32 v74, v82, v83
	v_cvt_pk_bf16_f32 v75, v84, v85
	v_cvt_pk_bf16_f32 v76, v76, v77
	v_cvt_pk_bf16_f32 v77, v90, v91
	v_or_b32_e32 v82, 48, v132
	global_store_dwordx4 v[94:95], v[74:77], off offset:256
	v_ashrrev_i32_e32 v83, 31, v82
	s_nop 0
	v_pk_add_f32 v[76:77], v[88:89], 0 op_sel_hi:[1,0]
	v_pk_add_f32 v[74:75], v[86:87], 0 op_sel_hi:[1,0]
	s_nop 0
	v_cvt_pk_bf16_f32 v74, v74, v75
	v_cvt_pk_bf16_f32 v75, v76, v77
	v_cvt_pk_bf16_f32 v76, v78, v79
	v_lshlrev_b64 v[78:79], 12, v[82:83]
	v_lshl_add_u64 v[78:79], s[36:37], 0, v[78:79]
	v_cvt_pk_bf16_f32 v77, v80, v81
	v_lshl_add_u64 v[78:79], v[78:79], 0, v[128:129]
	global_store_dwordx4 v[78:79], v[74:77], off
	s_nop 0
	s_nop 0
	v_pk_add_f32 v[74:75], v[68:69], 0 op_sel_hi:[1,0]
	v_pk_add_f32 v[68:69], v[66:67], 0 op_sel_hi:[1,0]
	v_cvt_pk_bf16_f32 v66, v70, v71
	v_cvt_pk_bf16_f32 v67, v72, v73
	v_cvt_pk_bf16_f32 v68, v68, v69
	v_cvt_pk_bf16_f32 v69, v74, v75
	s_nop 0
	s_mov_b64 s[0:1], 0x80000
	global_store_dwordx4 v[78:79], v[66:69], off offset:256
	s_nop 0
	s_nop 0
	v_pk_add_f32 v[66:67], v[60:61], 0 op_sel_hi:[1,0]
	v_pk_add_f32 v[60:61], v[58:59], 0 op_sel_hi:[1,0]
	v_cvt_pk_bf16_f32 v58, v62, v63
	v_lshl_add_u64 v[62:63], v[122:123], 0, s[0:1]
	s_mov_b32 s0, 0x80000
	v_cvt_pk_bf16_f32 v59, v64, v65
	v_add_co_u32_e32 v64, vcc, s0, v122
	v_cvt_pk_bf16_f32 v60, v60, v61
	v_cvt_pk_bf16_f32 v61, v66, v67
	v_addc_co_u32_e32 v65, vcc, 0, v123, vcc
	global_store_dwordx4 v[64:65], v[58:61], off
	s_nop 0
	s_nop 0
	v_pk_add_f32 v[58:59], v[44:45], 0 op_sel_hi:[1,0]
	v_pk_add_f32 v[44:45], v[42:43], 0 op_sel_hi:[1,0]
	v_cvt_pk_bf16_f32 v42, v50, v51
	v_cvt_pk_bf16_f32 v43, v52, v53
	v_cvt_pk_bf16_f32 v44, v44, v45
	v_cvt_pk_bf16_f32 v45, v58, v59
	global_store_dwordx4 v[62:63], v[42:45], off offset:256
	s_mov_b64 s[0:1], 0x90000
	s_nop 0
	v_pk_add_f32 v[44:45], v[56:57], 0 op_sel_hi:[1,0]
	v_pk_add_f32 v[42:43], v[54:55], 0 op_sel_hi:[1,0]
	s_nop 0
	v_cvt_pk_bf16_f32 v42, v42, v43
	v_cvt_pk_bf16_f32 v43, v44, v45
	v_cvt_pk_bf16_f32 v44, v46, v47
	v_lshl_add_u64 v[46:47], v[122:123], 0, s[0:1]
	s_mov_b32 s0, 0x90000
	v_cvt_pk_bf16_f32 v45, v48, v49
	v_add_co_u32_e32 v48, vcc, s0, v122
	s_nop 0
	s_nop 0
	v_addc_co_u32_e32 v49, vcc, 0, v123, vcc
	global_store_dwordx4 v[48:49], v[42:45], off
	s_nop 0
	s_mov_b64 s[0:1], 0xa0000
	v_pk_add_f32 v[42:43], v[28:29], 0 op_sel_hi:[1,0]
	v_pk_add_f32 v[28:29], v[26:27], 0 op_sel_hi:[1,0]
	v_cvt_pk_bf16_f32 v26, v34, v35
	v_cvt_pk_bf16_f32 v27, v36, v37
	v_cvt_pk_bf16_f32 v28, v28, v29
	v_cvt_pk_bf16_f32 v29, v42, v43
	global_store_dwordx4 v[46:47], v[26:29], off offset:256
	s_nop 0
	s_nop 0
	v_pk_add_f32 v[28:29], v[40:41], 0 op_sel_hi:[1,0]
	v_pk_add_f32 v[26:27], v[38:39], 0 op_sel_hi:[1,0]
	s_nop 0
	v_cvt_pk_bf16_f32 v26, v26, v27
	v_cvt_pk_bf16_f32 v27, v28, v29
	v_cvt_pk_bf16_f32 v28, v30, v31
	v_lshl_add_u64 v[30:31], v[122:123], 0, s[0:1]
	s_mov_b32 s0, 0xa0000
	v_cvt_pk_bf16_f32 v29, v32, v33
	v_add_co_u32_e32 v32, vcc, s0, v122
	s_mov_b64 s[0:1], 0xb0000
	s_nop 0
	v_addc_co_u32_e32 v33, vcc, 0, v123, vcc
	global_store_dwordx4 v[32:33], v[26:29], off
	s_nop 0
	v_lshl_add_u64 v[138:139], v[122:123], 0, s[0:1]
	v_pk_add_f32 v[26:27], v[12:13], 0 op_sel_hi:[1,0]
	v_pk_add_f32 v[12:13], v[10:11], 0 op_sel_hi:[1,0]
	v_cvt_pk_bf16_f32 v10, v18, v19
	v_cvt_pk_bf16_f32 v11, v20, v21
	v_cvt_pk_bf16_f32 v12, v12, v13
	v_cvt_pk_bf16_f32 v13, v26, v27
	global_store_dwordx4 v[30:31], v[10:13], off offset:256
	s_mov_b32 s0, 0xb0000
	v_readlane_b32 s38, v252, 2
	v_pk_add_f32 v[12:13], v[24:25], 0 op_sel_hi:[1,0]
	v_pk_add_f32 v[10:11], v[22:23], 0 op_sel_hi:[1,0]
	v_readlane_b32 s39, v252, 3
	s_nop 0
	v_cvt_pk_bf16_f32 v10, v10, v11
	v_cvt_pk_bf16_f32 v11, v12, v13
	v_cvt_pk_bf16_f32 v12, v14, v15
	v_add_co_u32_e32 v14, vcc, s0, v122
	s_nop 0
	s_nop 0
	s_nop 0
	s_mov_b64 s[38:39], 0x800
	v_cvt_pk_bf16_f32 v13, v16, v17
	v_addc_co_u32_e32 v15, vcc, 0, v123, vcc
	v_pk_add_f32 v[134:135], v[2:3], 0 op_sel_hi:[1,0]
	v_cvt_pk_bf16_f32 v130, v4, v5
	v_cvt_pk_bf16_f32 v131, v6, v7
	v_cvt_pk_bf16_f32 v132, v0, v1
	global_store_dwordx4 v[14:15], v[10:13], off

; __device__ __forceinline__ float bflo(unsigned u) { return __uint_as_float(u << 16); }
;     __device__ __forceinline__ void operator()(const f32x4 (&acc)[2][2][4][2], const Unit& u, int wr, int wc, int fr_, int fq_) const {
;     ...
;             for (int m = 0; m < 4; ++m) {
;                 const size_t ro = (size_t)(row0 + ai * 128 + m * 16) * ldc + col0;
; #pragma unroll
;                 for (int bj = 0; bj < 2; ++bj) {
;                     f32x4 v0 = acc[ai][bj][m][0] + bv[bj][0], v1 = acc[ai][bj][m][1] + bv[bj][1];
;                     if (MODE == 1) {
; #pragma unroll
;                         for (int j = 0; j < 4; ++j) { float a = fmaxf(v0[j], 0.f), b = fmaxf(v1[j], 0.f); v0[j] = a * a; v1[j] = b * b; }
;                     } else if (MODE == 2) {
; #pragma unroll
;                         for (int j = 0; j < 4; ++j) { v0[j] = sigmoidf_(v0[j]); v1[j] = sigmoidf_(v1[j]); }
;                     } else if (MODE == 5) {
;                         const u32x4v pp = pq[ai][m][bj];
;                         v0[0] += DN_ALPHA * bflo(pp[0]); v0[1] += DN_ALPHA * bfhi(pp[0]); v0[2] += DN_ALPHA * bflo(pp[1]); v0[3] += DN_ALPHA * bfhi(pp[1]);
;                         v1[0] += DN_ALPHA * bflo(pp[2]); v1[1] += DN_ALPHA * bfhi(pp[2]); v1[2] += DN_ALPHA * bflo(pp[3]); v1[3] += DN_ALPHA * bfhi(pp[3]);
;                     } else if (MODE == 3 || MODE == 4) {
;                         const u32x4v gg = gq[ai][m][bj];
;                         v0[0] *= bflo(gg[0]); v0[1] *= bfhi(gg[0]); v0[2] *= bflo(gg[1]); v0[3] *= bfhi(gg[1]);
;                         v1[0] *= bflo(gg[2]); v1[1] *= bfhi(gg[2]); v1[2] *= bflo(gg[3]); v1[3] *= bfhi(gg[3]);
;                         if (MODE == 4) {
;                             const u32x4v pp = pq[ai][m][bj];
;                             v0[0] += bflo(pp[0]); v0[1] += bfhi(pp[0]); v0[2] += bflo(pp[1]); v0[3] += bfhi(pp[1]);
;                             v1[0] += bflo(pp[2]); v1[1] += bfhi(pp[2]); v1[2] += bflo(pp[3]); v1[3] += bfhi(pp[3]);
;                         }
;                     }
;                     u32x4v o; o[0] = cvt_pk_bf16(v0[0], v0[1]); o[1] = cvt_pk_bf16(v0[2], v0[3]); o[2] = cvt_pk_bf16(v1[0], v1[1]); o[3] = cvt_pk_bf16(v1[2], v1[3]);
;                     if (MODE == 1) __builtin_nontemporal_store(o, (u32x4v*)(O + ro + bj * 128));
;                     else *(u32x4v*)(O + ro + bj * 128) = o;
.LBB0_411:
	v_mbcnt_lo_u32_b32 v139, -1, 0
	v_mbcnt_hi_u32_b32 v139, -1, v139
	s_lshl_b32 s13, s36, 8
	v_ashrrev_i32_e32 v138, 1, v139
	v_and_or_b32 v139, v139, 15, s40
	v_and_b32_e32 v138, -8, v138
	s_or_b32 s13, s13, s44
	v_lshl_add_u32 v140, s18, 8, v139
	v_add_u32_e32 v138, s13, v138
	v_ashrrev_i32_e32 v141, 31, v140
	s_nop 0
	s_nop 0
	v_readlane_b32 s34, v252, 24
	v_ashrrev_i32_e32 v139, 31, v138
	s_nop 0
	v_pk_add_f32 v[142:143], v[124:125], 0 op_sel_hi:[1,0]
	v_cvt_pk_bf16_f32 v124, v126, v127
	v_cvt_pk_bf16_f32 v126, v122, v123
	v_lshlrev_b64 v[122:123], 10, v[140:141]
	v_readlane_b32 s35, v252, 25
	v_cvt_pk_bf16_f32 v125, v128, v129
	v_lshlrev_b64 v[128:129], 1, v[138:139]
	v_lshl_add_u64 v[122:123], s[34:35], 0, v[122:123]
	v_cvt_pk_bf16_f32 v127, v142, v143
	v_lshl_add_u64 v[122:123], v[122:123], 0, v[128:129]
	global_store_dwordx4 v[122:123], v[124:127], off
	s_nop 0
	s_nop 0
	v_pk_add_f32 v[124:125], v[116:117], 0 op_sel_hi:[1,0]
	v_pk_add_f32 v[116:117], v[114:115], 0 op_sel_hi:[1,0]
	v_cvt_pk_bf16_f32 v114, v118, v119
	v_cvt_pk_bf16_f32 v115, v120, v121
	v_cvt_pk_bf16_f32 v116, v116, v117
	v_cvt_pk_bf16_f32 v117, v124, v125
	global_store_dwordx4 v[122:123], v[114:117], off offset:256
	s_nop 0
	s_nop 0
	v_or_b32_e32 v114, 16, v140
	v_ashrrev_i32_e32 v115, 31, v114
	v_pk_add_f32 v[116:117], v[104:105], 0 op_sel_hi:[1,0]
	v_pk_add_f32 v[104:105], v[102:103], 0 op_sel_hi:[1,0]
	v_cvt_pk_bf16_f32 v102, v110, v111
	v_lshlrev_b64 v[110:111], 10, v[114:115]
	v_lshl_add_u64 v[110:111], s[34:35], 0, v[110:111]
	v_cvt_pk_bf16_f32 v103, v112, v113
	v_cvt_pk_bf16_f32 v104, v104, v105
	v_cvt_pk_bf16_f32 v105, v116, v117
	v_lshl_add_u64 v[110:111], v[110:111], 0, v[128:129]
	global_store_dwordx4 v[110:111], v[102:105], off
	s_nop 0
	s_nop 0
	v_pk_add_f32 v[102:103], v[108:109], 0 op_sel_hi:[1,0]
	v_pk_add_f32 v[104:105], v[106:107], 0 op_sel_hi:[1,0]
	v_pk_add_f32 v[106:107], v[100:101], 0 op_sel_hi:[1,0]
	v_pk_add_f32 v[100:101], v[98:99], 0 op_sel_hi:[1,0]
	v_cvt_pk_bf16_f32 v98, v104, v105
	v_cvt_pk_bf16_f32 v99, v102, v103
	v_cvt_pk_bf16_f32 v100, v100, v101
	v_cvt_pk_bf16_f32 v101, v106, v107
	global_store_dwordx4 v[110:111], v[98:101], off offset:256
	s_nop 0
	s_nop 0
	v_or_b32_e32 v98, 32, v140
	v_ashrrev_i32_e32 v99, 31, v98
	v_pk_add_f32 v[100:101], v[88:89], 0 op_sel_hi:[1,0]
	v_pk_add_f32 v[88:89], v[86:87], 0 op_sel_hi:[1,0]
	v_cvt_pk_bf16_f32 v86, v94, v95
	v_lshlrev_b64 v[94:95], 10, v[98:99]
	v_lshl_add_u64 v[94:95], s[34:35], 0, v[94:95]
	v_cvt_pk_bf16_f32 v87, v96, v97
	v_cvt_pk_bf16_f32 v88, v88, v89
	v_cvt_pk_bf16_f32 v89, v100, v101
	v_lshl_add_u64 v[94:95], v[94:95], 0, v[128:129]
	global_store_dwordx4 v[94:95], v[86:89], off
	s_nop 0
	s_nop 0
	v_pk_add_f32 v[86:87], v[92:93], 0 op_sel_hi:[1,0]
	v_pk_add_f32 v[88:89], v[90:91], 0 op_sel_hi:[1,0]
	v_pk_add_f32 v[90:91], v[84:85], 0 op_sel_hi:[1,0]
	v_pk_add_f32 v[84:85], v[82:83], 0 op_sel_hi:[1,0]
	v_cvt_pk_bf16_f32 v82, v88, v89
	v_cvt_pk_bf16_f32 v83, v86, v87
	v_cvt_pk_bf16_f32 v84, v84, v85
	v_cvt_pk_bf16_f32 v85, v90, v91
	global_store_dwordx4 v[94:95], v[82:85], off offset:256
	s_mov_b32 s13, 0x20000
	s_nop 0
	v_or_b32_e32 v82, 48, v140
	v_ashrrev_i32_e32 v83, 31, v82
	v_pk_add_f32 v[84:85], v[60:61], 0 op_sel_hi:[1,0]
	v_pk_add_f32 v[60:61], v[58:59], 0 op_sel_hi:[1,0]
	v_cvt_pk_bf16_f32 v58, v62, v63
	v_lshlrev_b64 v[62:63], 10, v[82:83]
	v_lshl_add_u64 v[62:63], s[34:35], 0, v[62:63]
	v_cvt_pk_bf16_f32 v59, v64, v65
	v_cvt_pk_bf16_f32 v60, v60, v61
	v_cvt_pk_bf16_f32 v61, v84, v85
	v_lshl_add_u64 v[62:63], v[62:63], 0, v[128:129]
	global_store_dwordx4 v[62:63], v[58:61], off
	s_mov_b64 s[34:35], 0x20000
	s_nop 0
	v_pk_add_f32 v[58:59], v[52:53], 0 op_sel_hi:[1,0]
	v_pk_add_f32 v[52:53], v[50:51], 0 op_sel_hi:[1,0]
;     __device__ __forceinline__ void operator()(const f32x4 (&acc)[2][2][4][2], const Unit& u, int wr, int wc, int fr_, int fq_) const {
;         const int lane_ = lane_id_v(), fr = lane_ & 15, fq = lane_ >> 4;
;         const int row0 = u.pm * 256 + wr * 64 + fr, col0 = u.pn * 256 + wc * 32 + 8 * fq;
;         f32x4 bv[2][2];
; #pragma unroll
;         for (int bj = 0; bj < 2; ++bj)
; #pragma unroll
;             for (int n = 0; n < 2; ++n) bv[bj][n] = (MODE == 1 || MODE == 2 || (MODE == 5 && bias != nullptr)) ? *(const f32x4*)(bias + col0 + bj * 128 + 4 * n) : (f32x4){0.f, 0.f, 0.f, 0.f};
;         u32x4v gq[2][4][2], pq[2][4][2];
;         if (MODE == 3 || MODE == 5) {
; #pragma unroll
;             for (int ai = 0; ai < 2; ++ai)
; #pragma unroll
;                 for (int m = 0; m < 4; ++m)
; #pragma unroll
;                     for (int bj = 0; bj < 2; ++bj) {
;                         const size_t rowi = (size_t)(row0 + ai * 128 + m * 16);
;                         if (MODE == 3) gq[ai][m][bj] = *(const u32x4v*)(G + rowi * ldg + col0 + bj * 128);
;                         if (MODE == 5) pq[ai][m][bj] = *(const u32x4v*)(O + rowi * ldc + col0 + bj * 128);
;                     }
;         }
; #pragma unroll
;         for (int ai = 0; ai < 2; ++ai) {
;             if (MODE == 4) {
; #pragma unroll
;                 for (int m = 0; m < 4; ++m)
; #pragma unroll
;                     for (int bj = 0; bj < 2; ++bj) {
;                         const size_t rowi = (size_t)(row0 + ai * 128 + m * 16);
;                         gq[ai][m][bj] = *(const u32x4v*)(G + rowi * ldg + col0 + bj * 128);
;                         pq[ai][m][bj] = *(const u32x4v*)(O + rowi * ldc + col0 + bj * 128);
;                     }
;             }
; #pragma unroll
;             for (int m = 0; m < 4; ++m) {
;                 const size_t ro = (size_t)(row0 + ai * 128 + m * 16) * ldc + col0;
; #pragma unroll
;                 for (int bj = 0; bj < 2; ++bj) {
;                     f32x4 v0 = acc[ai][bj][m][0] + bv[bj][0], v1 = acc[ai][bj][m][1] + bv[bj][1];
;                     if (MODE == 1) {
; #pragma unroll
;                         for (int j = 0; j < 4; ++j) { float a = fmaxf(v0[j], 0.f), b = fmaxf(v1[j], 0.f); v0[j] = a * a; v1[j] = b * b; }
;                     } else if (MODE == 2) {
; #pragma unroll
	v_cvt_pk_bf16_f32 v50, v54, v55
	v_cvt_pk_bf16_f32 v51, v56, v57
	v_cvt_pk_bf16_f32 v52, v52, v53
	v_cvt_pk_bf16_f32 v53, v58, v59
	global_store_dwordx4 v[62:63], v[50:53], off offset:256
	v_pk_add_f32 v[56:57], v[74:75], 0 op_sel_hi:[1,0]
	v_pk_add_f32 v[54:55], v[76:77], 0 op_sel_hi:[1,0]
	v_pk_add_f32 v[52:53], v[80:81], 0 op_sel_hi:[1,0]
	v_pk_add_f32 v[50:51], v[78:79], 0 op_sel_hi:[1,0]
	v_pk_add_f32 v[58:59], v[66:67], 0 op_sel_hi:[1,0]
	v_cvt_pk_bf16_f32 v50, v50, v51
	v_cvt_pk_bf16_f32 v51, v52, v53
	v_cvt_pk_bf16_f32 v52, v56, v57
	v_add_co_u32_e32 v56, vcc, s13, v122
	v_cvt_pk_bf16_f32 v53, v54, v55
	s_nop 0
	v_addc_co_u32_e32 v57, vcc, 0, v123, vcc
	global_store_dwordx4 v[56:57], v[50:53], off
	v_pk_add_f32 v[56:57], v[68:69], 0 op_sel_hi:[1,0]
	v_lshl_add_u64 v[54:55], v[122:123], 0, s[34:35]
	v_pk_add_f32 v[52:53], v[72:73], 0 op_sel_hi:[1,0]
	v_pk_add_f32 v[50:51], v[70:71], 0 op_sel_hi:[1,0]
	s_mov_b32 s13, 0x24000
	v_cvt_pk_bf16_f32 v50, v50, v51
	v_cvt_pk_bf16_f32 v51, v52, v53
	v_cvt_pk_bf16_f32 v52, v58, v59
	v_cvt_pk_bf16_f32 v53, v56, v57
	global_store_dwordx4 v[54:55], v[50:53], off offset:256
	s_mov_b64 s[34:35], 0x24000
	s_nop 0
	v_pk_add_f32 v[50:51], v[44:45], 0 op_sel_hi:[1,0]
	v_pk_add_f32 v[44:45], v[42:43], 0 op_sel_hi:[1,0]
	v_cvt_pk_bf16_f32 v43, v48, v49
	v_add_co_u32_e32 v48, vcc, s13, v122
	v_cvt_pk_bf16_f32 v42, v46, v47
	v_cvt_pk_bf16_f32 v44, v44, v45
	v_cvt_pk_bf16_f32 v45, v50, v51
	v_addc_co_u32_e32 v49, vcc, 0, v123, vcc
	global_store_dwordx4 v[48:49], v[42:45], off
	s_nop 0
	v_lshl_add_u64 v[46:47], v[122:123], 0, s[34:35]
	v_pk_add_f32 v[42:43], v[36:37], 0 op_sel_hi:[1,0]
	v_pk_add_f32 v[36:37], v[34:35], 0 op_sel_hi:[1,0]
	v_cvt_pk_bf16_f32 v34, v38, v39
	v_cvt_pk_bf16_f32 v35, v40, v41
	v_cvt_pk_bf16_f32 v36, v36, v37
	v_cvt_pk_bf16_f32 v37, v42, v43
	s_nop 0
	s_mov_b32 s13, 0x28000
	global_store_dwordx4 v[46:47], v[34:37], off offset:256
	s_nop 0
	s_mov_b64 s[34:35], 0x28000
	v_pk_add_f32 v[34:35], v[28:29], 0 op_sel_hi:[1,0]
	v_pk_add_f32 v[28:29], v[26:27], 0 op_sel_hi:[1,0]
	v_cvt_pk_bf16_f32 v27, v32, v33
	v_add_co_u32_e32 v32, vcc, s13, v122
	v_cvt_pk_bf16_f32 v26, v30, v31
	v_cvt_pk_bf16_f32 v28, v28, v29
	v_cvt_pk_bf16_f32 v29, v34, v35
	v_addc_co_u32_e32 v33, vcc, 0, v123, vcc
	global_store_dwordx4 v[32:33], v[26:29], off
	s_nop 0
	s_nop 0
	v_pk_add_f32 v[26:27], v[20:21], 0 op_sel_hi:[1,0]
	v_pk_add_f32 v[20:21], v[18:19], 0 op_sel_hi:[1,0]
	v_lshl_add_u64 v[30:31], v[122:123], 0, s[34:35]
	v_cvt_pk_bf16_f32 v18, v22, v23
	v_cvt_pk_bf16_f32 v19, v24, v25
	v_cvt_pk_bf16_f32 v20, v20, v21
	v_cvt_pk_bf16_f32 v21, v26, v27
	s_nop 0
	s_mov_b32 s13, 0x2c000
	global_store_dwordx4 v[30:31], v[18:21], off offset:256
	s_nop 0
	s_mov_b64 s[34:35], 0x2c000
	v_pk_add_f32 v[18:19], v[12:13], 0 op_sel_hi:[1,0]
	v_pk_add_f32 v[12:13], v[10:11], 0 op_sel_hi:[1,0]
	v_cvt_pk_bf16_f32 v11, v16, v17
	v_add_co_u32_e32 v16, vcc, s13, v122
	v_cvt_pk_bf16_f32 v10, v14, v15
	v_cvt_pk_bf16_f32 v12, v12, v13
	v_cvt_pk_bf16_f32 v13, v18, v19
	v_addc_co_u32_e32 v17, vcc, 0, v123, vcc
	global_store_dwordx4 v[16:17], v[10:13], off
	s_nop 0
	s_nop 0
	v_pk_add_f32 v[10:11], v[2:3], 0 op_sel_hi:[1,0]
	v_pk_add_f32 v[2:3], v[0:1], 0 op_sel_hi:[1,0]
	v_readlane_b32 s56, v254, 27
	v_lshl_add_u64 v[14:15], v[122:123], 0, s[34:35]
	v_cvt_pk_bf16_f32 v0, v4, v5
	v_cvt_pk_bf16_f32 v1, v6, v7
	v_cvt_pk_bf16_f32 v2, v2, v3
	v_cvt_pk_bf16_f32 v3, v10, v11
	s_andn2_b64 vcc, exec, s[4:5]
	s_mov_b64 s[4:5], -1
	v_readlane_b32 s57, v254, 28
	s_mov_b64 s[38:39], 0x800
	v_mov_b32_e32 v248, 0x3727c5ac
	global_store_dwordx4 v[14:15], v[0:3], off offset:256
	s_cbranch_vccnz .LBB0_406
	s_andn2_b64 vcc, exec, s[6:7]
	s_cbranch_vccnz .LBB0_405
	s_barrier
	s_branch .LBB0_405

;     __device__ __forceinline__ void operator()(const f32x4 (&acc)[2][2][4][2], const Unit& u, int wr, int wc, int fr_, int fq_) const {
;         const int lane_ = lane_id_v(), fr = lane_ & 15, fq = lane_ >> 4;
;         const int row0 = u.pm * 256 + wr * 64 + fr, col0 = u.pn * 256 + wc * 32 + 8 * fq;
;         f32x4 bv[2][2];
; #pragma unroll
;         for (int bj = 0; bj < 2; ++bj)
; #pragma unroll
;             for (int n = 0; n < 2; ++n) bv[bj][n] = (MODE == 1 || MODE == 2 || (MODE == 5 && bias != nullptr)) ? *(const f32x4*)(bias + col0 + bj * 128 + 4 * n) : (f32x4){0.f, 0.f, 0.f, 0.f};
;         u32x4v gq[2][4][2], pq[2][4][2];
;         if (MODE == 3 || MODE == 5) {
; #pragma unroll
;             for (int ai = 0; ai < 2; ++ai)
; #pragma unroll
;                 for (int m = 0; m < 4; ++m)
; #pragma unroll
;                     for (int bj = 0; bj < 2; ++bj) {
;                         const size_t rowi = (size_t)(row0 + ai * 128 + m * 16);
;                         if (MODE == 3) gq[ai][m][bj] = *(const u32x4v*)(G + rowi * ldg + col0 + bj * 128);
;                         if (MODE == 5) pq[ai][m][bj] = *(const u32x4v*)(O + rowi * ldc + col0 + bj * 128);
;                     }
;         }
; #pragma unroll
;         for (int ai = 0; ai < 2; ++ai) {
;             if (MODE == 4) {
; #pragma unroll
;                 for (int m = 0; m < 4; ++m)
; #pragma unroll
;                     for (int bj = 0; bj < 2; ++bj) {
;                         const size_t rowi = (size_t)(row0 + ai * 128 + m * 16);
;                         gq[ai][m][bj] = *(const u32x4v*)(G + rowi * ldg + col0 + bj * 128);
;                         pq[ai][m][bj] = *(const u32x4v*)(O + rowi * ldc + col0 + bj * 128);
;                     }
;             }
; #pragma unroll
;             for (int m = 0; m < 4; ++m) {
;                 const size_t ro = (size_t)(row0 + ai * 128 + m * 16) * ldc + col0;
; #pragma unroll
;                 for (int bj = 0; bj < 2; ++bj) {
;                     f32x4 v0 = acc[ai][bj][m][0] + bv[bj][0], v1 = acc[ai][bj][m][1] + bv[bj][1];
;                     if (MODE == 1) {
; #pragma unroll
;                         for (int j = 0; j < 4; ++j) { float a = fmaxf(v0[j], 0.f), b = fmaxf(v1[j], 0.f); v0[j] = a * a; v1[j] = b * b; }
;                     } else if (MODE == 2) {
; #pragma unroll
.LBB0_425:
	v_mbcnt_lo_u32_b32 v139, -1, 0
	v_mbcnt_hi_u32_b32 v139, -1, v139
	s_lshl_b32 s13, s36, 8
	v_ashrrev_i32_e32 v138, 1, v139
	v_and_b32_e32 v138, -8, v138
	s_or_b32 s13, s13, s44
	v_readlane_b32 s34, v252, 28
	v_add_u32_e32 v138, s13, v138
	v_and_or_b32 v139, v139, 15, s40
	s_nop 0
	s_nop 0
	s_nop 0
	v_readlane_b32 s35, v252, 29
	v_lshl_add_u32 v142, s18, 8, v139
	v_ashrrev_i32_e32 v139, 31, v138
	s_nop 0
	v_cvt_pk_bf16_f32 v126, v126, v127
	v_cvt_pk_bf16_f32 v127, v128, v129
	v_cvt_pk_bf16_f32 v128, v122, v123
	v_mov_b64_e32 v[122:123], s[34:35]
	s_mov_b32 s13, 0x30800
	v_cvt_pk_bf16_f32 v129, v124, v125
	v_mad_i64_i32 v[140:141], s[34:35], v142, s13, v[122:123]
	v_lshlrev_b64 v[124:125], 1, v[138:139]
	v_lshl_add_u64 v[138:139], v[140:141], 0, v[124:125]
	global_store_dwordx4 v[138:139], v[126:129], off
	s_nop 0
	s_nop 0
	v_pk_add_f32 v[126:127], v[116:117], 0 op_sel_hi:[1,0]
	v_pk_add_f32 v[116:117], v[114:115], 0 op_sel_hi:[1,0]
	v_cvt_pk_bf16_f32 v114, v118, v119
	v_cvt_pk_bf16_f32 v115, v120, v121
	v_cvt_pk_bf16_f32 v116, v116, v117
	v_cvt_pk_bf16_f32 v117, v126, v127
	global_store_dwordx4 v[138:139], v[114:117], off offset:256
	s_nop 0
	s_nop 0
	v_or_b32_e32 v116, 16, v142
	v_pk_add_f32 v[114:115], v[104:105], 0 op_sel_hi:[1,0]
	v_pk_add_f32 v[104:105], v[102:103], 0 op_sel_hi:[1,0]
	v_cvt_pk_bf16_f32 v102, v110, v111
	v_mad_i64_i32 v[110:111], s[34:35], v116, s13, v[122:123]
	v_cvt_pk_bf16_f32 v103, v112, v113
	v_cvt_pk_bf16_f32 v104, v104, v105
	v_cvt_pk_bf16_f32 v105, v114, v115
	v_lshl_add_u64 v[110:111], v[110:111], 0, v[124:125]
	global_store_dwordx4 v[110:111], v[102:105], off
	s_nop 0
	s_nop 0
	v_pk_add_f32 v[102:103], v[108:109], 0 op_sel_hi:[1,0]
	v_pk_add_f32 v[104:105], v[106:107], 0 op_sel_hi:[1,0]
	v_pk_add_f32 v[106:107], v[100:101], 0 op_sel_hi:[1,0]
	v_pk_add_f32 v[100:101], v[98:99], 0 op_sel_hi:[1,0]
	v_cvt_pk_bf16_f32 v98, v104, v105
	v_cvt_pk_bf16_f32 v99, v102, v103
	v_cvt_pk_bf16_f32 v100, v100, v101
	v_cvt_pk_bf16_f32 v101, v106, v107
	global_store_dwordx4 v[110:111], v[98:101], off offset:256
	s_nop 0
	s_nop 0
	v_or_b32_e32 v100, 32, v142
	v_pk_add_f32 v[98:99], v[88:89], 0 op_sel_hi:[1,0]
	v_pk_add_f32 v[88:89], v[86:87], 0 op_sel_hi:[1,0]
	v_cvt_pk_bf16_f32 v86, v94, v95
	v_mad_i64_i32 v[94:95], s[34:35], v100, s13, v[122:123]
	v_cvt_pk_bf16_f32 v87, v96, v97
	v_cvt_pk_bf16_f32 v88, v88, v89
	v_cvt_pk_bf16_f32 v89, v98, v99
	v_lshl_add_u64 v[94:95], v[94:95], 0, v[124:125]
	global_store_dwordx4 v[94:95], v[86:89], off
	s_nop 0
	s_nop 0
	v_pk_add_f32 v[86:87], v[92:93], 0 op_sel_hi:[1,0]
	v_pk_add_f32 v[88:89], v[90:91], 0 op_sel_hi:[1,0]
	v_pk_add_f32 v[90:91], v[84:85], 0 op_sel_hi:[1,0]
	v_pk_add_f32 v[84:85], v[82:83], 0 op_sel_hi:[1,0]
	v_cvt_pk_bf16_f32 v82, v88, v89
	v_cvt_pk_bf16_f32 v83, v86, v87
	v_cvt_pk_bf16_f32 v84, v84, v85
	v_cvt_pk_bf16_f32 v85, v90, v91
	global_store_dwordx4 v[94:95], v[82:85], off offset:256
	s_nop 0
	s_nop 0
	v_or_b32_e32 v84, 48, v142
	v_pk_add_f32 v[82:83], v[56:57], 0 op_sel_hi:[1,0]
	v_pk_add_f32 v[56:57], v[54:55], 0 op_sel_hi:[1,0]
	v_cvt_pk_bf16_f32 v54, v62, v63
	v_mad_i64_i32 v[62:63], s[34:35], v84, s13, v[122:123]
	v_cvt_pk_bf16_f32 v55, v64, v65
	v_cvt_pk_bf16_f32 v56, v56, v57
	v_cvt_pk_bf16_f32 v57, v82, v83
	v_lshl_add_u64 v[62:63], v[62:63], 0, v[124:125]
	global_store_dwordx4 v[62:63], v[54:57], off
	s_nop 0
	s_nop 0
	v_pk_add_f32 v[54:55], v[60:61], 0 op_sel_hi:[1,0]
	v_pk_add_f32 v[56:57], v[58:59], 0 op_sel_hi:[1,0]
	v_pk_add_f32 v[58:59], v[52:53], 0 op_sel_hi:[1,0]
	v_pk_add_f32 v[52:53], v[50:51], 0 op_sel_hi:[1,0]
	v_cvt_pk_bf16_f32 v50, v56, v57
	v_cvt_pk_bf16_f32 v51, v54, v55
	v_cvt_pk_bf16_f32 v52, v52, v53
	v_cvt_pk_bf16_f32 v53, v58, v59
;     __device__ __forceinline__ void operator()(const f32x4 (&acc)[2][2][4][2], const Unit& u, int wr, int wc, int fr_, int fq_) const {
;         const int lane_ = lane_id_v(), fr = lane_ & 15, fq = lane_ >> 4;
;         const int row0 = u.pm * 256 + wr * 64 + fr, col0 = u.pn * 256 + wc * 32 + 8 * fq;
;         f32x4 bv[2][2];
; #pragma unroll
;         for (int bj = 0; bj < 2; ++bj)
; #pragma unroll
;             for (int n = 0; n < 2; ++n) bv[bj][n] = (MODE == 1 || MODE == 2 || (MODE == 5 && bias != nullptr)) ? *(const f32x4*)(bias + col0 + bj * 128 + 4 * n) : (f32x4){0.f, 0.f, 0.f, 0.f};
;         u32x4v gq[2][4][2], pq[2][4][2];
;         if (MODE == 3 || MODE == 5) {
; #pragma unroll
;             for (int ai = 0; ai < 2; ++ai)
; #pragma unroll
;                 for (int m = 0; m < 4; ++m)
; #pragma unroll
;                     for (int bj = 0; bj < 2; ++bj) {
;                         const size_t rowi = (size_t)(row0 + ai * 128 + m * 16);
;                         if (MODE == 3) gq[ai][m][bj] = *(const u32x4v*)(G + rowi * ldg + col0 + bj * 128);
;                         if (MODE == 5) pq[ai][m][bj] = *(const u32x4v*)(O + rowi * ldc + col0 + bj * 128);
;                     }
;         }
; #pragma unroll
;         for (int ai = 0; ai < 2; ++ai) {
;             if (MODE == 4) {
; #pragma unroll
;                 for (int m = 0; m < 4; ++m)
; #pragma unroll
;                     for (int bj = 0; bj < 2; ++bj) {
;                         const size_t rowi = (size_t)(row0 + ai * 128 + m * 16);
;                         gq[ai][m][bj] = *(const u32x4v*)(G + rowi * ldg + col0 + bj * 128);
;                         pq[ai][m][bj] = *(const u32x4v*)(O + rowi * ldc + col0 + bj * 128);
;                     }
;             }
; #pragma unroll
;             for (int m = 0; m < 4; ++m) {
;                 const size_t ro = (size_t)(row0 + ai * 128 + m * 16) * ldc + col0;
; #pragma unroll
;                 for (int bj = 0; bj < 2; ++bj) {
;                     f32x4 v0 = acc[ai][bj][m][0] + bv[bj][0], v1 = acc[ai][bj][m][1] + bv[bj][1];
;                     if (MODE == 1) {
; #pragma unroll
;                         for (int j = 0; j < 4; ++j) { float a = fmaxf(v0[j], 0.f), b = fmaxf(v1[j], 0.f); v0[j] = a * a; v1[j] = b * b; }
;                     } else if (MODE == 2) {
; #pragma unroll
	global_store_dwordx4 v[62:63], v[50:53], off offset:256
	v_add_u32_e32 v58, 0x80, v142
	v_pk_add_f32 v[54:55], v[72:73], 0 op_sel_hi:[1,0]
	v_pk_add_f32 v[52:53], v[80:81], 0 op_sel_hi:[1,0]
	v_pk_add_f32 v[50:51], v[78:79], 0 op_sel_hi:[1,0]
	v_pk_add_f32 v[56:57], v[70:71], 0 op_sel_hi:[1,0]
	v_cvt_pk_bf16_f32 v50, v50, v51
	v_cvt_pk_bf16_f32 v51, v52, v53
	v_cvt_pk_bf16_f32 v53, v54, v55
	v_mad_i64_i32 v[54:55], s[34:35], v58, s13, v[122:123]
	v_cvt_pk_bf16_f32 v52, v56, v57
	v_lshl_add_u64 v[54:55], v[54:55], 0, v[124:125]
	global_store_dwordx4 v[54:55], v[50:53], off
	v_pk_add_f32 v[56:57], v[68:69], 0 op_sel_hi:[1,0]
	v_pk_add_f32 v[58:59], v[66:67], 0 op_sel_hi:[1,0]
	v_pk_add_f32 v[52:53], v[76:77], 0 op_sel_hi:[1,0]
	v_pk_add_f32 v[50:51], v[74:75], 0 op_sel_hi:[1,0]
	v_readlane_b32 s56, v254, 27
	v_cvt_pk_bf16_f32 v50, v50, v51
	v_cvt_pk_bf16_f32 v51, v52, v53
	v_cvt_pk_bf16_f32 v52, v58, v59
	v_cvt_pk_bf16_f32 v53, v56, v57
	global_store_dwordx4 v[54:55], v[50:53], off offset:256
	s_andn2_b64 vcc, exec, s[4:5]
	s_mov_b64 s[4:5], -1
	v_add_u32_e32 v52, 0x90, v142
	v_pk_add_f32 v[50:51], v[40:41], 0 op_sel_hi:[1,0]
	v_pk_add_f32 v[40:41], v[38:39], 0 op_sel_hi:[1,0]
	v_cvt_pk_bf16_f32 v38, v46, v47
	v_mad_i64_i32 v[46:47], s[34:35], v52, s13, v[122:123]
	v_cvt_pk_bf16_f32 v39, v48, v49
	v_cvt_pk_bf16_f32 v40, v40, v41
	v_cvt_pk_bf16_f32 v41, v50, v51
	v_lshl_add_u64 v[46:47], v[46:47], 0, v[124:125]
	global_store_dwordx4 v[46:47], v[38:41], off
	v_readlane_b32 s57, v254, 28
	s_mov_b64 s[38:39], 0x800
	v_pk_add_f32 v[38:39], v[44:45], 0 op_sel_hi:[1,0]
	v_pk_add_f32 v[40:41], v[42:43], 0 op_sel_hi:[1,0]
	v_pk_add_f32 v[42:43], v[36:37], 0 op_sel_hi:[1,0]
	v_pk_add_f32 v[36:37], v[34:35], 0 op_sel_hi:[1,0]
	v_cvt_pk_bf16_f32 v34, v40, v41
	v_cvt_pk_bf16_f32 v35, v38, v39
	v_cvt_pk_bf16_f32 v36, v36, v37
	v_cvt_pk_bf16_f32 v37, v42, v43
	global_store_dwordx4 v[46:47], v[34:37], off offset:256
	v_mov_b32_e32 v248, 0x3727c5ac
	s_nop 0
	v_add_u32_e32 v36, 0xa0, v142
	v_pk_add_f32 v[34:35], v[24:25], 0 op_sel_hi:[1,0]
	v_pk_add_f32 v[24:25], v[22:23], 0 op_sel_hi:[1,0]
	v_cvt_pk_bf16_f32 v22, v30, v31
	v_mad_i64_i32 v[30:31], s[34:35], v36, s13, v[122:123]
	v_cvt_pk_bf16_f32 v23, v32, v33
	v_cvt_pk_bf16_f32 v24, v24, v25
	v_cvt_pk_bf16_f32 v25, v34, v35
	v_lshl_add_u64 v[30:31], v[30:31], 0, v[124:125]
	global_store_dwordx4 v[30:31], v[22:25], off
	s_nop 1
	v_pk_add_f32 v[22:23], v[28:29], 0 op_sel_hi:[1,0]
	v_pk_add_f32 v[24:25], v[26:27], 0 op_sel_hi:[1,0]
	v_pk_add_f32 v[26:27], v[20:21], 0 op_sel_hi:[1,0]
	v_pk_add_f32 v[20:21], v[18:19], 0 op_sel_hi:[1,0]
	v_cvt_pk_bf16_f32 v18, v24, v25
	v_cvt_pk_bf16_f32 v19, v22, v23
	v_cvt_pk_bf16_f32 v20, v20, v21
	v_cvt_pk_bf16_f32 v21, v26, v27
	global_store_dwordx4 v[30:31], v[18:21], off offset:256
	s_nop 1
	v_add_u32_e32 v20, 0xb0, v142
	v_pk_add_f32 v[18:19], v[6:7], 0 op_sel_hi:[1,0]
	v_pk_add_f32 v[6:7], v[4:5], 0 op_sel_hi:[1,0]
	v_cvt_pk_bf16_f32 v4, v14, v15
	v_mad_i64_i32 v[14:15], s[34:35], v20, s13, v[122:123]
	v_cvt_pk_bf16_f32 v5, v16, v17
	v_cvt_pk_bf16_f32 v6, v6, v7
	v_cvt_pk_bf16_f32 v7, v18, v19
	v_lshl_add_u64 v[14:15], v[14:15], 0, v[124:125]
	global_store_dwordx4 v[14:15], v[4:7], off
	s_nop 1
	v_pk_add_f32 v[4:5], v[12:13], 0 op_sel_hi:[1,0]
	v_pk_add_f32 v[6:7], v[10:11], 0 op_sel_hi:[1,0]
	v_pk_add_f32 v[10:11], v[2:3], 0 op_sel_hi:[1,0]
	v_pk_add_f32 v[2:3], v[0:1], 0 op_sel_hi:[1,0]
	v_cvt_pk_bf16_f32 v0, v6, v7
	v_cvt_pk_bf16_f32 v1, v4, v5
	v_cvt_pk_bf16_f32 v2, v2, v3
	v_cvt_pk_bf16_f32 v3, v10, v11
	global_store_dwordx4 v[14:15], v[0:3], off offset:256
	s_cbranch_vccnz .LBB0_420
	s_andn2_b64 vcc, exec, s[6:7]
	s_cbranch_vccnz .LBB0_419
	s_barrier
	s_branch .LBB0_419

; __device__ __forceinline__ float bflo(unsigned u) { return __uint_as_float(u << 16); }
; __device__ __forceinline__ float bfhi(unsigned u) { return __uint_as_float(u & 0xffff0000u); }
;     __device__ __forceinline__ void operator()(const f32x4 (&acc)[2][2][4][2], const Unit& u, int wr, int wc, int fr_, int fq_) const {
;     ...
;         u32x4v gq[2][4][2], pq[2][4][2];
;         if (MODE == 3 || MODE == 5) {
; #pragma unroll
;             for (int ai = 0; ai < 2; ++ai)
; #pragma unroll
;                 for (int m = 0; m < 4; ++m)
; #pragma unroll
;                     for (int bj = 0; bj < 2; ++bj) {
;                         const size_t rowi = (size_t)(row0 + ai * 128 + m * 16);
;                         if (MODE == 3) gq[ai][m][bj] = *(const u32x4v*)(G + rowi * ldg + col0 + bj * 128);
;                         if (MODE == 5) pq[ai][m][bj] = *(const u32x4v*)(O + rowi * ldc + col0 + bj * 128);
;                     }
;         }
;     ...
;                     } else if (MODE == 3 || MODE == 4) {
;                         const u32x4v gg = gq[ai][m][bj];
;                         v0[0] *= bflo(gg[0]); v0[1] *= bfhi(gg[0]); v0[2] *= bflo(gg[1]); v0[3] *= bfhi(gg[1]);
;                         v1[0] *= bflo(gg[2]); v1[1] *= bfhi(gg[2]); v1[2] *= bflo(gg[3]); v1[3] *= bfhi(gg[3]);
.LBB0_595:
	s_lshl_b32 s13, s51, 8
	v_mbcnt_lo_u32_b32 v118, -1, 0
	v_mbcnt_hi_u32_b32 v118, -1, v118
	s_add_i32 s13, s13, s40
	v_and_or_b32 v206, v118, 15, s13
	v_ashrrev_i32_e32 v118, 1, v118
	s_lshl_b32 s13, s50, 8
	v_and_b32_e32 v118, -8, v118
	s_or_b32 s13, s13, s44
	v_add_u32_e32 v118, s13, v118
	v_ashrrev_i32_e32 v119, 31, v118
	v_readlane_b32 s34, v252, 6
	v_lshlrev_b64 v[200:201], 1, v[118:119]
	v_readlane_b32 s35, v252, 7
	s_movk_i32 s13, 0x1800
	v_or_b32_e32 v226, 16, v206
	v_lshl_add_u64 v[118:119], s[34:35], 0, v[200:201]
	v_mad_i64_i32 v[120:121], s[34:35], v206, s13, v[118:119]
	global_load_dwordx4 v[210:213], v[120:121], off
	global_load_dwordx4 v[186:189], v[120:121], off offset:256
	v_mad_i64_i32 v[120:121], s[34:35], v226, s13, v[118:119]
	global_load_dwordx4 v[182:185], v[120:121], off
	global_load_dwordx4 v[178:181], v[120:121], off offset:256
	v_or_b32_e32 v224, 32, v206
	v_mad_i64_i32 v[120:121], s[34:35], v224, s13, v[118:119]
	global_load_dwordx4 v[174:177], v[120:121], off
	global_load_dwordx4 v[170:173], v[120:121], off offset:256
	v_or_b32_e32 v222, 48, v206
	v_mad_i64_i32 v[120:121], s[34:35], v222, s13, v[118:119]
	global_load_dwordx4 v[166:169], v[120:121], off
	global_load_dwordx4 v[162:165], v[120:121], off offset:256
	v_add_u32_e32 v220, 0x80, v206
	v_mad_i64_i32 v[120:121], s[34:35], v220, s13, v[118:119]
	global_load_dwordx4 v[158:161], v[120:121], off
	global_load_dwordx4 v[154:157], v[120:121], off offset:256
	v_add_u32_e32 v218, 0x90, v206
	v_mad_i64_i32 v[120:121], s[34:35], v218, s13, v[118:119]
	global_load_dwordx4 v[150:153], v[120:121], off
	global_load_dwordx4 v[138:141], v[120:121], off offset:256
	v_add_u32_e32 v204, 0xa0, v206
	v_mad_i64_i32 v[120:121], s[34:35], v204, s13, v[118:119]
	global_load_dwordx4 v[134:137], v[120:121], off
	global_load_dwordx4 v[130:133], v[120:121], off offset:256
	s_nop 0
	s_nop 0
	s_nop 0
	v_ashrrev_i32_e32 v207, 31, v206
	s_nop 0
	v_readlane_b32 s36, v252, 0
	v_readlane_b32 s37, v252, 1
	v_add_u32_e32 v202, 0xb0, v206
	v_mad_i64_i32 v[118:119], s[34:35], v202, s13, v[118:119]
	global_load_dwordx4 v[126:129], v[118:119], off
	s_nop 0
	global_load_dwordx4 v[118:121], v[118:119], off offset:256
	s_nop 0
	s_nop 0
	s_nop 0
	s_nop 0
	s_nop 0
	s_nop 0
	s_nop 0
	v_ashrrev_i32_e32 v227, 31, v226
	s_nop 0
	s_nop 0
	s_nop 0
	s_nop 0
	s_nop 0
	s_nop 0
	s_nop 0
	s_nop 0
	v_ashrrev_i32_e32 v225, 31, v224
	s_nop 0
	s_nop 0
	s_nop 0
	s_nop 0
	s_nop 0
	s_nop 0
	s_nop 0
	s_nop 0
	v_ashrrev_i32_e32 v223, 31, v222
	s_nop 0
	s_nop 0
	s_nop 0
	s_nop 0
	s_nop 0
	s_nop 0
	s_nop 0
	s_nop 0
	v_ashrrev_i32_e32 v221, 31, v220
	s_nop 0
	s_nop 0
	s_nop 0
	s_nop 0
	s_nop 0
	s_nop 0
	s_nop 0
	s_nop 0
	v_ashrrev_i32_e32 v219, 31, v218
	s_waitcnt vmcnt(0)
	v_lshlrev_b32_e32 v208, 16, v210
	v_and_b32_e32 v209, 0xffff0000, v210
	v_pk_mul_f32 v[146:147], v[146:147], v[208:209]
	v_lshlrev_b32_e32 v208, 16, v211
	v_and_b32_e32 v209, 0xffff0000, v211
	v_pk_mul_f32 v[148:149], v[148:149], v[208:209]
	v_lshlrev_b32_e32 v208, 16, v212
	v_and_b32_e32 v209, 0xffff0000, v212
	v_pk_mul_f32 v[142:143], v[142:143], v[208:209]
	v_lshlrev_b32_e32 v208, 16, v213
	v_and_b32_e32 v209, 0xffff0000, v213
	v_pk_mul_f32 v[208:209], v[144:145], v[208:209]
	v_cvt_pk_bf16_f32 v144, v146, v147
	v_cvt_pk_bf16_f32 v146, v142, v143
	v_lshlrev_b64 v[142:143], 11, v[206:207]
	v_lshl_add_u64 v[142:143], s[36:37], 0, v[142:143]
	v_cvt_pk_bf16_f32 v145, v148, v149
	v_cvt_pk_bf16_f32 v147, v208, v209
	v_lshl_add_u64 v[142:143], v[142:143], 0, v[200:201]
	global_store_dwordx4 v[142:143], v[144:147], off
	s_nop 0
	s_nop 0
	v_lshlrev_b32_e32 v144, 16, v186
	v_and_b32_e32 v145, 0xffff0000, v186
	v_pk_mul_f32 v[122:123], v[122:123], v[144:145]
	v_lshlrev_b32_e32 v144, 16, v187
	v_and_b32_e32 v145, 0xffff0000, v187
	v_pk_mul_f32 v[124:125], v[124:125], v[144:145]
	v_lshlrev_b32_e32 v144, 16, v188
	v_and_b32_e32 v145, 0xffff0000, v188
	v_pk_mul_f32 v[144:145], v[114:115], v[144:145]
	v_lshlrev_b32_e32 v114, 16, v189
	v_and_b32_e32 v115, 0xffff0000, v189
	v_pk_mul_f32 v[146:147], v[116:117], v[114:115]
	v_cvt_pk_bf16_f32 v114, v122, v123
	v_cvt_pk_bf16_f32 v115, v124, v125
	v_cvt_pk_bf16_f32 v116, v144, v145
	v_cvt_pk_bf16_f32 v117, v146, v147
	global_store_dwordx4 v[142:143], v[114:117], off offset:256
	s_nop 0
	s_nop 0
	v_lshlrev_b32_e32 v114, 16, v182
	v_and_b32_e32 v115, 0xffff0000, v182
	v_pk_mul_f32 v[110:111], v[110:111], v[114:115]
	v_lshlrev_b32_e32 v114, 16, v183
	v_and_b32_e32 v115, 0xffff0000, v183
	v_pk_mul_f32 v[112:113], v[112:113], v[114:115]
	v_lshlrev_b32_e32 v114, 16, v184
	v_and_b32_e32 v115, 0xffff0000, v184
	v_pk_mul_f32 v[114:115], v[106:107], v[114:115]
	v_lshlrev_b32_e32 v106, 16, v185
	v_and_b32_e32 v107, 0xffff0000, v185
	v_pk_mul_f32 v[116:117], v[108:109], v[106:107]
	v_cvt_pk_bf16_f32 v106, v110, v111
	v_lshlrev_b64 v[110:111], 11, v[226:227]
	v_lshl_add_u64 v[110:111], s[36:37], 0, v[110:111]
	v_cvt_pk_bf16_f32 v107, v112, v113
	v_cvt_pk_bf16_f32 v108, v114, v115
	v_cvt_pk_bf16_f32 v109, v116, v117
	v_lshl_add_u64 v[110:111], v[110:111], 0, v[200:201]
	global_store_dwordx4 v[110:111], v[106:109], off
	s_nop 0
	s_nop 0
	v_lshlrev_b32_e32 v106, 16, v178
	v_and_b32_e32 v107, 0xffff0000, v178
	v_pk_mul_f32 v[102:103], v[102:103], v[106:107]
	v_lshlrev_b32_e32 v106, 16, v179
	v_and_b32_e32 v107, 0xffff0000, v179
	v_pk_mul_f32 v[104:105], v[104:105], v[106:107]
	v_lshlrev_b32_e32 v106, 16, v180
	v_and_b32_e32 v107, 0xffff0000, v180
	v_pk_mul_f32 v[106:107], v[98:99], v[106:107]
	v_lshlrev_b32_e32 v98, 16, v181
	v_and_b32_e32 v99, 0xffff0000, v181
	v_pk_mul_f32 v[108:109], v[100:101], v[98:99]
	v_cvt_pk_bf16_f32 v98, v102, v103
; __device__ __forceinline__ unsigned cvt_pk_bf16(float lo, float hi) { const f32x2c v = {lo, hi}; const bf16x2c b = __builtin_convertvector(v, bf16x2c); return __builtin_bit_cast(unsigned, b); }
; __device__ __forceinline__ float bflo(unsigned u) { return __uint_as_float(u << 16); }
; __device__ __forceinline__ float bfhi(unsigned u) { return __uint_as_float(u & 0xffff0000u); }
;     __device__ __forceinline__ void operator()(const f32x4 (&acc)[2][2][4][2], const Unit& u, int wr, int wc, int fr_, int fq_) const {
;     ...
;                     } else if (MODE == 3 || MODE == 4) {
;                         const u32x4v gg = gq[ai][m][bj];
;                         v0[0] *= bflo(gg[0]); v0[1] *= bfhi(gg[0]); v0[2] *= bflo(gg[1]); v0[3] *= bfhi(gg[1]);
;                         v1[0] *= bflo(gg[2]); v1[1] *= bfhi(gg[2]); v1[2] *= bflo(gg[3]); v1[3] *= bfhi(gg[3]);
;                         if (MODE == 4) {
;                             const u32x4v pp = pq[ai][m][bj];
;                             v0[0] += bflo(pp[0]); v0[1] += bfhi(pp[0]); v0[2] += bflo(pp[1]); v0[3] += bfhi(pp[1]);
;                             v1[0] += bflo(pp[2]); v1[1] += bfhi(pp[2]); v1[2] += bflo(pp[3]); v1[3] += bfhi(pp[3]);
;                         }
;                     }
;                     u32x4v o; o[0] = cvt_pk_bf16(v0[0], v0[1]); o[1] = cvt_pk_bf16(v0[2], v0[3]); o[2] = cvt_pk_bf16(v1[0], v1[1]); o[3] = cvt_pk_bf16(v1[2], v1[3]);
;                     if (MODE == 1) __builtin_nontemporal_store(o, (u32x4v*)(O + ro + bj * 128));
;                     else *(u32x4v*)(O + ro + bj * 128) = o;
	v_cvt_pk_bf16_f32 v99, v104, v105
	v_cvt_pk_bf16_f32 v100, v106, v107
	v_cvt_pk_bf16_f32 v101, v108, v109
	global_store_dwordx4 v[110:111], v[98:101], off offset:256
	s_nop 0
	s_nop 0
	v_lshlrev_b32_e32 v98, 16, v174
	v_and_b32_e32 v99, 0xffff0000, v174
	v_pk_mul_f32 v[94:95], v[94:95], v[98:99]
	v_lshlrev_b32_e32 v98, 16, v175
	v_and_b32_e32 v99, 0xffff0000, v175
	v_pk_mul_f32 v[96:97], v[96:97], v[98:99]
	v_lshlrev_b32_e32 v98, 16, v176
	v_and_b32_e32 v99, 0xffff0000, v176
	v_pk_mul_f32 v[98:99], v[90:91], v[98:99]
	v_lshlrev_b32_e32 v90, 16, v177
	v_and_b32_e32 v91, 0xffff0000, v177
	v_pk_mul_f32 v[100:101], v[92:93], v[90:91]
	v_cvt_pk_bf16_f32 v90, v94, v95
	v_lshlrev_b64 v[94:95], 11, v[224:225]
	v_lshl_add_u64 v[94:95], s[36:37], 0, v[94:95]
	v_cvt_pk_bf16_f32 v91, v96, v97
	v_cvt_pk_bf16_f32 v92, v98, v99
	v_cvt_pk_bf16_f32 v93, v100, v101
	v_lshl_add_u64 v[94:95], v[94:95], 0, v[200:201]
	global_store_dwordx4 v[94:95], v[90:93], off
	v_ashrrev_i32_e32 v205, 31, v204
	s_nop 0
	v_lshlrev_b32_e32 v90, 16, v170
	v_and_b32_e32 v91, 0xffff0000, v170
	v_pk_mul_f32 v[86:87], v[86:87], v[90:91]
	v_lshlrev_b32_e32 v90, 16, v171
	v_and_b32_e32 v91, 0xffff0000, v171
	v_pk_mul_f32 v[88:89], v[88:89], v[90:91]
	v_lshlrev_b32_e32 v90, 16, v172
	v_and_b32_e32 v91, 0xffff0000, v172
	v_pk_mul_f32 v[90:91], v[82:83], v[90:91]
	v_lshlrev_b32_e32 v82, 16, v173
	v_and_b32_e32 v83, 0xffff0000, v173
	v_pk_mul_f32 v[92:93], v[84:85], v[82:83]
	v_cvt_pk_bf16_f32 v82, v86, v87
	v_cvt_pk_bf16_f32 v83, v88, v89
	v_cvt_pk_bf16_f32 v84, v90, v91
	v_cvt_pk_bf16_f32 v85, v92, v93
	global_store_dwordx4 v[94:95], v[82:85], off offset:256
	s_nop 0
	s_nop 0
	v_lshlrev_b32_e32 v82, 16, v166
	v_and_b32_e32 v83, 0xffff0000, v166
	v_pk_mul_f32 v[78:79], v[78:79], v[82:83]
	v_lshlrev_b32_e32 v82, 16, v167
	v_and_b32_e32 v83, 0xffff0000, v167
	v_pk_mul_f32 v[80:81], v[80:81], v[82:83]
	v_lshlrev_b32_e32 v82, 16, v168
	v_and_b32_e32 v83, 0xffff0000, v168
	v_pk_mul_f32 v[82:83], v[74:75], v[82:83]
	v_lshlrev_b32_e32 v74, 16, v169
	v_and_b32_e32 v75, 0xffff0000, v169
	v_pk_mul_f32 v[84:85], v[76:77], v[74:75]
	v_cvt_pk_bf16_f32 v74, v78, v79
	v_lshlrev_b64 v[78:79], 11, v[222:223]
	v_lshl_add_u64 v[78:79], s[36:37], 0, v[78:79]
	v_cvt_pk_bf16_f32 v75, v80, v81
	v_cvt_pk_bf16_f32 v76, v82, v83
	v_cvt_pk_bf16_f32 v77, v84, v85
	v_lshl_add_u64 v[78:79], v[78:79], 0, v[200:201]
	global_store_dwordx4 v[78:79], v[74:77], off
	s_nop 0
	s_nop 0
	v_lshlrev_b32_e32 v74, 16, v162
	v_and_b32_e32 v75, 0xffff0000, v162
	v_pk_mul_f32 v[70:71], v[70:71], v[74:75]
	v_lshlrev_b32_e32 v74, 16, v163
	v_and_b32_e32 v75, 0xffff0000, v163
	v_pk_mul_f32 v[72:73], v[72:73], v[74:75]
	v_lshlrev_b32_e32 v74, 16, v164
	v_and_b32_e32 v75, 0xffff0000, v164
	v_pk_mul_f32 v[74:75], v[66:67], v[74:75]
	v_lshlrev_b32_e32 v66, 16, v165
	v_and_b32_e32 v67, 0xffff0000, v165
	v_pk_mul_f32 v[76:77], v[68:69], v[66:67]
	v_cvt_pk_bf16_f32 v66, v70, v71
	v_cvt_pk_bf16_f32 v67, v72, v73
	v_cvt_pk_bf16_f32 v68, v74, v75
	v_cvt_pk_bf16_f32 v69, v76, v77
	global_store_dwordx4 v[78:79], v[66:69], off offset:256
	s_nop 0
	s_nop 0
	v_lshlrev_b32_e32 v66, 16, v158
	v_and_b32_e32 v67, 0xffff0000, v158
	v_pk_mul_f32 v[62:63], v[62:63], v[66:67]
	v_lshlrev_b32_e32 v66, 16, v159
	v_and_b32_e32 v67, 0xffff0000, v159
	v_pk_mul_f32 v[64:65], v[64:65], v[66:67]
	v_lshlrev_b32_e32 v66, 16, v160
	v_and_b32_e32 v67, 0xffff0000, v160
	v_pk_mul_f32 v[66:67], v[58:59], v[66:67]
	v_lshlrev_b32_e32 v58, 16, v161
	v_and_b32_e32 v59, 0xffff0000, v161
	v_pk_mul_f32 v[68:69], v[60:61], v[58:59]
	v_cvt_pk_bf16_f32 v58, v62, v63
	v_lshlrev_b64 v[62:63], 11, v[220:221]
	v_lshl_add_u64 v[62:63], s[36:37], 0, v[62:63]
	v_cvt_pk_bf16_f32 v59, v64, v65
	v_cvt_pk_bf16_f32 v60, v66, v67
	v_cvt_pk_bf16_f32 v61, v68, v69
	v_lshl_add_u64 v[62:63], v[62:63], 0, v[200:201]
	global_store_dwordx4 v[62:63], v[58:61], off
	s_nop 0
	v_ashrrev_i32_e32 v203, 31, v202
	v_lshlrev_b32_e32 v58, 16, v154
	v_and_b32_e32 v59, 0xffff0000, v154
	v_pk_mul_f32 v[54:55], v[54:55], v[58:59]
	v_lshlrev_b32_e32 v58, 16, v155
	v_and_b32_e32 v59, 0xffff0000, v155
	v_pk_mul_f32 v[56:57], v[56:57], v[58:59]
	v_lshlrev_b32_e32 v58, 16, v156
	v_and_b32_e32 v59, 0xffff0000, v156
	v_pk_mul_f32 v[58:59], v[50:51], v[58:59]
	v_lshlrev_b32_e32 v50, 16, v157
	v_and_b32_e32 v51, 0xffff0000, v157
	v_pk_mul_f32 v[60:61], v[52:53], v[50:51]
	v_cvt_pk_bf16_f32 v50, v54, v55
	v_cvt_pk_bf16_f32 v51, v56, v57
	v_cvt_pk_bf16_f32 v52, v58, v59
	v_cvt_pk_bf16_f32 v53, v60, v61
	global_store_dwordx4 v[62:63], v[50:53], off offset:256
; __device__ __forceinline__ unsigned cvt_pk_bf16(float lo, float hi) { const f32x2c v = {lo, hi}; const bf16x2c b = __builtin_convertvector(v, bf16x2c); return __builtin_bit_cast(unsigned, b); }
; #define PG8_BAR __builtin_amdgcn_s_barrier()
; __device__ __forceinline__ float bflo(unsigned u) { return __uint_as_float(u << 16); }
; __device__ __forceinline__ float bfhi(unsigned u) { return __uint_as_float(u & 0xffff0000u); }
; template <class Epi, class Sched, bool ALIGN_EPI = false, bool SP2 = false>
; __device__ __forceinline__ void gemm_phase(PG8_LAS unsigned char* lds, int tid_in, const Gemm g, const Sched& S, const Epi& E) {
;     ...
;         if (!has_next) break;
; #pragma unroll
;         for (int a = 0; a < 2; ++a)
; #pragma unroll
;             for (int b = 0; b < 2; ++b)
; #pragma unroll
;                 for (int m = 0; m < 4; ++m)
; #pragma unroll
;                     for (int n = 0; n < 2; ++n) acc[a][b][m][n] = (f32x4){0.f, 0.f, 0.f, 0.f};
;         cur = nxt; cA = nA; cB = nB; ++ui;
;         if constexpr (ALIGN_EPI) { if (wr == 1) PG8_BAR; }
;     __device__ __forceinline__ void operator()(const f32x4 (&acc)[2][2][4][2], const Unit& u, int wr, int wc, int fr_, int fq_) const {
;     ...
;                     } else if (MODE == 3 || MODE == 4) {
;                         const u32x4v gg = gq[ai][m][bj];
;                         v0[0] *= bflo(gg[0]); v0[1] *= bfhi(gg[0]); v0[2] *= bflo(gg[1]); v0[3] *= bfhi(gg[1]);
;                         v1[0] *= bflo(gg[2]); v1[1] *= bfhi(gg[2]); v1[2] *= bflo(gg[3]); v1[3] *= bfhi(gg[3]);
;                         if (MODE == 4) {
;                             const u32x4v pp = pq[ai][m][bj];
;                             v0[0] += bflo(pp[0]); v0[1] += bfhi(pp[0]); v0[2] += bflo(pp[1]); v0[3] += bfhi(pp[1]);
;                             v1[0] += bflo(pp[2]); v1[1] += bfhi(pp[2]); v1[2] += bflo(pp[3]); v1[3] += bfhi(pp[3]);
;                         }
;                     }
;                     u32x4v o; o[0] = cvt_pk_bf16(v0[0], v0[1]); o[1] = cvt_pk_bf16(v0[2], v0[3]); o[2] = cvt_pk_bf16(v1[0], v1[1]); o[3] = cvt_pk_bf16(v1[2], v1[3]);
;                     if (MODE == 1) __builtin_nontemporal_store(o, (u32x4v*)(O + ro + bj * 128));
;                     else *(u32x4v*)(O + ro + bj * 128) = o;
;                 }
;             }
;         }
;     }
	s_nop 0
	s_nop 0
	v_lshlrev_b32_e32 v50, 16, v150
	v_and_b32_e32 v51, 0xffff0000, v150
	v_pk_mul_f32 v[46:47], v[46:47], v[50:51]
	v_lshlrev_b32_e32 v50, 16, v151
	v_and_b32_e32 v51, 0xffff0000, v151
	v_pk_mul_f32 v[48:49], v[48:49], v[50:51]
	v_lshlrev_b32_e32 v50, 16, v152
	v_and_b32_e32 v51, 0xffff0000, v152
	v_pk_mul_f32 v[50:51], v[42:43], v[50:51]
	v_lshlrev_b32_e32 v42, 16, v153
	v_and_b32_e32 v43, 0xffff0000, v153
	v_pk_mul_f32 v[52:53], v[44:45], v[42:43]
	v_cvt_pk_bf16_f32 v42, v46, v47
	v_lshlrev_b64 v[46:47], 11, v[218:219]
	v_lshl_add_u64 v[46:47], s[36:37], 0, v[46:47]
	v_cvt_pk_bf16_f32 v43, v48, v49
	v_cvt_pk_bf16_f32 v44, v50, v51
	v_cvt_pk_bf16_f32 v45, v52, v53
	v_lshl_add_u64 v[46:47], v[46:47], 0, v[200:201]
	global_store_dwordx4 v[46:47], v[42:45], off
	s_nop 0
	s_nop 0
	v_lshlrev_b32_e32 v42, 16, v138
	v_and_b32_e32 v43, 0xffff0000, v138
	v_pk_mul_f32 v[38:39], v[38:39], v[42:43]
	v_lshlrev_b32_e32 v42, 16, v139
	v_and_b32_e32 v43, 0xffff0000, v139
	v_pk_mul_f32 v[40:41], v[40:41], v[42:43]
	v_lshlrev_b32_e32 v42, 16, v140
	v_and_b32_e32 v43, 0xffff0000, v140
	v_pk_mul_f32 v[42:43], v[34:35], v[42:43]
	v_lshlrev_b32_e32 v34, 16, v141
	v_and_b32_e32 v35, 0xffff0000, v141
	v_pk_mul_f32 v[44:45], v[36:37], v[34:35]
	v_cvt_pk_bf16_f32 v34, v38, v39
	v_cvt_pk_bf16_f32 v35, v40, v41
	v_cvt_pk_bf16_f32 v36, v42, v43
	v_cvt_pk_bf16_f32 v37, v44, v45
	global_store_dwordx4 v[46:47], v[34:37], off offset:256
	s_nop 0
	v_readlane_b32 s56, v254, 27
	v_lshlrev_b32_e32 v34, 16, v134
	v_and_b32_e32 v35, 0xffff0000, v134
	v_pk_mul_f32 v[30:31], v[30:31], v[34:35]
	v_lshlrev_b32_e32 v34, 16, v135
	v_and_b32_e32 v35, 0xffff0000, v135
	v_pk_mul_f32 v[32:33], v[32:33], v[34:35]
	v_lshlrev_b32_e32 v34, 16, v136
	v_and_b32_e32 v35, 0xffff0000, v136
	v_pk_mul_f32 v[34:35], v[26:27], v[34:35]
	v_lshlrev_b32_e32 v26, 16, v137
	v_and_b32_e32 v27, 0xffff0000, v137
	v_pk_mul_f32 v[36:37], v[28:29], v[26:27]
	v_cvt_pk_bf16_f32 v26, v30, v31
	v_lshlrev_b64 v[30:31], 11, v[204:205]
	v_lshl_add_u64 v[30:31], s[36:37], 0, v[30:31]
	v_cvt_pk_bf16_f32 v27, v32, v33
	v_cvt_pk_bf16_f32 v28, v34, v35
	v_cvt_pk_bf16_f32 v29, v36, v37
	v_lshl_add_u64 v[30:31], v[30:31], 0, v[200:201]
	global_store_dwordx4 v[30:31], v[26:29], off
	s_mov_b64 s[34:35], -1
	s_andn2_b64 vcc, exec, s[6:7]
	v_lshlrev_b32_e32 v26, 16, v130
	v_and_b32_e32 v27, 0xffff0000, v130
	v_pk_mul_f32 v[22:23], v[22:23], v[26:27]
	v_lshlrev_b32_e32 v26, 16, v131
	v_and_b32_e32 v27, 0xffff0000, v131
	v_pk_mul_f32 v[24:25], v[24:25], v[26:27]
	v_lshlrev_b32_e32 v26, 16, v132
	v_and_b32_e32 v27, 0xffff0000, v132
	v_pk_mul_f32 v[26:27], v[18:19], v[26:27]
	v_lshlrev_b32_e32 v18, 16, v133
	v_and_b32_e32 v19, 0xffff0000, v133
	v_pk_mul_f32 v[28:29], v[20:21], v[18:19]
	v_cvt_pk_bf16_f32 v18, v22, v23
	v_cvt_pk_bf16_f32 v19, v24, v25
	v_cvt_pk_bf16_f32 v20, v26, v27
	v_cvt_pk_bf16_f32 v21, v28, v29
	global_store_dwordx4 v[30:31], v[18:21], off offset:256
	v_readlane_b32 s57, v254, 28
	v_readlane_b32 s38, v252, 2
	v_lshlrev_b32_e32 v18, 16, v126
	v_and_b32_e32 v19, 0xffff0000, v126
	v_pk_mul_f32 v[14:15], v[14:15], v[18:19]
	v_lshlrev_b32_e32 v18, 16, v127
	v_and_b32_e32 v19, 0xffff0000, v127
	v_pk_mul_f32 v[16:17], v[16:17], v[18:19]
	v_lshlrev_b32_e32 v18, 16, v128
	v_and_b32_e32 v19, 0xffff0000, v128
	v_pk_mul_f32 v[18:19], v[10:11], v[18:19]
	v_lshlrev_b32_e32 v10, 16, v129
	v_and_b32_e32 v11, 0xffff0000, v129
	v_pk_mul_f32 v[20:21], v[12:13], v[10:11]
	v_cvt_pk_bf16_f32 v10, v14, v15
	v_lshlrev_b64 v[14:15], 11, v[202:203]
	v_lshl_add_u64 v[14:15], s[36:37], 0, v[14:15]
	v_cvt_pk_bf16_f32 v11, v16, v17
	v_cvt_pk_bf16_f32 v12, v18, v19
	v_cvt_pk_bf16_f32 v13, v20, v21
	v_lshl_add_u64 v[14:15], v[14:15], 0, v[200:201]
	global_store_dwordx4 v[14:15], v[10:13], off
	v_readlane_b32 s39, v252, 3
	s_nop 0
	v_lshlrev_b32_e32 v10, 16, v118
	v_and_b32_e32 v11, 0xffff0000, v118
	v_pk_mul_f32 v[4:5], v[4:5], v[10:11]
	v_lshlrev_b32_e32 v10, 16, v119
	v_and_b32_e32 v11, 0xffff0000, v119
	v_pk_mul_f32 v[6:7], v[6:7], v[10:11]
	v_lshlrev_b32_e32 v10, 16, v120
	v_and_b32_e32 v11, 0xffff0000, v120
	v_pk_mul_f32 v[10:11], v[0:1], v[10:11]
	v_lshlrev_b32_e32 v0, 16, v121
	v_and_b32_e32 v1, 0xffff0000, v121
	v_pk_mul_f32 v[12:13], v[2:3], v[0:1]
	v_cvt_pk_bf16_f32 v0, v4, v5
	v_cvt_pk_bf16_f32 v1, v6, v7
	v_cvt_pk_bf16_f32 v2, v10, v11
	v_cvt_pk_bf16_f32 v3, v12, v13
	global_store_dwordx4 v[14:15], v[0:3], off offset:256
	s_cbranch_vccnz .LBB0_584
	s_andn2_b64 vcc, exec, s[8:9]
	s_cbranch_vccnz .LBB0_583
	s_barrier
	s_branch .LBB0_583

; __device__ __forceinline__ float bflo(unsigned u) { return __uint_as_float(u << 16); }
; __device__ __forceinline__ float bfhi(unsigned u) { return __uint_as_float(u & 0xffff0000u); }
;     __device__ __forceinline__ void operator()(const f32x4 (&acc)[2][2][4][2], const Unit& u, int wr, int wc, int fr_, int fq_) const {
;     ...
;         for (int ai = 0; ai < 2; ++ai) {
;             if (MODE == 4) {
; #pragma unroll
;                 for (int m = 0; m < 4; ++m)
; #pragma unroll
;                     for (int bj = 0; bj < 2; ++bj) {
;                         const size_t rowi = (size_t)(row0 + ai * 128 + m * 16);
;                         gq[ai][m][bj] = *(const u32x4v*)(G + rowi * ldg + col0 + bj * 128);
;                         pq[ai][m][bj] = *(const u32x4v*)(O + rowi * ldc + col0 + bj * 128);
;                     }
;             }
;     ...
;                     } else if (MODE == 3 || MODE == 4) {
;                         const u32x4v gg = gq[ai][m][bj];
;                         v0[0] *= bflo(gg[0]); v0[1] *= bfhi(gg[0]); v0[2] *= bflo(gg[1]); v0[3] *= bfhi(gg[1]);
;                         v1[0] *= bflo(gg[2]); v1[1] *= bfhi(gg[2]); v1[2] *= bflo(gg[3]); v1[3] *= bfhi(gg[3]);
;                         if (MODE == 4) {
;                             const u32x4v pp = pq[ai][m][bj];
;                             v0[0] += bflo(pp[0]); v0[1] += bfhi(pp[0]); v0[2] += bflo(pp[1]); v0[3] += bfhi(pp[1]);
;                             v1[0] += bflo(pp[2]); v1[1] += bfhi(pp[2]); v1[2] += bflo(pp[3]); v1[3] += bfhi(pp[3]);
;                         }
.LBB0_613:
	s_lshl_b32 s15, s36, 8
	v_mbcnt_lo_u32_b32 v90, -1, 0
	v_mbcnt_hi_u32_b32 v90, -1, v90
	s_add_i32 s15, s15, s40
	v_and_or_b32 v194, v90, 15, s15
	v_ashrrev_i32_e32 v90, 1, v90
	s_lshl_b32 s15, s18, 8
	v_and_b32_e32 v90, -8, v90
	s_or_b32 s15, s15, s44
	v_add_u32_e32 v90, s15, v90
	v_ashrrev_i32_e32 v91, 31, v90
	v_readlane_b32 s36, v252, 38
	v_lshlrev_b64 v[192:193], 1, v[90:91]
	v_readlane_b32 s37, v252, 39
	v_readlane_b32 s48, v252, 0
	v_readlane_b32 s49, v252, 1
	v_lshl_add_u64 v[196:197], s[36:37], 0, v[192:193]
	v_ashrrev_i32_e32 v195, 31, v194
	s_movk_i32 s15, 0x1800
	v_lshl_add_u64 v[198:199], s[48:49], 0, v[192:193]
	v_mad_i64_i32 v[90:91], s[36:37], v194, s15, v[196:197]
	v_lshlrev_b64 v[206:207], 11, v[194:195]
	v_lshl_add_u64 v[92:93], v[198:199], 0, v[206:207]
	global_load_dwordx4 v[210:213], v[90:91], off
	global_load_dwordx4 v[214:217], v[92:93], off
	global_load_dwordx4 v[166:169], v[90:91], off offset:256
	global_load_dwordx4 v[162:165], v[92:93], off offset:256
	v_or_b32_e32 v90, 16, v194
	v_ashrrev_i32_e32 v91, 31, v90
	v_mad_i64_i32 v[92:93], s[36:37], v90, s15, v[196:197]
	v_lshlrev_b64 v[204:205], 11, v[90:91]
	v_lshl_add_u64 v[90:91], v[198:199], 0, v[204:205]
	global_load_dwordx4 v[158:161], v[92:93], off
	global_load_dwordx4 v[154:157], v[90:91], off
	global_load_dwordx4 v[150:153], v[92:93], off offset:256
	global_load_dwordx4 v[146:149], v[90:91], off offset:256
	v_or_b32_e32 v90, 32, v194
	v_ashrrev_i32_e32 v91, 31, v90
	v_mad_i64_i32 v[92:93], s[36:37], v90, s15, v[196:197]
	v_lshlrev_b64 v[202:203], 11, v[90:91]
	v_lshl_add_u64 v[90:91], v[198:199], 0, v[202:203]
	global_load_dwordx4 v[142:145], v[92:93], off
	global_load_dwordx4 v[138:141], v[90:91], off
	global_load_dwordx4 v[126:129], v[92:93], off offset:256
	global_load_dwordx4 v[122:125], v[90:91], off offset:256
	v_or_b32_e32 v90, 48, v194
	v_ashrrev_i32_e32 v91, 31, v90
	v_lshlrev_b64 v[200:201], 11, v[90:91]
	v_mad_i64_i32 v[92:93], s[36:37], v90, s15, v[196:197]
	v_lshl_add_u64 v[90:91], v[198:199], 0, v[200:201]
	global_load_dwordx4 v[110:113], v[92:93], off
	global_load_dwordx4 v[106:109], v[90:91], off
	global_load_dwordx4 v[94:97], v[92:93], off offset:256
	s_nop 0
	global_load_dwordx4 v[90:93], v[90:91], off offset:256
	s_nop 0
	s_nop 0
	s_nop 0
	s_nop 0
	s_nop 0
	s_nop 0
	s_nop 0
	s_nop 0
	s_nop 0
	s_nop 0
	s_nop 0
	s_nop 0
	s_nop 0
	s_nop 0
	s_nop 0
	s_nop 0
	s_nop 0
	s_nop 0
	s_nop 0
	s_nop 0
	s_nop 0
	s_nop 0
	s_nop 0
	s_nop 0
	s_nop 0
	s_nop 0
	s_nop 0
	s_nop 0
	s_nop 0
	s_nop 0
	s_nop 0
	s_nop 0
	s_nop 0
	s_nop 0
	s_nop 0
	s_nop 0
	s_nop 0
	s_nop 0
	s_nop 0
	s_nop 0
	s_nop 0
	s_nop 0
	s_nop 0
	s_nop 0
	s_nop 0
	s_nop 0
	s_nop 0
	s_nop 0
	s_nop 0
	s_nop 0
	s_nop 0
	s_nop 0
	s_nop 0
	s_nop 0
	s_nop 0
	s_waitcnt vmcnt(0)
	v_lshlrev_b32_e32 v208, 16, v210
	v_and_b32_e32 v209, 0xffff0000, v210
	v_lshlrev_b32_e32 v220, 16, v214
	v_and_b32_e32 v221, 0xffff0000, v214
	v_pk_fma_f32 v[182:183], v[182:183], v[208:209], v[220:221]
	v_lshlrev_b32_e32 v208, 16, v211
	v_and_b32_e32 v209, 0xffff0000, v211
	v_lshlrev_b32_e32 v210, 16, v215
	v_and_b32_e32 v211, 0xffff0000, v215
	v_pk_fma_f32 v[184:185], v[184:185], v[208:209], v[210:211]
	v_lshlrev_b32_e32 v208, 16, v212
	v_and_b32_e32 v209, 0xffff0000, v212
	v_lshlrev_b32_e32 v210, 16, v216
	v_and_b32_e32 v211, 0xffff0000, v216
	v_pk_fma_f32 v[178:179], v[178:179], v[208:209], v[210:211]
	v_lshlrev_b32_e32 v208, 16, v213
	v_and_b32_e32 v209, 0xffff0000, v213
	v_lshlrev_b32_e32 v210, 16, v217
	v_and_b32_e32 v211, 0xffff0000, v217
	v_pk_fma_f32 v[208:209], v[180:181], v[208:209], v[210:211]
	v_cvt_pk_bf16_f32 v180, v182, v183
	v_cvt_pk_bf16_f32 v182, v178, v179
	v_lshl_add_u64 v[178:179], s[48:49], 0, v[206:207]
	v_cvt_pk_bf16_f32 v181, v184, v185
	v_cvt_pk_bf16_f32 v183, v208, v209
	v_lshl_add_u64 v[178:179], v[178:179], 0, v[192:193]
	global_store_dwordx4 v[178:179], v[180:183], off
	s_nop 0
	s_nop 0
	v_lshlrev_b32_e32 v180, 16, v166
	v_and_b32_e32 v181, 0xffff0000, v166
	v_lshlrev_b32_e32 v182, 16, v162
	v_and_b32_e32 v183, 0xffff0000, v162
	v_lshlrev_b32_e32 v166, 16, v167
	v_and_b32_e32 v167, 0xffff0000, v167
	v_lshlrev_b32_e32 v162, 16, v163
	v_and_b32_e32 v163, 0xffff0000, v163
	v_pk_fma_f32 v[166:167], v[176:177], v[166:167], v[162:163]
	v_lshlrev_b32_e32 v162, 16, v168
	v_and_b32_e32 v163, 0xffff0000, v168
	v_lshlrev_b32_e32 v176, 16, v164
	v_and_b32_e32 v177, 0xffff0000, v164
	v_pk_fma_f32 v[170:171], v[170:171], v[162:163], v[176:177]
	v_lshlrev_b32_e32 v162, 16, v169
	v_and_b32_e32 v163, 0xffff0000, v169
	v_lshlrev_b32_e32 v164, 16, v165
	v_and_b32_e32 v165, 0xffff0000, v165
	v_pk_fma_f32 v[174:175], v[174:175], v[180:181], v[182:183]
	v_pk_fma_f32 v[168:169], v[172:173], v[162:163], v[164:165]
	v_cvt_pk_bf16_f32 v162, v174, v175
	v_cvt_pk_bf16_f32 v163, v166, v167
	v_cvt_pk_bf16_f32 v164, v170, v171
	v_cvt_pk_bf16_f32 v165, v168, v169
	global_store_dwordx4 v[178:179], v[162:165], off offset:256
	s_nop 0
	s_nop 0
	v_lshlrev_b32_e32 v162, 16, v158
	v_and_b32_e32 v163, 0xffff0000, v158
	v_lshlrev_b32_e32 v164, 16, v154
	v_and_b32_e32 v165, 0xffff0000, v154
	v_lshlrev_b32_e32 v158, 16, v159
	v_and_b32_e32 v159, 0xffff0000, v159
	v_lshlrev_b32_e32 v154, 16, v155
	v_and_b32_e32 v155, 0xffff0000, v155
	v_pk_fma_f32 v[136:137], v[136:137], v[158:159], v[154:155]
	v_lshlrev_b32_e32 v154, 16, v160
	v_and_b32_e32 v155, 0xffff0000, v160
	v_lshlrev_b32_e32 v158, 16, v156
	v_and_b32_e32 v159, 0xffff0000, v156
	v_pk_fma_f32 v[134:135], v[134:135], v[162:163], v[164:165]
	v_pk_fma_f32 v[154:155], v[130:131], v[154:155], v[158:159]
	v_lshlrev_b32_e32 v130, 16, v161
	v_and_b32_e32 v131, 0xffff0000, v161
; __device__ __forceinline__ unsigned cvt_pk_bf16(float lo, float hi) { const f32x2c v = {lo, hi}; const bf16x2c b = __builtin_convertvector(v, bf16x2c); return __builtin_bit_cast(unsigned, b); }
; __device__ __forceinline__ float bflo(unsigned u) { return __uint_as_float(u << 16); }
; __device__ __forceinline__ float bfhi(unsigned u) { return __uint_as_float(u & 0xffff0000u); }
;     __device__ __forceinline__ void operator()(const f32x4 (&acc)[2][2][4][2], const Unit& u, int wr, int wc, int fr_, int fq_) const {
;     ...
;                     } else if (MODE == 3 || MODE == 4) {
;                         const u32x4v gg = gq[ai][m][bj];
;                         v0[0] *= bflo(gg[0]); v0[1] *= bfhi(gg[0]); v0[2] *= bflo(gg[1]); v0[3] *= bfhi(gg[1]);
;                         v1[0] *= bflo(gg[2]); v1[1] *= bfhi(gg[2]); v1[2] *= bflo(gg[3]); v1[3] *= bfhi(gg[3]);
;                         if (MODE == 4) {
;                             const u32x4v pp = pq[ai][m][bj];
;                             v0[0] += bflo(pp[0]); v0[1] += bfhi(pp[0]); v0[2] += bflo(pp[1]); v0[3] += bfhi(pp[1]);
;                             v1[0] += bflo(pp[2]); v1[1] += bfhi(pp[2]); v1[2] += bflo(pp[3]); v1[3] += bfhi(pp[3]);
;                         }
;                     }
;                     u32x4v o; o[0] = cvt_pk_bf16(v0[0], v0[1]); o[1] = cvt_pk_bf16(v0[2], v0[3]); o[2] = cvt_pk_bf16(v1[0], v1[1]); o[3] = cvt_pk_bf16(v1[2], v1[3]);
;                     if (MODE == 1) __builtin_nontemporal_store(o, (u32x4v*)(O + ro + bj * 128));
;                     else *(u32x4v*)(O + ro + bj * 128) = o;
	v_lshlrev_b32_e32 v156, 16, v157
	v_and_b32_e32 v157, 0xffff0000, v157
	v_pk_fma_f32 v[156:157], v[132:133], v[130:131], v[156:157]
	v_cvt_pk_bf16_f32 v130, v134, v135
	v_lshl_add_u64 v[134:135], s[48:49], 0, v[204:205]
	v_cvt_pk_bf16_f32 v131, v136, v137
	v_cvt_pk_bf16_f32 v132, v154, v155
	v_cvt_pk_bf16_f32 v133, v156, v157
	v_lshl_add_u64 v[134:135], v[134:135], 0, v[192:193]
	global_store_dwordx4 v[134:135], v[130:133], off
	s_nop 0
	s_nop 0
	v_lshlrev_b32_e32 v130, 16, v150
	v_and_b32_e32 v131, 0xffff0000, v150
	v_lshlrev_b32_e32 v132, 16, v146
	v_and_b32_e32 v133, 0xffff0000, v146
	v_pk_fma_f32 v[118:119], v[118:119], v[130:131], v[132:133]
	v_lshlrev_b32_e32 v130, 16, v151
	v_and_b32_e32 v131, 0xffff0000, v151
	v_lshlrev_b32_e32 v132, 16, v147
	v_and_b32_e32 v133, 0xffff0000, v147
	v_pk_fma_f32 v[120:121], v[120:121], v[130:131], v[132:133]
	v_lshlrev_b32_e32 v130, 16, v152
	v_and_b32_e32 v131, 0xffff0000, v152
	v_lshlrev_b32_e32 v132, 16, v148
	v_and_b32_e32 v133, 0xffff0000, v148
	v_pk_fma_f32 v[130:131], v[114:115], v[130:131], v[132:133]
	v_lshlrev_b32_e32 v114, 16, v153
	v_and_b32_e32 v115, 0xffff0000, v153
	v_lshlrev_b32_e32 v132, 16, v149
	v_and_b32_e32 v133, 0xffff0000, v149
	v_pk_fma_f32 v[132:133], v[116:117], v[114:115], v[132:133]
	v_cvt_pk_bf16_f32 v114, v118, v119
	v_cvt_pk_bf16_f32 v115, v120, v121
	v_cvt_pk_bf16_f32 v116, v130, v131
	v_cvt_pk_bf16_f32 v117, v132, v133
	global_store_dwordx4 v[134:135], v[114:117], off offset:256
	s_nop 0
	s_nop 0
	v_lshlrev_b32_e32 v114, 16, v142
	v_and_b32_e32 v115, 0xffff0000, v142
	v_lshlrev_b32_e32 v116, 16, v138
	v_and_b32_e32 v117, 0xffff0000, v138
	v_pk_fma_f32 v[102:103], v[102:103], v[114:115], v[116:117]
	v_lshlrev_b32_e32 v114, 16, v143
	v_and_b32_e32 v115, 0xffff0000, v143
	v_lshlrev_b32_e32 v116, 16, v139
	v_and_b32_e32 v117, 0xffff0000, v139
	v_pk_fma_f32 v[104:105], v[104:105], v[114:115], v[116:117]
	v_lshlrev_b32_e32 v114, 16, v144
	v_and_b32_e32 v115, 0xffff0000, v144
	v_lshlrev_b32_e32 v116, 16, v140
	v_and_b32_e32 v117, 0xffff0000, v140
	v_pk_fma_f32 v[114:115], v[98:99], v[114:115], v[116:117]
	v_lshlrev_b32_e32 v98, 16, v145
	v_and_b32_e32 v99, 0xffff0000, v145
	v_lshlrev_b32_e32 v116, 16, v141
	v_and_b32_e32 v117, 0xffff0000, v141
	v_pk_fma_f32 v[116:117], v[100:101], v[98:99], v[116:117]
	v_cvt_pk_bf16_f32 v98, v102, v103
	v_lshl_add_u64 v[102:103], s[48:49], 0, v[202:203]
	v_cvt_pk_bf16_f32 v99, v104, v105
	v_cvt_pk_bf16_f32 v100, v114, v115
	v_cvt_pk_bf16_f32 v101, v116, v117
	v_lshl_add_u64 v[102:103], v[102:103], 0, v[192:193]
	global_store_dwordx4 v[102:103], v[98:101], off
	s_nop 0
	v_readlane_b32 s56, v254, 27
	v_lshlrev_b32_e32 v98, 16, v126
	v_and_b32_e32 v99, 0xffff0000, v126
	v_lshlrev_b32_e32 v100, 16, v122
	v_and_b32_e32 v101, 0xffff0000, v122
	v_pk_fma_f32 v[86:87], v[86:87], v[98:99], v[100:101]
	v_lshlrev_b32_e32 v98, 16, v127
	v_and_b32_e32 v99, 0xffff0000, v127
	v_lshlrev_b32_e32 v100, 16, v123
	v_and_b32_e32 v101, 0xffff0000, v123
	v_pk_fma_f32 v[88:89], v[88:89], v[98:99], v[100:101]
	v_lshlrev_b32_e32 v98, 16, v128
	v_and_b32_e32 v99, 0xffff0000, v128
	v_lshlrev_b32_e32 v100, 16, v124
	v_and_b32_e32 v101, 0xffff0000, v124
	v_pk_fma_f32 v[98:99], v[82:83], v[98:99], v[100:101]
	v_lshlrev_b32_e32 v82, 16, v129
	v_and_b32_e32 v83, 0xffff0000, v129
	v_lshlrev_b32_e32 v100, 16, v125
	v_and_b32_e32 v101, 0xffff0000, v125
	v_pk_fma_f32 v[100:101], v[84:85], v[82:83], v[100:101]
	v_cvt_pk_bf16_f32 v82, v86, v87
	v_cvt_pk_bf16_f32 v83, v88, v89
	v_cvt_pk_bf16_f32 v84, v98, v99
	v_cvt_pk_bf16_f32 v85, v100, v101
	global_store_dwordx4 v[102:103], v[82:85], off offset:256
	s_mov_b64 s[42:43], -1
	s_andn2_b64 vcc, exec, s[6:7]
	v_lshlrev_b32_e32 v82, 16, v110
	v_and_b32_e32 v83, 0xffff0000, v110
	v_lshlrev_b32_e32 v84, 16, v106
	v_and_b32_e32 v85, 0xffff0000, v106
	v_pk_fma_f32 v[78:79], v[78:79], v[82:83], v[84:85]
	v_lshlrev_b32_e32 v82, 16, v111
	v_and_b32_e32 v83, 0xffff0000, v111
	v_lshlrev_b32_e32 v84, 16, v107
	v_and_b32_e32 v85, 0xffff0000, v107
	v_pk_fma_f32 v[80:81], v[80:81], v[82:83], v[84:85]
	v_lshlrev_b32_e32 v82, 16, v112
	v_and_b32_e32 v83, 0xffff0000, v112
	v_lshlrev_b32_e32 v84, 16, v108
	v_and_b32_e32 v85, 0xffff0000, v108
	v_pk_fma_f32 v[82:83], v[74:75], v[82:83], v[84:85]
	v_lshlrev_b32_e32 v74, 16, v113
	v_and_b32_e32 v75, 0xffff0000, v113
	v_lshlrev_b32_e32 v84, 16, v109
	v_and_b32_e32 v85, 0xffff0000, v109
	v_pk_fma_f32 v[84:85], v[76:77], v[74:75], v[84:85]
	v_cvt_pk_bf16_f32 v74, v78, v79
	v_lshl_add_u64 v[78:79], s[48:49], 0, v[200:201]
	v_cvt_pk_bf16_f32 v75, v80, v81
	v_cvt_pk_bf16_f32 v76, v82, v83
	v_cvt_pk_bf16_f32 v77, v84, v85
	v_lshl_add_u64 v[78:79], v[78:79], 0, v[192:193]
	global_store_dwordx4 v[78:79], v[74:77], off
	v_readlane_b32 s57, v254, 28
	s_mov_b64 s[38:39], 0x800
	v_lshlrev_b32_e32 v74, 16, v94
	v_and_b32_e32 v75, 0xffff0000, v94
	v_lshlrev_b32_e32 v76, 16, v90
	v_and_b32_e32 v77, 0xffff0000, v90
	v_pk_fma_f32 v[70:71], v[70:71], v[74:75], v[76:77]
	v_lshlrev_b32_e32 v74, 16, v95
	v_and_b32_e32 v75, 0xffff0000, v95
	v_lshlrev_b32_e32 v76, 16, v91
	v_and_b32_e32 v77, 0xffff0000, v91
	v_pk_fma_f32 v[72:73], v[72:73], v[74:75], v[76:77]
	v_lshlrev_b32_e32 v74, 16, v96
	v_and_b32_e32 v75, 0xffff0000, v96
	v_lshlrev_b32_e32 v76, 16, v92
	v_and_b32_e32 v77, 0xffff0000, v92
	v_pk_fma_f32 v[74:75], v[66:67], v[74:75], v[76:77]
	v_lshlrev_b32_e32 v66, 16, v97
	v_and_b32_e32 v67, 0xffff0000, v97
	v_lshlrev_b32_e32 v76, 16, v93
	v_and_b32_e32 v77, 0xffff0000, v93
	v_pk_fma_f32 v[76:77], v[68:69], v[66:67], v[76:77]
	v_cvt_pk_bf16_f32 v66, v70, v71
	v_cvt_pk_bf16_f32 v67, v72, v73
	v_cvt_pk_bf16_f32 v68, v74, v75
;     __device__ __forceinline__ void operator()(const f32x4 (&acc)[2][2][4][2], const Unit& u, int wr, int wc, int fr_, int fq_) const {
;     ...
;         for (int ai = 0; ai < 2; ++ai) {
;             if (MODE == 4) {
; #pragma unroll
;                 for (int m = 0; m < 4; ++m)
; #pragma unroll
;                     for (int bj = 0; bj < 2; ++bj) {
;                         const size_t rowi = (size_t)(row0 + ai * 128 + m * 16);
;                         gq[ai][m][bj] = *(const u32x4v*)(G + rowi * ldg + col0 + bj * 128);
;                         pq[ai][m][bj] = *(const u32x4v*)(O + rowi * ldc + col0 + bj * 128);
;                     }
;             }
; #pragma unroll
;             for (int m = 0; m < 4; ++m) {
;                 const size_t ro = (size_t)(row0 + ai * 128 + m * 16) * ldc + col0;
; #pragma unroll
;                 for (int bj = 0; bj < 2; ++bj) {
;                     f32x4 v0 = acc[ai][bj][m][0] + bv[bj][0], v1 = acc[ai][bj][m][1] + bv[bj][1];
;                     if (MODE == 1) {
; #pragma unroll
;                         for (int j = 0; j < 4; ++j) { float a = fmaxf(v0[j], 0.f), b = fmaxf(v1[j], 0.f); v0[j] = a * a; v1[j] = b * b; }
;                     } else if (MODE == 2) {
; #pragma unroll
;                         for (int j = 0; j < 4; ++j) { v0[j] = sigmoidf_(v0[j]); v1[j] = sigmoidf_(v1[j]); }
;                     } else if (MODE == 5) {
;                         const u32x4v pp = pq[ai][m][bj];
;                         v0[0] += DN_ALPHA * bflo(pp[0]); v0[1] += DN_ALPHA * bfhi(pp[0]); v0[2] += DN_ALPHA * bflo(pp[1]); v0[3] += DN_ALPHA * bfhi(pp[1]);
;                         v1[0] += DN_ALPHA * bflo(pp[2]); v1[1] += DN_ALPHA * bfhi(pp[2]); v1[2] += DN_ALPHA * bflo(pp[3]); v1[3] += DN_ALPHA * bfhi(pp[3]);
;                     } else if (MODE == 3 || MODE == 4) {
;                         const u32x4v gg = gq[ai][m][bj];
;                         v0[0] *= bflo(gg[0]); v0[1] *= bfhi(gg[0]); v0[2] *= bflo(gg[1]); v0[3] *= bfhi(gg[1]);
;                         v1[0] *= bflo(gg[2]); v1[1] *= bfhi(gg[2]); v1[2] *= bflo(gg[3]); v1[3] *= bfhi(gg[3]);
;                         if (MODE == 4) {
;                             const u32x4v pp = pq[ai][m][bj];
;                             v0[0] += bflo(pp[0]); v0[1] += bfhi(pp[0]); v0[2] += bflo(pp[1]); v0[3] += bfhi(pp[1]);
	v_cvt_pk_bf16_f32 v69, v76, v77
	global_store_dwordx4 v[78:79], v[66:69], off offset:256
	v_readlane_b32 s50, v252, 2
	v_readlane_b32 s51, v252, 3
	v_add_u32_e32 v66, 0x80, v194
	v_ashrrev_i32_e32 v67, 31, v66
	v_mad_i64_i32 v[68:69], s[36:37], v66, s15, v[196:197]
	v_lshlrev_b64 v[134:135], 11, v[66:67]
	v_lshl_add_u64 v[66:67], v[198:199], 0, v[134:135]
	global_load_dwordx4 v[102:105], v[68:69], off
	global_load_dwordx4 v[106:109], v[66:67], off
	global_load_dwordx4 v[110:113], v[68:69], off offset:256
	global_load_dwordx4 v[114:117], v[66:67], off offset:256
	v_add_u32_e32 v66, 0x90, v194
	v_ashrrev_i32_e32 v67, 31, v66
	v_mad_i64_i32 v[68:69], s[36:37], v66, s15, v[196:197]
	v_lshlrev_b64 v[136:137], 11, v[66:67]
	v_lshl_add_u64 v[66:67], v[198:199], 0, v[136:137]
	global_load_dwordx4 v[118:121], v[68:69], off
	global_load_dwordx4 v[122:125], v[66:67], off
	global_load_dwordx4 v[126:129], v[68:69], off offset:256
	global_load_dwordx4 v[130:133], v[66:67], off offset:256
	v_add_u32_e32 v66, 0xa0, v194
	v_ashrrev_i32_e32 v67, 31, v66
	v_mad_i64_i32 v[68:69], s[36:37], v66, s15, v[196:197]
	v_lshlrev_b64 v[100:101], 11, v[66:67]
	v_lshl_add_u64 v[66:67], v[198:199], 0, v[100:101]
	global_load_dwordx4 v[94:97], v[68:69], off
	global_load_dwordx4 v[90:93], v[66:67], off
	global_load_dwordx4 v[82:85], v[68:69], off offset:256
	global_load_dwordx4 v[86:89], v[66:67], off offset:256
	v_add_u32_e32 v66, 0xb0, v194
	v_ashrrev_i32_e32 v67, 31, v66
	v_lshlrev_b64 v[98:99], 11, v[66:67]
	v_mad_i64_i32 v[68:69], s[36:37], v66, s15, v[196:197]
	v_lshl_add_u64 v[70:71], v[198:199], 0, v[98:99]
	global_load_dwordx4 v[78:81], v[68:69], off
	global_load_dwordx4 v[74:77], v[70:71], off
	s_nop 0
	global_load_dwordx4 v[66:69], v[68:69], off offset:256
	s_nop 0
	global_load_dwordx4 v[70:73], v[70:71], off offset:256
	s_waitcnt vmcnt(15)
	v_lshlrev_b32_e32 v138, 16, v102
	v_and_b32_e32 v139, 0xffff0000, v102
	s_waitcnt vmcnt(14)
	v_lshlrev_b32_e32 v140, 16, v106
	v_and_b32_e32 v141, 0xffff0000, v106
	v_lshlrev_b32_e32 v102, 16, v103
	v_and_b32_e32 v103, 0xffff0000, v103
	v_lshlrev_b32_e32 v106, 16, v107
	v_and_b32_e32 v107, 0xffff0000, v107
	v_pk_fma_f32 v[64:65], v[64:65], v[102:103], v[106:107]
	v_lshlrev_b32_e32 v102, 16, v104
	v_and_b32_e32 v103, 0xffff0000, v104
	v_lshlrev_b32_e32 v106, 16, v108
	v_and_b32_e32 v107, 0xffff0000, v108
	v_pk_fma_f32 v[62:63], v[62:63], v[138:139], v[140:141]
	v_pk_fma_f32 v[102:103], v[58:59], v[102:103], v[106:107]
	v_lshlrev_b32_e32 v58, 16, v105
	v_and_b32_e32 v59, 0xffff0000, v105
	v_lshlrev_b32_e32 v104, 16, v109
	v_and_b32_e32 v105, 0xffff0000, v109
	v_pk_fma_f32 v[104:105], v[60:61], v[58:59], v[104:105]
	v_cvt_pk_bf16_f32 v58, v62, v63
	v_lshl_add_u64 v[62:63], s[48:49], 0, v[134:135]
	v_cvt_pk_bf16_f32 v59, v64, v65
	v_cvt_pk_bf16_f32 v60, v102, v103
	v_cvt_pk_bf16_f32 v61, v104, v105
	v_lshl_add_u64 v[62:63], v[62:63], 0, v[192:193]
	global_store_dwordx4 v[62:63], v[58:61], off
	s_waitcnt vmcnt(14)
	s_nop 0
	v_lshlrev_b32_e32 v58, 16, v110
	v_and_b32_e32 v59, 0xffff0000, v110
	s_waitcnt vmcnt(13)
	v_lshlrev_b32_e32 v60, 16, v114
	v_and_b32_e32 v61, 0xffff0000, v114
	v_pk_fma_f32 v[54:55], v[54:55], v[58:59], v[60:61]
	v_lshlrev_b32_e32 v58, 16, v111
	v_and_b32_e32 v59, 0xffff0000, v111
	v_lshlrev_b32_e32 v60, 16, v115
	v_and_b32_e32 v61, 0xffff0000, v115
	v_pk_fma_f32 v[56:57], v[56:57], v[58:59], v[60:61]
	v_lshlrev_b32_e32 v58, 16, v112
	v_and_b32_e32 v59, 0xffff0000, v112
	v_lshlrev_b32_e32 v60, 16, v116
	v_and_b32_e32 v61, 0xffff0000, v116
	v_pk_fma_f32 v[58:59], v[50:51], v[58:59], v[60:61]
	v_lshlrev_b32_e32 v50, 16, v113
	v_and_b32_e32 v51, 0xffff0000, v113
	v_lshlrev_b32_e32 v60, 16, v117
	v_and_b32_e32 v61, 0xffff0000, v117
	v_pk_fma_f32 v[60:61], v[52:53], v[50:51], v[60:61]
	v_cvt_pk_bf16_f32 v50, v54, v55
	v_cvt_pk_bf16_f32 v51, v56, v57
	v_cvt_pk_bf16_f32 v52, v58, v59
	v_cvt_pk_bf16_f32 v53, v60, v61
	global_store_dwordx4 v[62:63], v[50:53], off offset:256
	s_waitcnt vmcnt(13)
	s_nop 0
	v_lshlrev_b32_e32 v50, 16, v118
	v_and_b32_e32 v51, 0xffff0000, v118
	s_waitcnt vmcnt(12)
	v_lshlrev_b32_e32 v52, 16, v122
	v_and_b32_e32 v53, 0xffff0000, v122
	v_pk_fma_f32 v[46:47], v[46:47], v[50:51], v[52:53]
	v_lshlrev_b32_e32 v50, 16, v119
	v_and_b32_e32 v51, 0xffff0000, v119
	v_lshlrev_b32_e32 v52, 16, v123
	v_and_b32_e32 v53, 0xffff0000, v123
	v_pk_fma_f32 v[48:49], v[48:49], v[50:51], v[52:53]
	v_lshlrev_b32_e32 v50, 16, v120
	v_and_b32_e32 v51, 0xffff0000, v120
	v_lshlrev_b32_e32 v52, 16, v124
	v_and_b32_e32 v53, 0xffff0000, v124
	v_pk_fma_f32 v[50:51], v[42:43], v[50:51], v[52:53]
	v_lshlrev_b32_e32 v42, 16, v121
	v_and_b32_e32 v43, 0xffff0000, v121
	v_lshlrev_b32_e32 v52, 16, v125
	v_and_b32_e32 v53, 0xffff0000, v125
	v_pk_fma_f32 v[52:53], v[44:45], v[42:43], v[52:53]
	v_cvt_pk_bf16_f32 v42, v46, v47
	v_lshl_add_u64 v[46:47], s[48:49], 0, v[136:137]
	v_cvt_pk_bf16_f32 v43, v48, v49
	v_cvt_pk_bf16_f32 v44, v50, v51
	v_cvt_pk_bf16_f32 v45, v52, v53
	v_lshl_add_u64 v[46:47], v[46:47], 0, v[192:193]
	global_store_dwordx4 v[46:47], v[42:45], off
	s_waitcnt vmcnt(12)
	s_nop 0
	v_lshlrev_b32_e32 v42, 16, v126
	v_and_b32_e32 v43, 0xffff0000, v126
	s_waitcnt vmcnt(11)
;     __device__ __forceinline__ void operator()(const f32x4 (&acc)[2][2][4][2], const Unit& u, int wr, int wc, int fr_, int fq_) const {
;     ...
; #pragma unroll
;             for (int m = 0; m < 4; ++m) {
;                 const size_t ro = (size_t)(row0 + ai * 128 + m * 16) * ldc + col0;
; #pragma unroll
;                 for (int bj = 0; bj < 2; ++bj) {
;                     f32x4 v0 = acc[ai][bj][m][0] + bv[bj][0], v1 = acc[ai][bj][m][1] + bv[bj][1];
;                     if (MODE == 1) {
; #pragma unroll
;                         for (int j = 0; j < 4; ++j) { float a = fmaxf(v0[j], 0.f), b = fmaxf(v1[j], 0.f); v0[j] = a * a; v1[j] = b * b; }
;                     } else if (MODE == 2) {
; #pragma unroll
;                         for (int j = 0; j < 4; ++j) { v0[j] = sigmoidf_(v0[j]); v1[j] = sigmoidf_(v1[j]); }
;                     } else if (MODE == 5) {
;                         const u32x4v pp = pq[ai][m][bj];
;                         v0[0] += DN_ALPHA * bflo(pp[0]); v0[1] += DN_ALPHA * bfhi(pp[0]); v0[2] += DN_ALPHA * bflo(pp[1]); v0[3] += DN_ALPHA * bfhi(pp[1]);
;                         v1[0] += DN_ALPHA * bflo(pp[2]); v1[1] += DN_ALPHA * bfhi(pp[2]); v1[2] += DN_ALPHA * bflo(pp[3]); v1[3] += DN_ALPHA * bfhi(pp[3]);
;                     } else if (MODE == 3 || MODE == 4) {
;                         const u32x4v gg = gq[ai][m][bj];
;                         v0[0] *= bflo(gg[0]); v0[1] *= bfhi(gg[0]); v0[2] *= bflo(gg[1]); v0[3] *= bfhi(gg[1]);
;                         v1[0] *= bflo(gg[2]); v1[1] *= bfhi(gg[2]); v1[2] *= bflo(gg[3]); v1[3] *= bfhi(gg[3]);
;                         if (MODE == 4) {
;                             const u32x4v pp = pq[ai][m][bj];
;                             v0[0] += bflo(pp[0]); v0[1] += bfhi(pp[0]); v0[2] += bflo(pp[1]); v0[3] += bfhi(pp[1]);
;                             v1[0] += bflo(pp[2]); v1[1] += bfhi(pp[2]); v1[2] += bflo(pp[3]); v1[3] += bfhi(pp[3]);
;                         }
;                     }
;                     u32x4v o; o[0] = cvt_pk_bf16(v0[0], v0[1]); o[1] = cvt_pk_bf16(v0[2], v0[3]); o[2] = cvt_pk_bf16(v1[0], v1[1]); o[3] = cvt_pk_bf16(v1[2], v1[3]);
;                     if (MODE == 1) __builtin_nontemporal_store(o, (u32x4v*)(O + ro + bj * 128));
;                     else *(u32x4v*)(O + ro + bj * 128) = o;
;                 }
;             }
;         }
;     }
	v_lshlrev_b32_e32 v44, 16, v130
	v_and_b32_e32 v45, 0xffff0000, v130
	v_pk_fma_f32 v[38:39], v[38:39], v[42:43], v[44:45]
	v_lshlrev_b32_e32 v42, 16, v127
	v_and_b32_e32 v43, 0xffff0000, v127
	v_lshlrev_b32_e32 v44, 16, v131
	v_and_b32_e32 v45, 0xffff0000, v131
	v_pk_fma_f32 v[40:41], v[40:41], v[42:43], v[44:45]
	v_lshlrev_b32_e32 v42, 16, v128
	v_and_b32_e32 v43, 0xffff0000, v128
	v_lshlrev_b32_e32 v44, 16, v132
	v_and_b32_e32 v45, 0xffff0000, v132
	v_pk_fma_f32 v[42:43], v[34:35], v[42:43], v[44:45]
	v_lshlrev_b32_e32 v34, 16, v129
	v_and_b32_e32 v35, 0xffff0000, v129
	v_lshlrev_b32_e32 v44, 16, v133
	v_and_b32_e32 v45, 0xffff0000, v133
	v_pk_fma_f32 v[44:45], v[36:37], v[34:35], v[44:45]
	v_cvt_pk_bf16_f32 v34, v38, v39
	v_cvt_pk_bf16_f32 v35, v40, v41
	v_cvt_pk_bf16_f32 v36, v42, v43
	v_cvt_pk_bf16_f32 v37, v44, v45
	global_store_dwordx4 v[46:47], v[34:37], off offset:256
	s_waitcnt vmcnt(11)
	s_nop 0
	v_lshlrev_b32_e32 v34, 16, v94
	v_and_b32_e32 v35, 0xffff0000, v94
	s_waitcnt vmcnt(10)
	v_lshlrev_b32_e32 v36, 16, v90
	v_and_b32_e32 v37, 0xffff0000, v90
	v_pk_fma_f32 v[30:31], v[30:31], v[34:35], v[36:37]
	v_lshlrev_b32_e32 v34, 16, v95
	v_and_b32_e32 v35, 0xffff0000, v95
	v_lshlrev_b32_e32 v36, 16, v91
	v_and_b32_e32 v37, 0xffff0000, v91
	v_pk_fma_f32 v[32:33], v[32:33], v[34:35], v[36:37]
	v_lshlrev_b32_e32 v34, 16, v96
	v_and_b32_e32 v35, 0xffff0000, v96
	v_lshlrev_b32_e32 v36, 16, v92
	v_and_b32_e32 v37, 0xffff0000, v92
	v_pk_fma_f32 v[34:35], v[26:27], v[34:35], v[36:37]
	v_lshlrev_b32_e32 v26, 16, v97
	v_and_b32_e32 v27, 0xffff0000, v97
	v_lshlrev_b32_e32 v36, 16, v93
	v_and_b32_e32 v37, 0xffff0000, v93
	v_pk_fma_f32 v[36:37], v[28:29], v[26:27], v[36:37]
	v_cvt_pk_bf16_f32 v26, v30, v31
	v_lshl_add_u64 v[30:31], s[48:49], 0, v[100:101]
	v_cvt_pk_bf16_f32 v27, v32, v33
	v_cvt_pk_bf16_f32 v28, v34, v35
	v_cvt_pk_bf16_f32 v29, v36, v37
	v_lshl_add_u64 v[30:31], v[30:31], 0, v[192:193]
	global_store_dwordx4 v[30:31], v[26:29], off
	s_waitcnt vmcnt(10)
	s_nop 0
	v_lshlrev_b32_e32 v26, 16, v82
	v_and_b32_e32 v27, 0xffff0000, v82
	s_waitcnt vmcnt(9)
	v_lshlrev_b32_e32 v28, 16, v86
	v_and_b32_e32 v29, 0xffff0000, v86
	v_pk_fma_f32 v[22:23], v[22:23], v[26:27], v[28:29]
	v_lshlrev_b32_e32 v26, 16, v83
	v_and_b32_e32 v27, 0xffff0000, v83
	v_lshlrev_b32_e32 v28, 16, v87
	v_and_b32_e32 v29, 0xffff0000, v87
	v_pk_fma_f32 v[24:25], v[24:25], v[26:27], v[28:29]
	v_lshlrev_b32_e32 v26, 16, v84
	v_and_b32_e32 v27, 0xffff0000, v84
	v_lshlrev_b32_e32 v28, 16, v88
	v_and_b32_e32 v29, 0xffff0000, v88
	v_pk_fma_f32 v[26:27], v[18:19], v[26:27], v[28:29]
	v_lshlrev_b32_e32 v18, 16, v85
	v_and_b32_e32 v19, 0xffff0000, v85
	v_lshlrev_b32_e32 v28, 16, v89
	v_and_b32_e32 v29, 0xffff0000, v89
	v_pk_fma_f32 v[28:29], v[20:21], v[18:19], v[28:29]
	v_cvt_pk_bf16_f32 v18, v22, v23
	v_cvt_pk_bf16_f32 v19, v24, v25
	v_cvt_pk_bf16_f32 v20, v26, v27
	v_cvt_pk_bf16_f32 v21, v28, v29
	global_store_dwordx4 v[30:31], v[18:21], off offset:256
	s_waitcnt vmcnt(9)
	s_nop 0
	v_lshlrev_b32_e32 v18, 16, v78
	v_and_b32_e32 v19, 0xffff0000, v78
	s_waitcnt vmcnt(8)
	v_lshlrev_b32_e32 v20, 16, v74
	v_and_b32_e32 v21, 0xffff0000, v74
	v_pk_fma_f32 v[14:15], v[14:15], v[18:19], v[20:21]
	v_lshlrev_b32_e32 v18, 16, v79
	v_and_b32_e32 v19, 0xffff0000, v79
	v_lshlrev_b32_e32 v20, 16, v75
	v_and_b32_e32 v21, 0xffff0000, v75
	v_pk_fma_f32 v[16:17], v[16:17], v[18:19], v[20:21]
	v_lshlrev_b32_e32 v18, 16, v80
	v_and_b32_e32 v19, 0xffff0000, v80
	v_lshlrev_b32_e32 v20, 16, v76
	v_and_b32_e32 v21, 0xffff0000, v76
	v_pk_fma_f32 v[18:19], v[10:11], v[18:19], v[20:21]
	v_lshlrev_b32_e32 v10, 16, v81
	v_and_b32_e32 v11, 0xffff0000, v81
	v_lshlrev_b32_e32 v20, 16, v77
	v_and_b32_e32 v21, 0xffff0000, v77
	v_pk_fma_f32 v[20:21], v[12:13], v[10:11], v[20:21]
	v_cvt_pk_bf16_f32 v10, v14, v15
	v_lshl_add_u64 v[14:15], s[48:49], 0, v[98:99]
	v_cvt_pk_bf16_f32 v11, v16, v17
	v_cvt_pk_bf16_f32 v12, v18, v19
	v_cvt_pk_bf16_f32 v13, v20, v21
	v_lshl_add_u64 v[14:15], v[14:15], 0, v[192:193]
	global_store_dwordx4 v[14:15], v[10:13], off
	s_waitcnt vmcnt(8)
	s_nop 0
	v_lshlrev_b32_e32 v10, 16, v66
	v_and_b32_e32 v11, 0xffff0000, v66
	s_waitcnt vmcnt(7)
	v_lshlrev_b32_e32 v12, 16, v70
	v_and_b32_e32 v13, 0xffff0000, v70
	v_pk_fma_f32 v[4:5], v[4:5], v[10:11], v[12:13]
	v_lshlrev_b32_e32 v10, 16, v67
	v_and_b32_e32 v11, 0xffff0000, v67
	v_lshlrev_b32_e32 v12, 16, v71
	v_and_b32_e32 v13, 0xffff0000, v71
	v_pk_fma_f32 v[6:7], v[6:7], v[10:11], v[12:13]
	v_lshlrev_b32_e32 v10, 16, v68
	v_and_b32_e32 v11, 0xffff0000, v68
	v_lshlrev_b32_e32 v12, 16, v72
	v_and_b32_e32 v13, 0xffff0000, v72
	v_pk_fma_f32 v[10:11], v[0:1], v[10:11], v[12:13]
	v_lshlrev_b32_e32 v0, 16, v69
	v_and_b32_e32 v1, 0xffff0000, v69
	v_lshlrev_b32_e32 v12, 16, v73
	v_and_b32_e32 v13, 0xffff0000, v73
	v_pk_fma_f32 v[12:13], v[2:3], v[0:1], v[12:13]
	v_cvt_pk_bf16_f32 v0, v4, v5
	v_cvt_pk_bf16_f32 v1, v6, v7
	v_cvt_pk_bf16_f32 v2, v10, v11
	v_cvt_pk_bf16_f32 v3, v12, v13
	global_store_dwordx4 v[14:15], v[0:3], off offset:256
	s_cbranch_vccnz .LBB0_604
	s_andn2_b64 vcc, exec, s[8:9]
	s_cbranch_vccnz .LBB0_603
	s_barrier
	s_branch .LBB0_603

; __device__ __forceinline__ float bflo(unsigned u) { return __uint_as_float(u << 16); }
; __device__ __forceinline__ float bfhi(unsigned u) { return __uint_as_float(u & 0xffff0000u); }
;     __device__ __forceinline__ void operator()(const f32x4 (&acc)[2][2][4][2], const Unit& u, int wr, int wc, int fr_, int fq_) const {
;     ...
;         for (int ai = 0; ai < 2; ++ai) {
;             if (MODE == 4) {
; #pragma unroll
;                 for (int m = 0; m < 4; ++m)
; #pragma unroll
;                     for (int bj = 0; bj < 2; ++bj) {
;                         const size_t rowi = (size_t)(row0 + ai * 128 + m * 16);
;                         gq[ai][m][bj] = *(const u32x4v*)(G + rowi * ldg + col0 + bj * 128);
;                         pq[ai][m][bj] = *(const u32x4v*)(O + rowi * ldc + col0 + bj * 128);
;                     }
;             }
;     ...
;                     } else if (MODE == 3 || MODE == 4) {
;                         const u32x4v gg = gq[ai][m][bj];
;                         v0[0] *= bflo(gg[0]); v0[1] *= bfhi(gg[0]); v0[2] *= bflo(gg[1]); v0[3] *= bfhi(gg[1]);
;                         v1[0] *= bflo(gg[2]); v1[1] *= bfhi(gg[2]); v1[2] *= bflo(gg[3]); v1[3] *= bfhi(gg[3]);
;                         if (MODE == 4) {
;                             const u32x4v pp = pq[ai][m][bj];
;                             v0[0] += bflo(pp[0]); v0[1] += bfhi(pp[0]); v0[2] += bflo(pp[1]); v0[3] += bfhi(pp[1]);
;                             v1[0] += bflo(pp[2]); v1[1] += bfhi(pp[2]); v1[2] += bflo(pp[3]); v1[3] += bfhi(pp[3]);
;                         }
.LBB0_631:
	s_lshl_b32 s13, s36, 8
	v_mbcnt_lo_u32_b32 v90, -1, 0
	v_mbcnt_hi_u32_b32 v90, -1, v90
	s_add_i32 s13, s13, s40
	v_and_or_b32 v194, v90, 15, s13
	v_ashrrev_i32_e32 v90, 1, v90
	s_lshl_b32 s13, s18, 8
	v_and_b32_e32 v90, -8, v90
	s_or_b32 s13, s13, s44
	v_add_u32_e32 v90, s13, v90
	v_ashrrev_i32_e32 v91, 31, v90
	v_readlane_b32 s34, v252, 40
	v_lshlrev_b64 v[192:193], 1, v[90:91]
	v_readlane_b32 s35, v252, 41
	v_readlane_b32 s36, v252, 0
	v_readlane_b32 s37, v252, 1
	v_lshl_add_u64 v[196:197], s[34:35], 0, v[192:193]
	v_ashrrev_i32_e32 v195, 31, v194
	s_movk_i32 s13, 0x1800
	v_lshl_add_u64 v[198:199], s[36:37], 0, v[192:193]
	v_mad_i64_i32 v[90:91], s[34:35], v194, s13, v[196:197]
	v_lshlrev_b64 v[206:207], 11, v[194:195]
	v_lshl_add_u64 v[92:93], v[198:199], 0, v[206:207]
	global_load_dwordx4 v[210:213], v[90:91], off
	global_load_dwordx4 v[214:217], v[92:93], off
	global_load_dwordx4 v[166:169], v[90:91], off offset:256
	global_load_dwordx4 v[162:165], v[92:93], off offset:256
	v_or_b32_e32 v90, 16, v194
	v_ashrrev_i32_e32 v91, 31, v90
	v_mad_i64_i32 v[92:93], s[34:35], v90, s13, v[196:197]
	v_lshlrev_b64 v[204:205], 11, v[90:91]
	v_lshl_add_u64 v[90:91], v[198:199], 0, v[204:205]
	global_load_dwordx4 v[158:161], v[92:93], off
	global_load_dwordx4 v[154:157], v[90:91], off
	global_load_dwordx4 v[150:153], v[92:93], off offset:256
	global_load_dwordx4 v[146:149], v[90:91], off offset:256
	v_or_b32_e32 v90, 32, v194
	v_ashrrev_i32_e32 v91, 31, v90
	v_mad_i64_i32 v[92:93], s[34:35], v90, s13, v[196:197]
	v_lshlrev_b64 v[202:203], 11, v[90:91]
	v_lshl_add_u64 v[90:91], v[198:199], 0, v[202:203]
	global_load_dwordx4 v[142:145], v[92:93], off
	global_load_dwordx4 v[138:141], v[90:91], off
	global_load_dwordx4 v[126:129], v[92:93], off offset:256
	global_load_dwordx4 v[122:125], v[90:91], off offset:256
	v_or_b32_e32 v90, 48, v194
	v_ashrrev_i32_e32 v91, 31, v90
	v_lshlrev_b64 v[200:201], 11, v[90:91]
	v_mad_i64_i32 v[92:93], s[34:35], v90, s13, v[196:197]
	v_lshl_add_u64 v[90:91], v[198:199], 0, v[200:201]
	global_load_dwordx4 v[110:113], v[92:93], off
	global_load_dwordx4 v[106:109], v[90:91], off
	global_load_dwordx4 v[94:97], v[92:93], off offset:256
	s_nop 0
	global_load_dwordx4 v[90:93], v[90:91], off offset:256
	s_nop 0
	s_nop 0
	s_nop 0
	s_nop 0
	s_nop 0
	s_nop 0
	s_nop 0
	s_nop 0
	s_nop 0
	s_nop 0
	s_nop 0
	s_nop 0
	s_nop 0
	s_nop 0
	s_nop 0
	s_nop 0
	s_nop 0
	s_nop 0
	s_nop 0
	s_nop 0
	s_nop 0
	s_nop 0
	s_nop 0
	s_nop 0
	s_nop 0
	s_nop 0
	s_nop 0
	s_nop 0
	s_nop 0
	s_nop 0
	s_nop 0
	s_nop 0
	s_nop 0
	s_nop 0
	s_nop 0
	s_nop 0
	s_nop 0
	s_nop 0
	s_nop 0
	s_nop 0
	s_nop 0
	s_nop 0
	s_nop 0
	s_nop 0
	s_nop 0
	s_nop 0
	s_nop 0
	s_nop 0
	s_nop 0
	s_nop 0
	s_nop 0
	s_nop 0
	s_nop 0
	s_nop 0
	s_nop 0
	s_waitcnt vmcnt(0)
	v_lshlrev_b32_e32 v208, 16, v210
	v_and_b32_e32 v209, 0xffff0000, v210
	v_lshlrev_b32_e32 v220, 16, v214
	v_and_b32_e32 v221, 0xffff0000, v214
	v_pk_fma_f32 v[182:183], v[182:183], v[208:209], v[220:221]
	v_lshlrev_b32_e32 v208, 16, v211
	v_and_b32_e32 v209, 0xffff0000, v211
	v_lshlrev_b32_e32 v210, 16, v215
	v_and_b32_e32 v211, 0xffff0000, v215
	v_pk_fma_f32 v[184:185], v[184:185], v[208:209], v[210:211]
	v_lshlrev_b32_e32 v208, 16, v212
	v_and_b32_e32 v209, 0xffff0000, v212
	v_lshlrev_b32_e32 v210, 16, v216
	v_and_b32_e32 v211, 0xffff0000, v216
	v_pk_fma_f32 v[178:179], v[178:179], v[208:209], v[210:211]
	v_lshlrev_b32_e32 v208, 16, v213
	v_and_b32_e32 v209, 0xffff0000, v213
	v_lshlrev_b32_e32 v210, 16, v217
	v_and_b32_e32 v211, 0xffff0000, v217
	v_pk_fma_f32 v[208:209], v[180:181], v[208:209], v[210:211]
	v_cvt_pk_bf16_f32 v180, v182, v183
	v_cvt_pk_bf16_f32 v182, v178, v179
	v_lshl_add_u64 v[178:179], s[36:37], 0, v[206:207]
	v_cvt_pk_bf16_f32 v181, v184, v185
	v_cvt_pk_bf16_f32 v183, v208, v209
	v_lshl_add_u64 v[178:179], v[178:179], 0, v[192:193]
	global_store_dwordx4 v[178:179], v[180:183], off
	s_nop 0
	s_nop 0
	v_lshlrev_b32_e32 v180, 16, v166
	v_and_b32_e32 v181, 0xffff0000, v166
	v_lshlrev_b32_e32 v182, 16, v162
	v_and_b32_e32 v183, 0xffff0000, v162
	v_lshlrev_b32_e32 v166, 16, v167
	v_and_b32_e32 v167, 0xffff0000, v167
	v_lshlrev_b32_e32 v162, 16, v163
	v_and_b32_e32 v163, 0xffff0000, v163
	v_pk_fma_f32 v[166:167], v[176:177], v[166:167], v[162:163]
	v_lshlrev_b32_e32 v162, 16, v168
	v_and_b32_e32 v163, 0xffff0000, v168
	v_lshlrev_b32_e32 v176, 16, v164
	v_and_b32_e32 v177, 0xffff0000, v164
	v_pk_fma_f32 v[170:171], v[170:171], v[162:163], v[176:177]
	v_lshlrev_b32_e32 v162, 16, v169
	v_and_b32_e32 v163, 0xffff0000, v169
	v_lshlrev_b32_e32 v164, 16, v165
	v_and_b32_e32 v165, 0xffff0000, v165
	v_pk_fma_f32 v[174:175], v[174:175], v[180:181], v[182:183]
	v_pk_fma_f32 v[168:169], v[172:173], v[162:163], v[164:165]
	v_cvt_pk_bf16_f32 v162, v174, v175
	v_cvt_pk_bf16_f32 v163, v166, v167
	v_cvt_pk_bf16_f32 v164, v170, v171
	v_cvt_pk_bf16_f32 v165, v168, v169
	global_store_dwordx4 v[178:179], v[162:165], off offset:256
	s_nop 0
	s_nop 0
	v_lshlrev_b32_e32 v162, 16, v158
	v_and_b32_e32 v163, 0xffff0000, v158
	v_lshlrev_b32_e32 v164, 16, v154
	v_and_b32_e32 v165, 0xffff0000, v154
	v_lshlrev_b32_e32 v158, 16, v159
	v_and_b32_e32 v159, 0xffff0000, v159
	v_lshlrev_b32_e32 v154, 16, v155
	v_and_b32_e32 v155, 0xffff0000, v155
	v_pk_fma_f32 v[136:137], v[136:137], v[158:159], v[154:155]
	v_lshlrev_b32_e32 v154, 16, v160
	v_and_b32_e32 v155, 0xffff0000, v160
	v_lshlrev_b32_e32 v158, 16, v156
	v_and_b32_e32 v159, 0xffff0000, v156
	v_pk_fma_f32 v[134:135], v[134:135], v[162:163], v[164:165]
	v_pk_fma_f32 v[154:155], v[130:131], v[154:155], v[158:159]
	v_lshlrev_b32_e32 v130, 16, v161
	v_and_b32_e32 v131, 0xffff0000, v161
; __device__ __forceinline__ unsigned cvt_pk_bf16(float lo, float hi) { const f32x2c v = {lo, hi}; const bf16x2c b = __builtin_convertvector(v, bf16x2c); return __builtin_bit_cast(unsigned, b); }
; __device__ __forceinline__ float bflo(unsigned u) { return __uint_as_float(u << 16); }
; __device__ __forceinline__ float bfhi(unsigned u) { return __uint_as_float(u & 0xffff0000u); }
;     __device__ __forceinline__ void operator()(const f32x4 (&acc)[2][2][4][2], const Unit& u, int wr, int wc, int fr_, int fq_) const {
;     ...
;                     } else if (MODE == 3 || MODE == 4) {
;                         const u32x4v gg = gq[ai][m][bj];
;                         v0[0] *= bflo(gg[0]); v0[1] *= bfhi(gg[0]); v0[2] *= bflo(gg[1]); v0[3] *= bfhi(gg[1]);
;                         v1[0] *= bflo(gg[2]); v1[1] *= bfhi(gg[2]); v1[2] *= bflo(gg[3]); v1[3] *= bfhi(gg[3]);
;                         if (MODE == 4) {
;                             const u32x4v pp = pq[ai][m][bj];
;                             v0[0] += bflo(pp[0]); v0[1] += bfhi(pp[0]); v0[2] += bflo(pp[1]); v0[3] += bfhi(pp[1]);
;                             v1[0] += bflo(pp[2]); v1[1] += bfhi(pp[2]); v1[2] += bflo(pp[3]); v1[3] += bfhi(pp[3]);
;                         }
;                     }
;                     u32x4v o; o[0] = cvt_pk_bf16(v0[0], v0[1]); o[1] = cvt_pk_bf16(v0[2], v0[3]); o[2] = cvt_pk_bf16(v1[0], v1[1]); o[3] = cvt_pk_bf16(v1[2], v1[3]);
;                     if (MODE == 1) __builtin_nontemporal_store(o, (u32x4v*)(O + ro + bj * 128));
;                     else *(u32x4v*)(O + ro + bj * 128) = o;
	v_lshlrev_b32_e32 v156, 16, v157
	v_and_b32_e32 v157, 0xffff0000, v157
	v_pk_fma_f32 v[156:157], v[132:133], v[130:131], v[156:157]
	v_cvt_pk_bf16_f32 v130, v134, v135
	v_lshl_add_u64 v[134:135], s[36:37], 0, v[204:205]
	v_cvt_pk_bf16_f32 v131, v136, v137
	v_cvt_pk_bf16_f32 v132, v154, v155
	v_cvt_pk_bf16_f32 v133, v156, v157
	v_lshl_add_u64 v[134:135], v[134:135], 0, v[192:193]
	global_store_dwordx4 v[134:135], v[130:133], off
	s_nop 0
	s_nop 0
	v_lshlrev_b32_e32 v130, 16, v150
	v_and_b32_e32 v131, 0xffff0000, v150
	v_lshlrev_b32_e32 v132, 16, v146
	v_and_b32_e32 v133, 0xffff0000, v146
	v_pk_fma_f32 v[118:119], v[118:119], v[130:131], v[132:133]
	v_lshlrev_b32_e32 v130, 16, v151
	v_and_b32_e32 v131, 0xffff0000, v151
	v_lshlrev_b32_e32 v132, 16, v147
	v_and_b32_e32 v133, 0xffff0000, v147
	v_pk_fma_f32 v[120:121], v[120:121], v[130:131], v[132:133]
	v_lshlrev_b32_e32 v130, 16, v152
	v_and_b32_e32 v131, 0xffff0000, v152
	v_lshlrev_b32_e32 v132, 16, v148
	v_and_b32_e32 v133, 0xffff0000, v148
	v_pk_fma_f32 v[130:131], v[114:115], v[130:131], v[132:133]
	v_lshlrev_b32_e32 v114, 16, v153
	v_and_b32_e32 v115, 0xffff0000, v153
	v_lshlrev_b32_e32 v132, 16, v149
	v_and_b32_e32 v133, 0xffff0000, v149
	v_pk_fma_f32 v[132:133], v[116:117], v[114:115], v[132:133]
	v_cvt_pk_bf16_f32 v114, v118, v119
	v_cvt_pk_bf16_f32 v115, v120, v121
	v_cvt_pk_bf16_f32 v116, v130, v131
	v_cvt_pk_bf16_f32 v117, v132, v133
	global_store_dwordx4 v[134:135], v[114:117], off offset:256
	s_nop 0
	s_nop 0
	v_lshlrev_b32_e32 v114, 16, v142
	v_and_b32_e32 v115, 0xffff0000, v142
	v_lshlrev_b32_e32 v116, 16, v138
	v_and_b32_e32 v117, 0xffff0000, v138
	v_pk_fma_f32 v[102:103], v[102:103], v[114:115], v[116:117]
	v_lshlrev_b32_e32 v114, 16, v143
	v_and_b32_e32 v115, 0xffff0000, v143
	v_lshlrev_b32_e32 v116, 16, v139
	v_and_b32_e32 v117, 0xffff0000, v139
	v_pk_fma_f32 v[104:105], v[104:105], v[114:115], v[116:117]
	v_lshlrev_b32_e32 v114, 16, v144
	v_and_b32_e32 v115, 0xffff0000, v144
	v_lshlrev_b32_e32 v116, 16, v140
	v_and_b32_e32 v117, 0xffff0000, v140
	v_pk_fma_f32 v[114:115], v[98:99], v[114:115], v[116:117]
	v_lshlrev_b32_e32 v98, 16, v145
	v_and_b32_e32 v99, 0xffff0000, v145
	v_lshlrev_b32_e32 v116, 16, v141
	v_and_b32_e32 v117, 0xffff0000, v141
	v_pk_fma_f32 v[116:117], v[100:101], v[98:99], v[116:117]
	v_cvt_pk_bf16_f32 v98, v102, v103
	v_lshl_add_u64 v[102:103], s[36:37], 0, v[202:203]
	v_cvt_pk_bf16_f32 v99, v104, v105
	v_cvt_pk_bf16_f32 v100, v114, v115
	v_cvt_pk_bf16_f32 v101, v116, v117
	v_lshl_add_u64 v[102:103], v[102:103], 0, v[192:193]
	global_store_dwordx4 v[102:103], v[98:101], off
	s_nop 0
	v_readlane_b32 s38, v252, 2
	v_lshlrev_b32_e32 v98, 16, v126
	v_and_b32_e32 v99, 0xffff0000, v126
	v_lshlrev_b32_e32 v100, 16, v122
	v_and_b32_e32 v101, 0xffff0000, v122
	v_pk_fma_f32 v[86:87], v[86:87], v[98:99], v[100:101]
	v_lshlrev_b32_e32 v98, 16, v127
	v_and_b32_e32 v99, 0xffff0000, v127
	v_lshlrev_b32_e32 v100, 16, v123
	v_and_b32_e32 v101, 0xffff0000, v123
	v_pk_fma_f32 v[88:89], v[88:89], v[98:99], v[100:101]
	v_lshlrev_b32_e32 v98, 16, v128
	v_and_b32_e32 v99, 0xffff0000, v128
	v_lshlrev_b32_e32 v100, 16, v124
	v_and_b32_e32 v101, 0xffff0000, v124
	v_pk_fma_f32 v[98:99], v[82:83], v[98:99], v[100:101]
	v_lshlrev_b32_e32 v82, 16, v129
	v_and_b32_e32 v83, 0xffff0000, v129
	v_lshlrev_b32_e32 v100, 16, v125
	v_and_b32_e32 v101, 0xffff0000, v125
	v_pk_fma_f32 v[100:101], v[84:85], v[82:83], v[100:101]
	v_cvt_pk_bf16_f32 v82, v86, v87
	v_cvt_pk_bf16_f32 v83, v88, v89
	v_cvt_pk_bf16_f32 v84, v98, v99
	v_cvt_pk_bf16_f32 v85, v100, v101
	global_store_dwordx4 v[102:103], v[82:85], off offset:256
	v_readlane_b32 s39, v252, 3
	v_readlane_b32 s56, v254, 27
	v_lshlrev_b32_e32 v82, 16, v110
	v_and_b32_e32 v83, 0xffff0000, v110
	v_lshlrev_b32_e32 v84, 16, v106
	v_and_b32_e32 v85, 0xffff0000, v106
	v_pk_fma_f32 v[78:79], v[78:79], v[82:83], v[84:85]
	v_lshlrev_b32_e32 v82, 16, v111
	v_and_b32_e32 v83, 0xffff0000, v111
	v_lshlrev_b32_e32 v84, 16, v107
	v_and_b32_e32 v85, 0xffff0000, v107
	v_pk_fma_f32 v[80:81], v[80:81], v[82:83], v[84:85]
	v_lshlrev_b32_e32 v82, 16, v112
	v_and_b32_e32 v83, 0xffff0000, v112
	v_lshlrev_b32_e32 v84, 16, v108
	v_and_b32_e32 v85, 0xffff0000, v108
	v_pk_fma_f32 v[82:83], v[74:75], v[82:83], v[84:85]
	v_lshlrev_b32_e32 v74, 16, v113
	v_and_b32_e32 v75, 0xffff0000, v113
	v_lshlrev_b32_e32 v84, 16, v109
	v_and_b32_e32 v85, 0xffff0000, v109
	v_pk_fma_f32 v[84:85], v[76:77], v[74:75], v[84:85]
	v_cvt_pk_bf16_f32 v74, v78, v79
	v_lshl_add_u64 v[78:79], s[36:37], 0, v[200:201]
	v_cvt_pk_bf16_f32 v75, v80, v81
	v_cvt_pk_bf16_f32 v76, v82, v83
	v_cvt_pk_bf16_f32 v77, v84, v85
	v_lshl_add_u64 v[78:79], v[78:79], 0, v[192:193]
	global_store_dwordx4 v[78:79], v[74:77], off
	s_andn2_b64 vcc, exec, s[4:5]
	v_readlane_b32 s57, v254, 28
	v_lshlrev_b32_e32 v74, 16, v94
	v_and_b32_e32 v75, 0xffff0000, v94
	v_lshlrev_b32_e32 v76, 16, v90
	v_and_b32_e32 v77, 0xffff0000, v90
	v_pk_fma_f32 v[70:71], v[70:71], v[74:75], v[76:77]
	v_lshlrev_b32_e32 v74, 16, v95
	v_and_b32_e32 v75, 0xffff0000, v95
	v_lshlrev_b32_e32 v76, 16, v91
	v_and_b32_e32 v77, 0xffff0000, v91
	v_pk_fma_f32 v[72:73], v[72:73], v[74:75], v[76:77]
	v_lshlrev_b32_e32 v74, 16, v96
	v_and_b32_e32 v75, 0xffff0000, v96
	v_lshlrev_b32_e32 v76, 16, v92
	v_and_b32_e32 v77, 0xffff0000, v92
	v_pk_fma_f32 v[74:75], v[66:67], v[74:75], v[76:77]
	v_lshlrev_b32_e32 v66, 16, v97
	v_and_b32_e32 v67, 0xffff0000, v97
	v_lshlrev_b32_e32 v76, 16, v93
	v_and_b32_e32 v77, 0xffff0000, v93
	v_pk_fma_f32 v[76:77], v[68:69], v[66:67], v[76:77]
	v_cvt_pk_bf16_f32 v66, v70, v71
	v_cvt_pk_bf16_f32 v67, v72, v73
	v_cvt_pk_bf16_f32 v68, v74, v75
;     __device__ __forceinline__ void operator()(const f32x4 (&acc)[2][2][4][2], const Unit& u, int wr, int wc, int fr_, int fq_) const {
;     ...
;         for (int ai = 0; ai < 2; ++ai) {
;             if (MODE == 4) {
; #pragma unroll
;                 for (int m = 0; m < 4; ++m)
; #pragma unroll
;                     for (int bj = 0; bj < 2; ++bj) {
;                         const size_t rowi = (size_t)(row0 + ai * 128 + m * 16);
;                         gq[ai][m][bj] = *(const u32x4v*)(G + rowi * ldg + col0 + bj * 128);
;                         pq[ai][m][bj] = *(const u32x4v*)(O + rowi * ldc + col0 + bj * 128);
;                     }
;             }
; #pragma unroll
;             for (int m = 0; m < 4; ++m) {
;                 const size_t ro = (size_t)(row0 + ai * 128 + m * 16) * ldc + col0;
; #pragma unroll
;                 for (int bj = 0; bj < 2; ++bj) {
;                     f32x4 v0 = acc[ai][bj][m][0] + bv[bj][0], v1 = acc[ai][bj][m][1] + bv[bj][1];
;                     if (MODE == 1) {
; #pragma unroll
;                         for (int j = 0; j < 4; ++j) { float a = fmaxf(v0[j], 0.f), b = fmaxf(v1[j], 0.f); v0[j] = a * a; v1[j] = b * b; }
;                     } else if (MODE == 2) {
; #pragma unroll
;                         for (int j = 0; j < 4; ++j) { v0[j] = sigmoidf_(v0[j]); v1[j] = sigmoidf_(v1[j]); }
;                     } else if (MODE == 5) {
;                         const u32x4v pp = pq[ai][m][bj];
;                         v0[0] += DN_ALPHA * bflo(pp[0]); v0[1] += DN_ALPHA * bfhi(pp[0]); v0[2] += DN_ALPHA * bflo(pp[1]); v0[3] += DN_ALPHA * bfhi(pp[1]);
;                         v1[0] += DN_ALPHA * bflo(pp[2]); v1[1] += DN_ALPHA * bfhi(pp[2]); v1[2] += DN_ALPHA * bflo(pp[3]); v1[3] += DN_ALPHA * bfhi(pp[3]);
;                     } else if (MODE == 3 || MODE == 4) {
;                         const u32x4v gg = gq[ai][m][bj];
;                         v0[0] *= bflo(gg[0]); v0[1] *= bfhi(gg[0]); v0[2] *= bflo(gg[1]); v0[3] *= bfhi(gg[1]);
;                         v1[0] *= bflo(gg[2]); v1[1] *= bfhi(gg[2]); v1[2] *= bflo(gg[3]); v1[3] *= bfhi(gg[3]);
;                         if (MODE == 4) {
;                             const u32x4v pp = pq[ai][m][bj];
;                             v0[0] += bflo(pp[0]); v0[1] += bfhi(pp[0]); v0[2] += bflo(pp[1]); v0[3] += bfhi(pp[1]);
	v_cvt_pk_bf16_f32 v69, v76, v77
	global_store_dwordx4 v[78:79], v[66:69], off offset:256
	s_mov_b64 s[38:39], 0x800
	s_nop 0
	v_add_u32_e32 v66, 0x80, v194
	v_ashrrev_i32_e32 v67, 31, v66
	v_mad_i64_i32 v[68:69], s[34:35], v66, s13, v[196:197]
	v_lshlrev_b64 v[134:135], 11, v[66:67]
	v_lshl_add_u64 v[66:67], v[198:199], 0, v[134:135]
	global_load_dwordx4 v[102:105], v[68:69], off
	global_load_dwordx4 v[106:109], v[66:67], off
	global_load_dwordx4 v[110:113], v[68:69], off offset:256
	global_load_dwordx4 v[114:117], v[66:67], off offset:256
	v_add_u32_e32 v66, 0x90, v194
	v_ashrrev_i32_e32 v67, 31, v66
	v_mad_i64_i32 v[68:69], s[34:35], v66, s13, v[196:197]
	v_lshlrev_b64 v[136:137], 11, v[66:67]
	v_lshl_add_u64 v[66:67], v[198:199], 0, v[136:137]
	global_load_dwordx4 v[118:121], v[68:69], off
	global_load_dwordx4 v[122:125], v[66:67], off
	global_load_dwordx4 v[126:129], v[68:69], off offset:256
	global_load_dwordx4 v[130:133], v[66:67], off offset:256
	v_add_u32_e32 v66, 0xa0, v194
	v_ashrrev_i32_e32 v67, 31, v66
	v_mad_i64_i32 v[68:69], s[34:35], v66, s13, v[196:197]
	v_lshlrev_b64 v[100:101], 11, v[66:67]
	v_lshl_add_u64 v[66:67], v[198:199], 0, v[100:101]
	global_load_dwordx4 v[94:97], v[68:69], off
	global_load_dwordx4 v[90:93], v[66:67], off
	global_load_dwordx4 v[82:85], v[68:69], off offset:256
	global_load_dwordx4 v[86:89], v[66:67], off offset:256
	v_add_u32_e32 v66, 0xb0, v194
	v_ashrrev_i32_e32 v67, 31, v66
	v_lshlrev_b64 v[98:99], 11, v[66:67]
	v_mad_i64_i32 v[68:69], s[34:35], v66, s13, v[196:197]
	v_lshl_add_u64 v[70:71], v[198:199], 0, v[98:99]
	global_load_dwordx4 v[78:81], v[68:69], off
	global_load_dwordx4 v[74:77], v[70:71], off
	s_nop 0
	global_load_dwordx4 v[66:69], v[68:69], off offset:256
	s_nop 0
	global_load_dwordx4 v[70:73], v[70:71], off offset:256
	s_mov_b64 s[34:35], -1
	s_waitcnt vmcnt(15)
	v_lshlrev_b32_e32 v138, 16, v102
	v_and_b32_e32 v139, 0xffff0000, v102
	s_waitcnt vmcnt(14)
	v_lshlrev_b32_e32 v140, 16, v106
	v_and_b32_e32 v141, 0xffff0000, v106
	v_lshlrev_b32_e32 v102, 16, v103
	v_and_b32_e32 v103, 0xffff0000, v103
	v_lshlrev_b32_e32 v106, 16, v107
	v_and_b32_e32 v107, 0xffff0000, v107
	v_pk_fma_f32 v[64:65], v[64:65], v[102:103], v[106:107]
	v_lshlrev_b32_e32 v102, 16, v104
	v_and_b32_e32 v103, 0xffff0000, v104
	v_lshlrev_b32_e32 v106, 16, v108
	v_and_b32_e32 v107, 0xffff0000, v108
	v_pk_fma_f32 v[62:63], v[62:63], v[138:139], v[140:141]
	v_pk_fma_f32 v[102:103], v[58:59], v[102:103], v[106:107]
	v_lshlrev_b32_e32 v58, 16, v105
	v_and_b32_e32 v59, 0xffff0000, v105
	v_lshlrev_b32_e32 v104, 16, v109
	v_and_b32_e32 v105, 0xffff0000, v109
	v_pk_fma_f32 v[104:105], v[60:61], v[58:59], v[104:105]
	v_cvt_pk_bf16_f32 v58, v62, v63
	v_lshl_add_u64 v[62:63], s[36:37], 0, v[134:135]
	v_cvt_pk_bf16_f32 v59, v64, v65
	v_cvt_pk_bf16_f32 v60, v102, v103
	v_cvt_pk_bf16_f32 v61, v104, v105
	v_lshl_add_u64 v[62:63], v[62:63], 0, v[192:193]
	global_store_dwordx4 v[62:63], v[58:61], off
	s_waitcnt vmcnt(14)
	s_nop 0
	v_lshlrev_b32_e32 v58, 16, v110
	v_and_b32_e32 v59, 0xffff0000, v110
	s_waitcnt vmcnt(13)
	v_lshlrev_b32_e32 v60, 16, v114
	v_and_b32_e32 v61, 0xffff0000, v114
	v_pk_fma_f32 v[54:55], v[54:55], v[58:59], v[60:61]
	v_lshlrev_b32_e32 v58, 16, v111
	v_and_b32_e32 v59, 0xffff0000, v111
	v_lshlrev_b32_e32 v60, 16, v115
	v_and_b32_e32 v61, 0xffff0000, v115
	v_pk_fma_f32 v[56:57], v[56:57], v[58:59], v[60:61]
	v_lshlrev_b32_e32 v58, 16, v112
	v_and_b32_e32 v59, 0xffff0000, v112
	v_lshlrev_b32_e32 v60, 16, v116
	v_and_b32_e32 v61, 0xffff0000, v116
	v_pk_fma_f32 v[58:59], v[50:51], v[58:59], v[60:61]
	v_lshlrev_b32_e32 v50, 16, v113
	v_and_b32_e32 v51, 0xffff0000, v113
	v_lshlrev_b32_e32 v60, 16, v117
	v_and_b32_e32 v61, 0xffff0000, v117
	v_pk_fma_f32 v[60:61], v[52:53], v[50:51], v[60:61]
	v_cvt_pk_bf16_f32 v50, v54, v55
	v_cvt_pk_bf16_f32 v51, v56, v57
	v_cvt_pk_bf16_f32 v52, v58, v59
	v_cvt_pk_bf16_f32 v53, v60, v61
	global_store_dwordx4 v[62:63], v[50:53], off offset:256
	s_waitcnt vmcnt(13)
	s_nop 0
	v_lshlrev_b32_e32 v50, 16, v118
	v_and_b32_e32 v51, 0xffff0000, v118
	s_waitcnt vmcnt(12)
	v_lshlrev_b32_e32 v52, 16, v122
	v_and_b32_e32 v53, 0xffff0000, v122
	v_pk_fma_f32 v[46:47], v[46:47], v[50:51], v[52:53]
	v_lshlrev_b32_e32 v50, 16, v119
	v_and_b32_e32 v51, 0xffff0000, v119
	v_lshlrev_b32_e32 v52, 16, v123
	v_and_b32_e32 v53, 0xffff0000, v123
	v_pk_fma_f32 v[48:49], v[48:49], v[50:51], v[52:53]
	v_lshlrev_b32_e32 v50, 16, v120
	v_and_b32_e32 v51, 0xffff0000, v120
	v_lshlrev_b32_e32 v52, 16, v124
	v_and_b32_e32 v53, 0xffff0000, v124
	v_pk_fma_f32 v[50:51], v[42:43], v[50:51], v[52:53]
	v_lshlrev_b32_e32 v42, 16, v121
	v_and_b32_e32 v43, 0xffff0000, v121
	v_lshlrev_b32_e32 v52, 16, v125
	v_and_b32_e32 v53, 0xffff0000, v125
	v_pk_fma_f32 v[52:53], v[44:45], v[42:43], v[52:53]
	v_cvt_pk_bf16_f32 v42, v46, v47
	v_lshl_add_u64 v[46:47], s[36:37], 0, v[136:137]
	v_cvt_pk_bf16_f32 v43, v48, v49
	v_cvt_pk_bf16_f32 v44, v50, v51
	v_cvt_pk_bf16_f32 v45, v52, v53
	v_lshl_add_u64 v[46:47], v[46:47], 0, v[192:193]
	global_store_dwordx4 v[46:47], v[42:45], off
	s_waitcnt vmcnt(12)
	s_nop 0
	v_lshlrev_b32_e32 v42, 16, v126
	v_and_b32_e32 v43, 0xffff0000, v126
	s_waitcnt vmcnt(11)
;     __device__ __forceinline__ void operator()(const f32x4 (&acc)[2][2][4][2], const Unit& u, int wr, int wc, int fr_, int fq_) const {
;     ...
; #pragma unroll
;             for (int m = 0; m < 4; ++m) {
;                 const size_t ro = (size_t)(row0 + ai * 128 + m * 16) * ldc + col0;
; #pragma unroll
;                 for (int bj = 0; bj < 2; ++bj) {
;                     f32x4 v0 = acc[ai][bj][m][0] + bv[bj][0], v1 = acc[ai][bj][m][1] + bv[bj][1];
;                     if (MODE == 1) {
; #pragma unroll
;                         for (int j = 0; j < 4; ++j) { float a = fmaxf(v0[j], 0.f), b = fmaxf(v1[j], 0.f); v0[j] = a * a; v1[j] = b * b; }
;                     } else if (MODE == 2) {
; #pragma unroll
;                         for (int j = 0; j < 4; ++j) { v0[j] = sigmoidf_(v0[j]); v1[j] = sigmoidf_(v1[j]); }
;                     } else if (MODE == 5) {
;                         const u32x4v pp = pq[ai][m][bj];
;                         v0[0] += DN_ALPHA * bflo(pp[0]); v0[1] += DN_ALPHA * bfhi(pp[0]); v0[2] += DN_ALPHA * bflo(pp[1]); v0[3] += DN_ALPHA * bfhi(pp[1]);
;                         v1[0] += DN_ALPHA * bflo(pp[2]); v1[1] += DN_ALPHA * bfhi(pp[2]); v1[2] += DN_ALPHA * bflo(pp[3]); v1[3] += DN_ALPHA * bfhi(pp[3]);
;                     } else if (MODE == 3 || MODE == 4) {
;                         const u32x4v gg = gq[ai][m][bj];
;                         v0[0] *= bflo(gg[0]); v0[1] *= bfhi(gg[0]); v0[2] *= bflo(gg[1]); v0[3] *= bfhi(gg[1]);
;                         v1[0] *= bflo(gg[2]); v1[1] *= bfhi(gg[2]); v1[2] *= bflo(gg[3]); v1[3] *= bfhi(gg[3]);
;                         if (MODE == 4) {
;                             const u32x4v pp = pq[ai][m][bj];
;                             v0[0] += bflo(pp[0]); v0[1] += bfhi(pp[0]); v0[2] += bflo(pp[1]); v0[3] += bfhi(pp[1]);
;                             v1[0] += bflo(pp[2]); v1[1] += bfhi(pp[2]); v1[2] += bflo(pp[3]); v1[3] += bfhi(pp[3]);
;                         }
;                     }
;                     u32x4v o; o[0] = cvt_pk_bf16(v0[0], v0[1]); o[1] = cvt_pk_bf16(v0[2], v0[3]); o[2] = cvt_pk_bf16(v1[0], v1[1]); o[3] = cvt_pk_bf16(v1[2], v1[3]);
;                     if (MODE == 1) __builtin_nontemporal_store(o, (u32x4v*)(O + ro + bj * 128));
;                     else *(u32x4v*)(O + ro + bj * 128) = o;
;                 }
;             }
;         }
;     }
	v_lshlrev_b32_e32 v44, 16, v130
	v_and_b32_e32 v45, 0xffff0000, v130
	v_pk_fma_f32 v[38:39], v[38:39], v[42:43], v[44:45]
	v_lshlrev_b32_e32 v42, 16, v127
	v_and_b32_e32 v43, 0xffff0000, v127
	v_lshlrev_b32_e32 v44, 16, v131
	v_and_b32_e32 v45, 0xffff0000, v131
	v_pk_fma_f32 v[40:41], v[40:41], v[42:43], v[44:45]
	v_lshlrev_b32_e32 v42, 16, v128
	v_and_b32_e32 v43, 0xffff0000, v128
	v_lshlrev_b32_e32 v44, 16, v132
	v_and_b32_e32 v45, 0xffff0000, v132
	v_pk_fma_f32 v[42:43], v[34:35], v[42:43], v[44:45]
	v_lshlrev_b32_e32 v34, 16, v129
	v_and_b32_e32 v35, 0xffff0000, v129
	v_lshlrev_b32_e32 v44, 16, v133
	v_and_b32_e32 v45, 0xffff0000, v133
	v_pk_fma_f32 v[44:45], v[36:37], v[34:35], v[44:45]
	v_cvt_pk_bf16_f32 v34, v38, v39
	v_cvt_pk_bf16_f32 v35, v40, v41
	v_cvt_pk_bf16_f32 v36, v42, v43
	v_cvt_pk_bf16_f32 v37, v44, v45
	global_store_dwordx4 v[46:47], v[34:37], off offset:256
	s_waitcnt vmcnt(11)
	s_nop 0
	v_lshlrev_b32_e32 v34, 16, v94
	v_and_b32_e32 v35, 0xffff0000, v94
	s_waitcnt vmcnt(10)
	v_lshlrev_b32_e32 v36, 16, v90
	v_and_b32_e32 v37, 0xffff0000, v90
	v_pk_fma_f32 v[30:31], v[30:31], v[34:35], v[36:37]
	v_lshlrev_b32_e32 v34, 16, v95
	v_and_b32_e32 v35, 0xffff0000, v95
	v_lshlrev_b32_e32 v36, 16, v91
	v_and_b32_e32 v37, 0xffff0000, v91
	v_pk_fma_f32 v[32:33], v[32:33], v[34:35], v[36:37]
	v_lshlrev_b32_e32 v34, 16, v96
	v_and_b32_e32 v35, 0xffff0000, v96
	v_lshlrev_b32_e32 v36, 16, v92
	v_and_b32_e32 v37, 0xffff0000, v92
	v_pk_fma_f32 v[34:35], v[26:27], v[34:35], v[36:37]
	v_lshlrev_b32_e32 v26, 16, v97
	v_and_b32_e32 v27, 0xffff0000, v97
	v_lshlrev_b32_e32 v36, 16, v93
	v_and_b32_e32 v37, 0xffff0000, v93
	v_pk_fma_f32 v[36:37], v[28:29], v[26:27], v[36:37]
	v_cvt_pk_bf16_f32 v26, v30, v31
	v_lshl_add_u64 v[30:31], s[36:37], 0, v[100:101]
	v_cvt_pk_bf16_f32 v27, v32, v33
	v_cvt_pk_bf16_f32 v28, v34, v35
	v_cvt_pk_bf16_f32 v29, v36, v37
	v_lshl_add_u64 v[30:31], v[30:31], 0, v[192:193]
	global_store_dwordx4 v[30:31], v[26:29], off
	s_waitcnt vmcnt(10)
	s_nop 0
	v_lshlrev_b32_e32 v26, 16, v82
	v_and_b32_e32 v27, 0xffff0000, v82
	s_waitcnt vmcnt(9)
	v_lshlrev_b32_e32 v28, 16, v86
	v_and_b32_e32 v29, 0xffff0000, v86
	v_pk_fma_f32 v[22:23], v[22:23], v[26:27], v[28:29]
	v_lshlrev_b32_e32 v26, 16, v83
	v_and_b32_e32 v27, 0xffff0000, v83
	v_lshlrev_b32_e32 v28, 16, v87
	v_and_b32_e32 v29, 0xffff0000, v87
	v_pk_fma_f32 v[24:25], v[24:25], v[26:27], v[28:29]
	v_lshlrev_b32_e32 v26, 16, v84
	v_and_b32_e32 v27, 0xffff0000, v84
	v_lshlrev_b32_e32 v28, 16, v88
	v_and_b32_e32 v29, 0xffff0000, v88
	v_pk_fma_f32 v[26:27], v[18:19], v[26:27], v[28:29]
	v_lshlrev_b32_e32 v18, 16, v85
	v_and_b32_e32 v19, 0xffff0000, v85
	v_lshlrev_b32_e32 v28, 16, v89
	v_and_b32_e32 v29, 0xffff0000, v89
	v_pk_fma_f32 v[28:29], v[20:21], v[18:19], v[28:29]
	v_cvt_pk_bf16_f32 v18, v22, v23
	v_cvt_pk_bf16_f32 v19, v24, v25
	v_cvt_pk_bf16_f32 v20, v26, v27
	v_cvt_pk_bf16_f32 v21, v28, v29
	global_store_dwordx4 v[30:31], v[18:21], off offset:256
	s_waitcnt vmcnt(9)
	s_nop 0
	v_lshlrev_b32_e32 v18, 16, v78
	v_and_b32_e32 v19, 0xffff0000, v78
	s_waitcnt vmcnt(8)
	v_lshlrev_b32_e32 v20, 16, v74
	v_and_b32_e32 v21, 0xffff0000, v74
	v_pk_fma_f32 v[14:15], v[14:15], v[18:19], v[20:21]
	v_lshlrev_b32_e32 v18, 16, v79
	v_and_b32_e32 v19, 0xffff0000, v79
	v_lshlrev_b32_e32 v20, 16, v75
	v_and_b32_e32 v21, 0xffff0000, v75
	v_pk_fma_f32 v[16:17], v[16:17], v[18:19], v[20:21]
	v_lshlrev_b32_e32 v18, 16, v80
	v_and_b32_e32 v19, 0xffff0000, v80
	v_lshlrev_b32_e32 v20, 16, v76
	v_and_b32_e32 v21, 0xffff0000, v76
	v_pk_fma_f32 v[18:19], v[10:11], v[18:19], v[20:21]
	v_lshlrev_b32_e32 v10, 16, v81
	v_and_b32_e32 v11, 0xffff0000, v81
	v_lshlrev_b32_e32 v20, 16, v77
	v_and_b32_e32 v21, 0xffff0000, v77
	v_pk_fma_f32 v[20:21], v[12:13], v[10:11], v[20:21]
	v_cvt_pk_bf16_f32 v10, v14, v15
	v_lshl_add_u64 v[14:15], s[36:37], 0, v[98:99]
	v_cvt_pk_bf16_f32 v11, v16, v17
	v_cvt_pk_bf16_f32 v12, v18, v19
	v_cvt_pk_bf16_f32 v13, v20, v21
	v_lshl_add_u64 v[14:15], v[14:15], 0, v[192:193]
	global_store_dwordx4 v[14:15], v[10:13], off
	s_waitcnt vmcnt(8)
	s_nop 0
	v_lshlrev_b32_e32 v10, 16, v66
	v_and_b32_e32 v11, 0xffff0000, v66
	s_waitcnt vmcnt(7)
	v_lshlrev_b32_e32 v12, 16, v70
	v_and_b32_e32 v13, 0xffff0000, v70
	v_pk_fma_f32 v[4:5], v[4:5], v[10:11], v[12:13]
	v_lshlrev_b32_e32 v10, 16, v67
	v_and_b32_e32 v11, 0xffff0000, v67
	v_lshlrev_b32_e32 v12, 16, v71
	v_and_b32_e32 v13, 0xffff0000, v71
	v_pk_fma_f32 v[6:7], v[6:7], v[10:11], v[12:13]
	v_lshlrev_b32_e32 v10, 16, v68
	v_and_b32_e32 v11, 0xffff0000, v68
	v_lshlrev_b32_e32 v12, 16, v72
	v_and_b32_e32 v13, 0xffff0000, v72
	v_pk_fma_f32 v[10:11], v[0:1], v[10:11], v[12:13]
	v_lshlrev_b32_e32 v0, 16, v69
	v_and_b32_e32 v1, 0xffff0000, v69
	v_lshlrev_b32_e32 v12, 16, v73
	v_and_b32_e32 v13, 0xffff0000, v73
	v_pk_fma_f32 v[12:13], v[2:3], v[0:1], v[12:13]
	v_cvt_pk_bf16_f32 v0, v4, v5
	v_cvt_pk_bf16_f32 v1, v6, v7
	v_cvt_pk_bf16_f32 v2, v10, v11
	v_cvt_pk_bf16_f32 v3, v12, v13
	global_store_dwordx4 v[14:15], v[0:3], off offset:256
	s_cbranch_vccnz .LBB0_622
	s_andn2_b64 vcc, exec, s[6:7]
	s_cbranch_vccnz .LBB0_621
	s_barrier
	s_branch .LBB0_621

; __device__ __forceinline__ float bflo(unsigned u) { return __uint_as_float(u << 16); }
; __device__ __forceinline__ float bfhi(unsigned u) { return __uint_as_float(u & 0xffff0000u); }
;     __device__ __forceinline__ void operator()(const f32x4 (&acc)[2][2][4][2], const Unit& u, int wr, int wc, int fr_, int fq_) const {
;     ...
;         u32x4v gq[2][4][2], pq[2][4][2];
;         if (MODE == 3 || MODE == 5) {
; #pragma unroll
;             for (int ai = 0; ai < 2; ++ai)
; #pragma unroll
;                 for (int m = 0; m < 4; ++m)
; #pragma unroll
;                     for (int bj = 0; bj < 2; ++bj) {
;                         const size_t rowi = (size_t)(row0 + ai * 128 + m * 16);
;                         if (MODE == 3) gq[ai][m][bj] = *(const u32x4v*)(G + rowi * ldg + col0 + bj * 128);
;                         if (MODE == 5) pq[ai][m][bj] = *(const u32x4v*)(O + rowi * ldc + col0 + bj * 128);
;                     }
;         }
;     ...
;                     } else if (MODE == 5) {
;                         const u32x4v pp = pq[ai][m][bj];
;                         v0[0] += DN_ALPHA * bflo(pp[0]); v0[1] += DN_ALPHA * bfhi(pp[0]); v0[2] += DN_ALPHA * bflo(pp[1]); v0[3] += DN_ALPHA * bfhi(pp[1]);
;                         v1[0] += DN_ALPHA * bflo(pp[2]); v1[1] += DN_ALPHA * bfhi(pp[2]); v1[2] += DN_ALPHA * bflo(pp[3]); v1[3] += DN_ALPHA * bfhi(pp[3]);
.LBB0_711:
	v_mbcnt_lo_u32_b32 v124, -1, 0
	v_mbcnt_hi_u32_b32 v124, -1, v124
	s_lshl_b32 s15, s43, 8
	v_ashrrev_i32_e32 v122, 1, v124
	s_or_b32 s15, s15, s57
	v_and_b32_e32 v122, -8, v122
	v_add_u32_e32 v122, s15, v122
	s_lshl_b32 s15, s42, 8
	s_add_i32 s15, s15, s56
	v_ashrrev_i32_e32 v123, 31, v122
	v_and_or_b32 v124, v124, 15, s15
	v_lshlrev_b64 v[200:201], 1, v[122:123]
	v_ashrrev_i32_e32 v125, 31, v124
	v_lshl_add_u64 v[122:123], s[10:11], 0, v[200:201]
	v_lshlrev_b64 v[206:207], 11, v[124:125]
	v_lshl_add_u64 v[126:127], v[122:123], 0, v[206:207]
	global_load_dwordx4 v[210:213], v[126:127], off
	global_load_dwordx4 v[186:189], v[126:127], off offset:256
	v_or_b32_e32 v126, 16, v124
	v_ashrrev_i32_e32 v127, 31, v126
	v_lshlrev_b64 v[226:227], 11, v[126:127]
	v_lshl_add_u64 v[126:127], v[122:123], 0, v[226:227]
	global_load_dwordx4 v[182:185], v[126:127], off
	global_load_dwordx4 v[178:181], v[126:127], off offset:256
	v_or_b32_e32 v126, 32, v124
	v_ashrrev_i32_e32 v127, 31, v126
	v_lshlrev_b64 v[224:225], 11, v[126:127]
	v_lshl_add_u64 v[126:127], v[122:123], 0, v[224:225]
	global_load_dwordx4 v[174:177], v[126:127], off
	global_load_dwordx4 v[170:173], v[126:127], off offset:256
	v_or_b32_e32 v124, 48, v124
	v_ashrrev_i32_e32 v125, 31, v124
	v_lshlrev_b64 v[222:223], 11, v[124:125]
	v_lshl_add_u64 v[124:125], v[122:123], 0, v[222:223]
	global_load_dwordx4 v[166:169], v[124:125], off
	global_load_dwordx4 v[162:165], v[124:125], off offset:256
	s_mov_b64 s[36:37], 0x40000
	v_lshl_add_u64 v[220:221], v[206:207], 0, s[36:37]
	v_lshl_add_u64 v[124:125], v[122:123], 0, v[220:221]
	global_load_dwordx4 v[158:161], v[124:125], off
	global_load_dwordx4 v[154:157], v[124:125], off offset:256
	s_mov_b64 s[36:37], 0x48000
	v_lshl_add_u64 v[218:219], v[206:207], 0, s[36:37]
	v_lshl_add_u64 v[124:125], v[122:123], 0, v[218:219]
	global_load_dwordx4 v[150:153], v[124:125], off
	global_load_dwordx4 v[146:149], v[124:125], off offset:256
	s_mov_b64 s[36:37], 0x50000
	v_lshl_add_u64 v[204:205], v[206:207], 0, s[36:37]
	v_lshl_add_u64 v[124:125], v[122:123], 0, v[204:205]
	global_load_dwordx4 v[134:137], v[124:125], off
	global_load_dwordx4 v[130:133], v[124:125], off offset:256
	s_nop 0
	s_nop 0
	s_mov_b64 s[36:37], 0x58000
	s_nop 0
	v_lshl_add_u64 v[202:203], v[206:207], 0, s[36:37]
	s_nop 0
	v_lshl_add_u64 v[122:123], v[122:123], 0, v[202:203]
	global_load_dwordx4 v[126:129], v[122:123], off
	s_nop 0
	global_load_dwordx4 v[122:125], v[122:123], off offset:256
	s_nop 0
	s_nop 0
	s_nop 0
	s_nop 0
	s_nop 0
	s_nop 0
	s_nop 0
	s_nop 0
	s_nop 0
	s_nop 0
	s_nop 0
	s_nop 0
	s_nop 0
	s_nop 0
	s_nop 0
	s_nop 0
	s_nop 0
	s_nop 0
	s_nop 0
	s_nop 0
	s_nop 0
	s_nop 0
	s_nop 0
	s_nop 0
	s_nop 0
	s_nop 0
	s_nop 0
	s_nop 0
	s_nop 0
	s_nop 0
	s_nop 0
	s_nop 0
	s_nop 0
	s_nop 0
	s_nop 0
	s_nop 0
	s_nop 0
	s_nop 0
	s_nop 0
	s_nop 0
	s_nop 0
	s_nop 0
	s_nop 0
	s_waitcnt vmcnt(0)
	v_lshlrev_b32_e32 v208, 16, v210
	v_and_b32_e32 v209, 0xffff0000, v210
	v_pk_fma_f32 v[142:143], v[208:209], s[26:27], v[142:143] op_sel_hi:[1,0,1]
	v_lshlrev_b32_e32 v208, 16, v211
	v_and_b32_e32 v209, 0xffff0000, v211
	v_pk_fma_f32 v[144:145], v[208:209], s[26:27], v[144:145] op_sel_hi:[1,0,1]
	v_lshlrev_b32_e32 v208, 16, v212
	v_and_b32_e32 v209, 0xffff0000, v212
	v_pk_fma_f32 v[138:139], v[208:209], s[26:27], v[138:139] op_sel_hi:[1,0,1]
	v_lshlrev_b32_e32 v208, 16, v213
	v_and_b32_e32 v209, 0xffff0000, v213
	v_pk_fma_f32 v[208:209], v[208:209], s[26:27], v[140:141] op_sel_hi:[1,0,1]
	v_cvt_pk_bf16_f32 v140, v142, v143
	v_cvt_pk_bf16_f32 v142, v138, v139
	v_lshl_add_u64 v[138:139], s[10:11], 0, v[206:207]
	v_cvt_pk_bf16_f32 v141, v144, v145
	v_cvt_pk_bf16_f32 v143, v208, v209
	v_lshl_add_u64 v[138:139], v[138:139], 0, v[200:201]
	global_store_dwordx4 v[138:139], v[140:143], off
	s_nop 0
	s_nop 0
	v_lshlrev_b32_e32 v140, 16, v186
	v_and_b32_e32 v141, 0xffff0000, v186
	v_pk_fma_f32 v[118:119], v[140:141], s[26:27], v[118:119] op_sel_hi:[1,0,1]
	v_lshlrev_b32_e32 v140, 16, v187
	v_and_b32_e32 v141, 0xffff0000, v187
	v_pk_fma_f32 v[120:121], v[140:141], s[26:27], v[120:121] op_sel_hi:[1,0,1]
	v_lshlrev_b32_e32 v140, 16, v188
	v_and_b32_e32 v141, 0xffff0000, v188
	v_pk_fma_f32 v[140:141], v[140:141], s[26:27], v[114:115] op_sel_hi:[1,0,1]
	v_lshlrev_b32_e32 v114, 16, v189
	v_and_b32_e32 v115, 0xffff0000, v189
	v_pk_fma_f32 v[142:143], v[114:115], s[26:27], v[116:117] op_sel_hi:[1,0,1]
	v_cvt_pk_bf16_f32 v114, v118, v119
	v_cvt_pk_bf16_f32 v115, v120, v121
	v_cvt_pk_bf16_f32 v116, v140, v141
	v_cvt_pk_bf16_f32 v117, v142, v143
	global_store_dwordx4 v[138:139], v[114:117], off offset:256
	s_nop 0
	s_nop 0
	v_lshlrev_b32_e32 v114, 16, v182
	v_and_b32_e32 v115, 0xffff0000, v182
	v_pk_fma_f32 v[110:111], v[114:115], s[26:27], v[110:111] op_sel_hi:[1,0,1]
	v_lshlrev_b32_e32 v114, 16, v183
	v_and_b32_e32 v115, 0xffff0000, v183
	v_pk_fma_f32 v[112:113], v[114:115], s[26:27], v[112:113] op_sel_hi:[1,0,1]
	v_lshlrev_b32_e32 v114, 16, v184
	v_and_b32_e32 v115, 0xffff0000, v184
	v_pk_fma_f32 v[114:115], v[114:115], s[26:27], v[106:107] op_sel_hi:[1,0,1]
	v_lshlrev_b32_e32 v106, 16, v185
	v_and_b32_e32 v107, 0xffff0000, v185
	v_pk_fma_f32 v[116:117], v[106:107], s[26:27], v[108:109] op_sel_hi:[1,0,1]
	v_cvt_pk_bf16_f32 v106, v110, v111
	v_lshl_add_u64 v[110:111], s[10:11], 0, v[226:227]
	v_cvt_pk_bf16_f32 v107, v112, v113
	v_cvt_pk_bf16_f32 v108, v114, v115
	v_cvt_pk_bf16_f32 v109, v116, v117
	v_lshl_add_u64 v[110:111], v[110:111], 0, v[200:201]
	global_store_dwordx4 v[110:111], v[106:109], off
	s_nop 0
	s_nop 0
	v_lshlrev_b32_e32 v106, 16, v178
	v_and_b32_e32 v107, 0xffff0000, v178
; __device__ __forceinline__ unsigned cvt_pk_bf16(float lo, float hi) { const f32x2c v = {lo, hi}; const bf16x2c b = __builtin_convertvector(v, bf16x2c); return __builtin_bit_cast(unsigned, b); }
; __device__ __forceinline__ float bflo(unsigned u) { return __uint_as_float(u << 16); }
; __device__ __forceinline__ float bfhi(unsigned u) { return __uint_as_float(u & 0xffff0000u); }
;     __device__ __forceinline__ void operator()(const f32x4 (&acc)[2][2][4][2], const Unit& u, int wr, int wc, int fr_, int fq_) const {
;     ...
;                     } else if (MODE == 5) {
;                         const u32x4v pp = pq[ai][m][bj];
;                         v0[0] += DN_ALPHA * bflo(pp[0]); v0[1] += DN_ALPHA * bfhi(pp[0]); v0[2] += DN_ALPHA * bflo(pp[1]); v0[3] += DN_ALPHA * bfhi(pp[1]);
;                         v1[0] += DN_ALPHA * bflo(pp[2]); v1[1] += DN_ALPHA * bfhi(pp[2]); v1[2] += DN_ALPHA * bflo(pp[3]); v1[3] += DN_ALPHA * bfhi(pp[3]);
;                     } else if (MODE == 3 || MODE == 4) {
;                         const u32x4v gg = gq[ai][m][bj];
;                         v0[0] *= bflo(gg[0]); v0[1] *= bfhi(gg[0]); v0[2] *= bflo(gg[1]); v0[3] *= bfhi(gg[1]);
;                         v1[0] *= bflo(gg[2]); v1[1] *= bfhi(gg[2]); v1[2] *= bflo(gg[3]); v1[3] *= bfhi(gg[3]);
;                         if (MODE == 4) {
;                             const u32x4v pp = pq[ai][m][bj];
;                             v0[0] += bflo(pp[0]); v0[1] += bfhi(pp[0]); v0[2] += bflo(pp[1]); v0[3] += bfhi(pp[1]);
;                             v1[0] += bflo(pp[2]); v1[1] += bfhi(pp[2]); v1[2] += bflo(pp[3]); v1[3] += bfhi(pp[3]);
;                         }
;                     }
;                     u32x4v o; o[0] = cvt_pk_bf16(v0[0], v0[1]); o[1] = cvt_pk_bf16(v0[2], v0[3]); o[2] = cvt_pk_bf16(v1[0], v1[1]); o[3] = cvt_pk_bf16(v1[2], v1[3]);
;                     if (MODE == 1) __builtin_nontemporal_store(o, (u32x4v*)(O + ro + bj * 128));
;                     else *(u32x4v*)(O + ro + bj * 128) = o;
	v_pk_fma_f32 v[102:103], v[106:107], s[26:27], v[102:103] op_sel_hi:[1,0,1]
	v_lshlrev_b32_e32 v106, 16, v179
	v_and_b32_e32 v107, 0xffff0000, v179
	v_pk_fma_f32 v[104:105], v[106:107], s[26:27], v[104:105] op_sel_hi:[1,0,1]
	v_lshlrev_b32_e32 v106, 16, v180
	v_and_b32_e32 v107, 0xffff0000, v180
	v_pk_fma_f32 v[106:107], v[106:107], s[26:27], v[98:99] op_sel_hi:[1,0,1]
	v_lshlrev_b32_e32 v98, 16, v181
	v_and_b32_e32 v99, 0xffff0000, v181
	v_pk_fma_f32 v[108:109], v[98:99], s[26:27], v[100:101] op_sel_hi:[1,0,1]
	v_cvt_pk_bf16_f32 v98, v102, v103
	v_cvt_pk_bf16_f32 v99, v104, v105
	v_cvt_pk_bf16_f32 v100, v106, v107
	v_cvt_pk_bf16_f32 v101, v108, v109
	global_store_dwordx4 v[110:111], v[98:101], off offset:256
	s_nop 0
	s_nop 0
	v_lshlrev_b32_e32 v98, 16, v174
	v_and_b32_e32 v99, 0xffff0000, v174
	v_pk_fma_f32 v[94:95], v[98:99], s[26:27], v[94:95] op_sel_hi:[1,0,1]
	v_lshlrev_b32_e32 v98, 16, v175
	v_and_b32_e32 v99, 0xffff0000, v175
	v_pk_fma_f32 v[96:97], v[98:99], s[26:27], v[96:97] op_sel_hi:[1,0,1]
	v_lshlrev_b32_e32 v98, 16, v176
	v_and_b32_e32 v99, 0xffff0000, v176
	v_pk_fma_f32 v[98:99], v[98:99], s[26:27], v[90:91] op_sel_hi:[1,0,1]
	v_lshlrev_b32_e32 v90, 16, v177
	v_and_b32_e32 v91, 0xffff0000, v177
	v_pk_fma_f32 v[100:101], v[90:91], s[26:27], v[92:93] op_sel_hi:[1,0,1]
	v_cvt_pk_bf16_f32 v90, v94, v95
	v_lshl_add_u64 v[94:95], s[10:11], 0, v[224:225]
	v_cvt_pk_bf16_f32 v91, v96, v97
	v_cvt_pk_bf16_f32 v92, v98, v99
	v_cvt_pk_bf16_f32 v93, v100, v101
	v_lshl_add_u64 v[94:95], v[94:95], 0, v[200:201]
	global_store_dwordx4 v[94:95], v[90:93], off
	s_nop 0
	s_nop 0
	v_lshlrev_b32_e32 v90, 16, v170
	v_and_b32_e32 v91, 0xffff0000, v170
	v_pk_fma_f32 v[86:87], v[90:91], s[26:27], v[86:87] op_sel_hi:[1,0,1]
	v_lshlrev_b32_e32 v90, 16, v171
	v_and_b32_e32 v91, 0xffff0000, v171
	v_pk_fma_f32 v[88:89], v[90:91], s[26:27], v[88:89] op_sel_hi:[1,0,1]
	v_lshlrev_b32_e32 v90, 16, v172
	v_and_b32_e32 v91, 0xffff0000, v172
	v_pk_fma_f32 v[90:91], v[90:91], s[26:27], v[82:83] op_sel_hi:[1,0,1]
	v_lshlrev_b32_e32 v82, 16, v173
	v_and_b32_e32 v83, 0xffff0000, v173
	v_pk_fma_f32 v[92:93], v[82:83], s[26:27], v[84:85] op_sel_hi:[1,0,1]
	v_cvt_pk_bf16_f32 v82, v86, v87
	v_cvt_pk_bf16_f32 v83, v88, v89
	v_cvt_pk_bf16_f32 v84, v90, v91
	v_cvt_pk_bf16_f32 v85, v92, v93
	global_store_dwordx4 v[94:95], v[82:85], off offset:256
	s_nop 0
	s_nop 0
	v_lshlrev_b32_e32 v82, 16, v166
	v_and_b32_e32 v83, 0xffff0000, v166
	v_pk_fma_f32 v[78:79], v[82:83], s[26:27], v[78:79] op_sel_hi:[1,0,1]
	v_lshlrev_b32_e32 v82, 16, v167
	v_and_b32_e32 v83, 0xffff0000, v167
	v_pk_fma_f32 v[80:81], v[82:83], s[26:27], v[80:81] op_sel_hi:[1,0,1]
	v_lshlrev_b32_e32 v82, 16, v168
	v_and_b32_e32 v83, 0xffff0000, v168
	v_pk_fma_f32 v[82:83], v[82:83], s[26:27], v[74:75] op_sel_hi:[1,0,1]
	v_lshlrev_b32_e32 v74, 16, v169
	v_and_b32_e32 v75, 0xffff0000, v169
	v_pk_fma_f32 v[84:85], v[74:75], s[26:27], v[76:77] op_sel_hi:[1,0,1]
	v_cvt_pk_bf16_f32 v74, v78, v79
	v_lshl_add_u64 v[78:79], s[10:11], 0, v[222:223]
	v_cvt_pk_bf16_f32 v75, v80, v81
	v_cvt_pk_bf16_f32 v76, v82, v83
	v_cvt_pk_bf16_f32 v77, v84, v85
	v_lshl_add_u64 v[78:79], v[78:79], 0, v[200:201]
	global_store_dwordx4 v[78:79], v[74:77], off
	s_nop 0
	s_nop 0
	v_lshlrev_b32_e32 v74, 16, v162
	v_and_b32_e32 v75, 0xffff0000, v162
	v_pk_fma_f32 v[70:71], v[74:75], s[26:27], v[70:71] op_sel_hi:[1,0,1]
	v_lshlrev_b32_e32 v74, 16, v163
	v_and_b32_e32 v75, 0xffff0000, v163
	v_pk_fma_f32 v[72:73], v[74:75], s[26:27], v[72:73] op_sel_hi:[1,0,1]
	v_lshlrev_b32_e32 v74, 16, v164
	v_and_b32_e32 v75, 0xffff0000, v164
	v_pk_fma_f32 v[74:75], v[74:75], s[26:27], v[66:67] op_sel_hi:[1,0,1]
	v_lshlrev_b32_e32 v66, 16, v165
	v_and_b32_e32 v67, 0xffff0000, v165
	v_pk_fma_f32 v[76:77], v[66:67], s[26:27], v[68:69] op_sel_hi:[1,0,1]
	v_cvt_pk_bf16_f32 v66, v70, v71
	v_cvt_pk_bf16_f32 v67, v72, v73
	v_cvt_pk_bf16_f32 v68, v74, v75
	v_cvt_pk_bf16_f32 v69, v76, v77
	global_store_dwordx4 v[78:79], v[66:69], off offset:256
	s_nop 0
	s_nop 0
	v_lshlrev_b32_e32 v66, 16, v158
	v_and_b32_e32 v67, 0xffff0000, v158
	v_pk_fma_f32 v[62:63], v[66:67], s[26:27], v[62:63] op_sel_hi:[1,0,1]
	v_lshlrev_b32_e32 v66, 16, v159
	v_and_b32_e32 v67, 0xffff0000, v159
	v_pk_fma_f32 v[64:65], v[66:67], s[26:27], v[64:65] op_sel_hi:[1,0,1]
	v_lshlrev_b32_e32 v66, 16, v160
	v_and_b32_e32 v67, 0xffff0000, v160
	v_pk_fma_f32 v[66:67], v[66:67], s[26:27], v[58:59] op_sel_hi:[1,0,1]
	v_lshlrev_b32_e32 v58, 16, v161
	v_and_b32_e32 v59, 0xffff0000, v161
	v_pk_fma_f32 v[68:69], v[58:59], s[26:27], v[60:61] op_sel_hi:[1,0,1]
	v_cvt_pk_bf16_f32 v58, v62, v63
	v_lshl_add_u64 v[62:63], s[10:11], 0, v[220:221]
	v_cvt_pk_bf16_f32 v59, v64, v65
	v_cvt_pk_bf16_f32 v60, v66, v67
	v_cvt_pk_bf16_f32 v61, v68, v69
	v_lshl_add_u64 v[62:63], v[62:63], 0, v[200:201]
	global_store_dwordx4 v[62:63], v[58:61], off
	s_nop 0
	s_mov_b64 s[42:43], -1
	v_lshlrev_b32_e32 v58, 16, v154
	v_and_b32_e32 v59, 0xffff0000, v154
	v_pk_fma_f32 v[54:55], v[58:59], s[26:27], v[54:55] op_sel_hi:[1,0,1]
	v_lshlrev_b32_e32 v58, 16, v155
	v_and_b32_e32 v59, 0xffff0000, v155
	v_pk_fma_f32 v[56:57], v[58:59], s[26:27], v[56:57] op_sel_hi:[1,0,1]
	v_lshlrev_b32_e32 v58, 16, v156
	v_and_b32_e32 v59, 0xffff0000, v156
	v_pk_fma_f32 v[58:59], v[58:59], s[26:27], v[50:51] op_sel_hi:[1,0,1]
; #define PG8_BAR __builtin_amdgcn_s_barrier()
; template <class Epi, class Sched, bool ALIGN_EPI = false, bool SP2 = false>
; __device__ __forceinline__ void gemm_phase(PG8_LAS unsigned char* lds, int tid_in, const Gemm g, const Sched& S, const Epi& E) {
;     ...
;         if (!has_next) break;
; #pragma unroll
;         for (int a = 0; a < 2; ++a)
; #pragma unroll
;             for (int b = 0; b < 2; ++b)
; #pragma unroll
;                 for (int m = 0; m < 4; ++m)
; #pragma unroll
;                     for (int n = 0; n < 2; ++n) acc[a][b][m][n] = (f32x4){0.f, 0.f, 0.f, 0.f};
;         cur = nxt; cA = nA; cB = nB; ++ui;
;         if constexpr (ALIGN_EPI) { if (wr == 1) PG8_BAR; }
;     __device__ __forceinline__ void operator()(const f32x4 (&acc)[2][2][4][2], const Unit& u, int wr, int wc, int fr_, int fq_) const {
;     ...
;                     } else if (MODE == 5) {
;                         const u32x4v pp = pq[ai][m][bj];
;                         v0[0] += DN_ALPHA * bflo(pp[0]); v0[1] += DN_ALPHA * bfhi(pp[0]); v0[2] += DN_ALPHA * bflo(pp[1]); v0[3] += DN_ALPHA * bfhi(pp[1]);
;                         v1[0] += DN_ALPHA * bflo(pp[2]); v1[1] += DN_ALPHA * bfhi(pp[2]); v1[2] += DN_ALPHA * bflo(pp[3]); v1[3] += DN_ALPHA * bfhi(pp[3]);
;                     } else if (MODE == 3 || MODE == 4) {
;                         const u32x4v gg = gq[ai][m][bj];
;                         v0[0] *= bflo(gg[0]); v0[1] *= bfhi(gg[0]); v0[2] *= bflo(gg[1]); v0[3] *= bfhi(gg[1]);
;                         v1[0] *= bflo(gg[2]); v1[1] *= bfhi(gg[2]); v1[2] *= bflo(gg[3]); v1[3] *= bfhi(gg[3]);
;                         if (MODE == 4) {
;                             const u32x4v pp = pq[ai][m][bj];
;                             v0[0] += bflo(pp[0]); v0[1] += bfhi(pp[0]); v0[2] += bflo(pp[1]); v0[3] += bfhi(pp[1]);
;                             v1[0] += bflo(pp[2]); v1[1] += bfhi(pp[2]); v1[2] += bflo(pp[3]); v1[3] += bfhi(pp[3]);
;                         }
;                     }
;                     u32x4v o; o[0] = cvt_pk_bf16(v0[0], v0[1]); o[1] = cvt_pk_bf16(v0[2], v0[3]); o[2] = cvt_pk_bf16(v1[0], v1[1]); o[3] = cvt_pk_bf16(v1[2], v1[3]);
;                     if (MODE == 1) __builtin_nontemporal_store(o, (u32x4v*)(O + ro + bj * 128));
;                     else *(u32x4v*)(O + ro + bj * 128) = o;
;                 }
;             }
;         }
;     }
	v_lshlrev_b32_e32 v50, 16, v157
	v_and_b32_e32 v51, 0xffff0000, v157
	v_pk_fma_f32 v[60:61], v[50:51], s[26:27], v[52:53] op_sel_hi:[1,0,1]
	v_cvt_pk_bf16_f32 v50, v54, v55
	v_cvt_pk_bf16_f32 v51, v56, v57
	v_cvt_pk_bf16_f32 v52, v58, v59
	v_cvt_pk_bf16_f32 v53, v60, v61
	global_store_dwordx4 v[62:63], v[50:53], off offset:256
	s_andn2_b64 vcc, exec, s[4:5]
	s_nop 0
	v_lshlrev_b32_e32 v50, 16, v150
	v_and_b32_e32 v51, 0xffff0000, v150
	v_pk_fma_f32 v[46:47], v[50:51], s[26:27], v[46:47] op_sel_hi:[1,0,1]
	v_lshlrev_b32_e32 v50, 16, v151
	v_and_b32_e32 v51, 0xffff0000, v151
	v_pk_fma_f32 v[48:49], v[50:51], s[26:27], v[48:49] op_sel_hi:[1,0,1]
	v_lshlrev_b32_e32 v50, 16, v152
	v_and_b32_e32 v51, 0xffff0000, v152
	v_pk_fma_f32 v[50:51], v[50:51], s[26:27], v[42:43] op_sel_hi:[1,0,1]
	v_lshlrev_b32_e32 v42, 16, v153
	v_and_b32_e32 v43, 0xffff0000, v153
	v_pk_fma_f32 v[52:53], v[42:43], s[26:27], v[44:45] op_sel_hi:[1,0,1]
	v_cvt_pk_bf16_f32 v42, v46, v47
	v_lshl_add_u64 v[46:47], s[10:11], 0, v[218:219]
	v_cvt_pk_bf16_f32 v43, v48, v49
	v_cvt_pk_bf16_f32 v44, v50, v51
	v_cvt_pk_bf16_f32 v45, v52, v53
	v_lshl_add_u64 v[46:47], v[46:47], 0, v[200:201]
	global_store_dwordx4 v[46:47], v[42:45], off
	s_nop 1
	v_lshlrev_b32_e32 v42, 16, v146
	v_and_b32_e32 v43, 0xffff0000, v146
	v_pk_fma_f32 v[38:39], v[42:43], s[26:27], v[38:39] op_sel_hi:[1,0,1]
	v_lshlrev_b32_e32 v42, 16, v147
	v_and_b32_e32 v43, 0xffff0000, v147
	v_pk_fma_f32 v[40:41], v[42:43], s[26:27], v[40:41] op_sel_hi:[1,0,1]
	v_lshlrev_b32_e32 v42, 16, v148
	v_and_b32_e32 v43, 0xffff0000, v148
	v_pk_fma_f32 v[42:43], v[42:43], s[26:27], v[34:35] op_sel_hi:[1,0,1]
	v_lshlrev_b32_e32 v34, 16, v149
	v_and_b32_e32 v35, 0xffff0000, v149
	v_pk_fma_f32 v[44:45], v[34:35], s[26:27], v[36:37] op_sel_hi:[1,0,1]
	v_cvt_pk_bf16_f32 v34, v38, v39
	v_cvt_pk_bf16_f32 v35, v40, v41
	v_cvt_pk_bf16_f32 v36, v42, v43
	v_cvt_pk_bf16_f32 v37, v44, v45
	global_store_dwordx4 v[46:47], v[34:37], off offset:256
	s_nop 1
	v_lshlrev_b32_e32 v34, 16, v134
	v_and_b32_e32 v35, 0xffff0000, v134
	v_pk_fma_f32 v[30:31], v[34:35], s[26:27], v[30:31] op_sel_hi:[1,0,1]
	v_lshlrev_b32_e32 v34, 16, v135
	v_and_b32_e32 v35, 0xffff0000, v135
	v_pk_fma_f32 v[32:33], v[34:35], s[26:27], v[32:33] op_sel_hi:[1,0,1]
	v_lshlrev_b32_e32 v34, 16, v136
	v_and_b32_e32 v35, 0xffff0000, v136
	v_pk_fma_f32 v[34:35], v[34:35], s[26:27], v[26:27] op_sel_hi:[1,0,1]
	v_lshlrev_b32_e32 v26, 16, v137
	v_and_b32_e32 v27, 0xffff0000, v137
	v_pk_fma_f32 v[36:37], v[26:27], s[26:27], v[28:29] op_sel_hi:[1,0,1]
	v_cvt_pk_bf16_f32 v26, v30, v31
	v_lshl_add_u64 v[30:31], s[10:11], 0, v[204:205]
	v_cvt_pk_bf16_f32 v27, v32, v33
	v_cvt_pk_bf16_f32 v28, v34, v35
	v_cvt_pk_bf16_f32 v29, v36, v37
	v_lshl_add_u64 v[30:31], v[30:31], 0, v[200:201]
	global_store_dwordx4 v[30:31], v[26:29], off
	s_nop 1
	v_lshlrev_b32_e32 v26, 16, v130
	v_and_b32_e32 v27, 0xffff0000, v130
	v_pk_fma_f32 v[22:23], v[26:27], s[26:27], v[22:23] op_sel_hi:[1,0,1]
	v_lshlrev_b32_e32 v26, 16, v131
	v_and_b32_e32 v27, 0xffff0000, v131
	v_pk_fma_f32 v[24:25], v[26:27], s[26:27], v[24:25] op_sel_hi:[1,0,1]
	v_lshlrev_b32_e32 v26, 16, v132
	v_and_b32_e32 v27, 0xffff0000, v132
	v_pk_fma_f32 v[26:27], v[26:27], s[26:27], v[18:19] op_sel_hi:[1,0,1]
	v_lshlrev_b32_e32 v18, 16, v133
	v_and_b32_e32 v19, 0xffff0000, v133
	v_pk_fma_f32 v[28:29], v[18:19], s[26:27], v[20:21] op_sel_hi:[1,0,1]
	v_cvt_pk_bf16_f32 v18, v22, v23
	v_cvt_pk_bf16_f32 v19, v24, v25
	v_cvt_pk_bf16_f32 v20, v26, v27
	v_cvt_pk_bf16_f32 v21, v28, v29
	global_store_dwordx4 v[30:31], v[18:21], off offset:256
	s_nop 1
	v_lshlrev_b32_e32 v18, 16, v126
	v_and_b32_e32 v19, 0xffff0000, v126
	v_pk_fma_f32 v[14:15], v[18:19], s[26:27], v[14:15] op_sel_hi:[1,0,1]
	v_lshlrev_b32_e32 v18, 16, v127
	v_and_b32_e32 v19, 0xffff0000, v127
	v_pk_fma_f32 v[16:17], v[18:19], s[26:27], v[16:17] op_sel_hi:[1,0,1]
	v_lshlrev_b32_e32 v18, 16, v128
	v_and_b32_e32 v19, 0xffff0000, v128
	v_pk_fma_f32 v[18:19], v[18:19], s[26:27], v[10:11] op_sel_hi:[1,0,1]
	v_lshlrev_b32_e32 v10, 16, v129
	v_and_b32_e32 v11, 0xffff0000, v129
	v_pk_fma_f32 v[20:21], v[10:11], s[26:27], v[12:13] op_sel_hi:[1,0,1]
	v_cvt_pk_bf16_f32 v10, v14, v15
	v_lshl_add_u64 v[14:15], s[10:11], 0, v[202:203]
	v_cvt_pk_bf16_f32 v11, v16, v17
	v_cvt_pk_bf16_f32 v12, v18, v19
	v_cvt_pk_bf16_f32 v13, v20, v21
	v_lshl_add_u64 v[14:15], v[14:15], 0, v[200:201]
	global_store_dwordx4 v[14:15], v[10:13], off
	s_nop 1
	v_lshlrev_b32_e32 v10, 16, v122
	v_and_b32_e32 v11, 0xffff0000, v122
	v_pk_fma_f32 v[4:5], v[10:11], s[26:27], v[4:5] op_sel_hi:[1,0,1]
	v_lshlrev_b32_e32 v10, 16, v123
	v_and_b32_e32 v11, 0xffff0000, v123
	v_pk_fma_f32 v[6:7], v[10:11], s[26:27], v[6:7] op_sel_hi:[1,0,1]
	v_lshlrev_b32_e32 v10, 16, v124
	v_and_b32_e32 v11, 0xffff0000, v124
	v_pk_fma_f32 v[10:11], v[10:11], s[26:27], v[0:1] op_sel_hi:[1,0,1]
	v_lshlrev_b32_e32 v0, 16, v125
	v_and_b32_e32 v1, 0xffff0000, v125
	v_pk_fma_f32 v[12:13], v[0:1], s[26:27], v[2:3] op_sel_hi:[1,0,1]
	v_cvt_pk_bf16_f32 v0, v4, v5
	v_cvt_pk_bf16_f32 v1, v6, v7
	v_cvt_pk_bf16_f32 v2, v10, v11
	v_cvt_pk_bf16_f32 v3, v12, v13
	global_store_dwordx4 v[14:15], v[0:3], off offset:256
	s_cbranch_vccnz .LBB0_700
	s_andn2_b64 vcc, exec, s[8:9]
	s_cbranch_vccnz .LBB0_699
	s_barrier
	s_branch .LBB0_699
